# read/write phase separation in the EpiResid epilogues: pass 1 = all residual loads + v in place + row sums, pass 2 = all out/xn stores (on top of v13 layout)
# baseline (speedup 1.0000x reference)
;     __device__ __forceinline__ void operator()(const f32x4 (&acc)[2][2][4][2], const Unit& u, int wr, int wc, int fr, int fq) const {
;         const int row0 = u.pm * BM + wr * 64 + fr, col0 = u.pn * BM + wc * 32 + 4 * fq;
;         const float* rbase = (u.pm * BM < SEQ_P) ? resA : (resB - (size_t)SEQ_P * ldc);
;         f32x4 wv[2][2];
;         if (xn) {
; #pragma unroll
;             for (int bj = 0; bj < 2; ++bj)
; #pragma unroll
;                 for (int n = 0; n < 2; ++n) wv[bj][n] = *(const f32x4*)(wn + col0 + bj * HALF + n * 16);
;         }
; #pragma unroll
;         for (int ai = 0; ai < 2; ++ai)
; #pragma unroll
;             for (int m = 0; m < 4; ++m) {
;                 const int row = row0 + ai * HALF + m * 16;
;                 const size_t off = (size_t)row * ldc + col0;
;                 float q = 0.f;
; #pragma unroll
;                 for (int bj = 0; bj < 2; ++bj)
; #pragma unroll
;                     for (int n = 0; n < 2; ++n) {
;                         const f32x4 rv = *(const f32x4*)(rbase + off + bj * HALF + n * 16);
;                         const f32x4 v = rv + acc[ai][bj][m][n] * scale;
;                         if (out) *(f32x4*)(out + off + bj * HALF + n * 16) = v;
;                         if (xn) { q += (v.x * v.x + v.y * v.y) + (v.z * v.z + v.w * v.w); const f32x4 o = v * wv[bj][n];
;                             u32x2 p; p.x = pk2(o.x, o.y); p.y = pk2(o.z, o.w); *(u32x2*)(xn + off + bj * HALF + n * 16) = p; }
;                     }
;                 if (xn) { q += __shfl_xor(q, 16); q += __shfl_xor(q, 32); if (fq == 0) (void)__hip_atomic_fetch_add(ss + row, q, __ATOMIC_RELAXED, __HIP_MEMORY_SCOPE_AGENT); }
;             }
.LBB0_312:
	v_lshl_add_u32 v212, s62, 8, v168
	v_lshl_or_b32 v214, s61, 8, v170
	v_and_b32_e32 v243, 8, v174
	v_mov_b32_e32 v213, 0
	v_cmp_eq_u32_e64 s[34:35], 0, v243
	v_lshlrev_b32_e32 v175, 1, v243
	v_add_u32_e32 v216, v214, v175
	v_sub_u32_e32 v234, 16, v175
	v_add_u32_e32 v234, v214, v234
	v_mov_b32_e32 v214, v216
	v_mov_b32_e32 v216, v234
	v_mov_b32_e32 v215, 0
	v_mov_b32_e32 v217, 0
	v_sub_u32_e32 v210, v212, v243
	v_mov_b32_e32 v211, 0
	v_lshlrev_b64 v[208:209], 11, v[210:211]
	v_add_u32_e32 v210, 8, v210
	v_lshlrev_b64 v[210:211], 11, v[210:211]
	s_cmp_lt_i32 s62, 32
	s_cselect_b32 s31, s2, s54
	s_cselect_b32 s30, s33, s53
	v_lshl_add_u64 v[208:209], v[208:209], 0, v[214:215]
	v_lshl_add_u64 v[210:211], v[210:211], 0, v[216:217]
	v_lshl_add_u64 v[164:165], v[208:209], 2, s[30:31]
	v_lshl_add_u64 v[200:201], v[210:211], 2, s[30:31]
	v_lshl_add_u64 v[202:203], v[214:215], 2, s[10:11]
	v_lshl_add_u64 v[204:205], v[216:217], 2, s[10:11]
	global_load_dwordx4 v[64:67], v[202:203], off
	global_load_dwordx4 v[72:75], v[202:203], off offset:512
	global_load_dwordx4 v[80:83], v[204:205], off
	global_load_dwordx4 v[84:87], v[204:205], off offset:512
	global_load_dwordx4 v[156:159], v[164:165], off
	global_load_dwordx4 v[160:163], v[164:165], off offset:512
	global_load_dwordx4 v[176:179], v[200:201], off
	global_load_dwordx4 v[180:183], v[200:201], off offset:512
	s_mov_b64 vcc, 0x20000
	v_lshl_add_u64 v[164:165], v[164:165], 0, vcc
	v_lshl_add_u64 v[200:201], v[200:201], 0, vcc
	global_load_dwordx4 v[184:187], v[164:165], off
	global_load_dwordx4 v[188:191], v[164:165], off offset:512
	global_load_dwordx4 v[192:195], v[200:201], off
	global_load_dwordx4 v[196:199], v[200:201], off offset:512
	s_mov_b64 vcc, 0x20000
	v_lshl_add_u64 v[164:165], v[164:165], 0, vcc
	v_lshl_add_u64 v[200:201], v[200:201], 0, vcc
	v_lshl_add_u64 v[218:219], v[208:209], 2, s[8:9]
	v_lshl_add_u64 v[220:221], v[210:211], 2, s[8:9]
	v_lshl_add_u64 v[202:203], v[208:209], 1, s[14:15]
	v_lshl_add_u64 v[204:205], v[210:211], 1, s[14:15]
	v_lshl_add_u64 v[206:207], v[212:213], 2, s[18:19]
	v_xor_b32_e32 v235, 16, v174
	v_xor_b32_e32 v240, 32, v174
	v_lshlrev_b32_e32 v235, 2, v235
	v_lshlrev_b32_e32 v240, 2, v240
	v_mov_b32_dpp v236, v136 row_ror:8 row_mask:0xf bank_mask:0xf
	v_mov_b32_dpp v237, v137 row_ror:8 row_mask:0xf bank_mask:0xf
	v_mov_b32_dpp v238, v138 row_ror:8 row_mask:0xf bank_mask:0xf
	v_mov_b32_dpp v239, v139 row_ror:8 row_mask:0xf bank_mask:0xf
	v_cndmask_b32_e64 v136, v236, v140, s[34:35]
	v_cndmask_b32_e64 v137, v237, v141, s[34:35]
	v_cndmask_b32_e64 v138, v238, v142, s[34:35]
	v_cndmask_b32_e64 v139, v239, v143, s[34:35]
	v_cndmask_b32_e64 v140, v140, v236, s[34:35]
	v_cndmask_b32_e64 v141, v141, v237, s[34:35]
	v_cndmask_b32_e64 v142, v142, v238, s[34:35]
	v_cndmask_b32_e64 v143, v143, v239, s[34:35]
	v_mov_b32_dpp v236, v128 row_ror:8 row_mask:0xf bank_mask:0xf
	v_mov_b32_dpp v237, v129 row_ror:8 row_mask:0xf bank_mask:0xf
	v_mov_b32_dpp v238, v130 row_ror:8 row_mask:0xf bank_mask:0xf
	v_mov_b32_dpp v239, v131 row_ror:8 row_mask:0xf bank_mask:0xf
	v_cndmask_b32_e64 v128, v236, v132, s[34:35]
	v_cndmask_b32_e64 v129, v237, v133, s[34:35]
	v_cndmask_b32_e64 v130, v238, v134, s[34:35]
	v_cndmask_b32_e64 v131, v239, v135, s[34:35]
	v_cndmask_b32_e64 v132, v132, v236, s[34:35]
	v_cndmask_b32_e64 v133, v133, v237, s[34:35]
	v_cndmask_b32_e64 v134, v134, v238, s[34:35]
	v_cndmask_b32_e64 v135, v135, v239, s[34:35]
	s_waitcnt vmcnt(4)
	v_pk_fma_f32 v[138:139], v[138:139], 0.5, v[158:159] op_sel_hi:[1,0,1]
	v_pk_fma_f32 v[136:137], v[136:137], 0.5, v[156:157] op_sel_hi:[1,0,1]
	v_pk_fma_f32 v[130:131], v[130:131], 0.5, v[162:163] op_sel_hi:[1,0,1]
	v_pk_fma_f32 v[128:129], v[128:129], 0.5, v[160:161] op_sel_hi:[1,0,1]
	v_pk_fma_f32 v[142:143], v[142:143], 0.5, v[178:179] op_sel_hi:[1,0,1]
	v_pk_fma_f32 v[140:141], v[140:141], 0.5, v[176:177] op_sel_hi:[1,0,1]
	v_pk_fma_f32 v[134:135], v[134:135], 0.5, v[182:183] op_sel_hi:[1,0,1]
	v_pk_fma_f32 v[132:133], v[132:133], 0.5, v[180:181] op_sel_hi:[1,0,1]
	global_load_dwordx4 v[156:159], v[164:165], off
	global_load_dwordx4 v[160:163], v[164:165], off offset:512
	global_load_dwordx4 v[176:179], v[200:201], off
	global_load_dwordx4 v[180:183], v[200:201], off offset:512
	s_mov_b64 vcc, 0x20000
	v_lshl_add_u64 v[164:165], v[164:165], 0, vcc
	v_lshl_add_u64 v[200:201], v[200:201], 0, vcc
	v_mul_f32_e32 v175, v136, v136
	v_fmac_f32_e32 v175, v137, v137
	v_fmac_f32_e32 v175, v138, v138
	v_fmac_f32_e32 v175, v139, v139
	v_fmac_f32_e32 v175, v128, v128
	v_fmac_f32_e32 v175, v129, v129
	v_fmac_f32_e32 v175, v130, v130
	v_fmac_f32_e32 v175, v131, v131
	v_mul_f32_e32 v234, v140, v140
	v_fmac_f32_e32 v234, v141, v141
	v_fmac_f32_e32 v234, v142, v142
	v_fmac_f32_e32 v234, v143, v143
	v_fmac_f32_e32 v234, v132, v132
	v_fmac_f32_e32 v234, v133, v133
	v_fmac_f32_e32 v234, v134, v134
	v_fmac_f32_e32 v234, v135, v135
	s_nop 1
	v_mov_b32_dpp v241, v175 row_ror:8 row_mask:0xf bank_mask:0xf
	v_mov_b32_dpp v242, v234 row_ror:8 row_mask:0xf bank_mask:0xf
	v_add_f32_e32 v175, v175, v241
	v_add_f32_e32 v234, v234, v242
	v_cndmask_b32_e64 v175, v234, v175, s[34:35]
	s_nop 0
	ds_bpermute_b32 v241, v235, v175
	s_waitcnt lgkmcnt(0)
	v_add_f32_e32 v175, v175, v241
	s_nop 0
	ds_bpermute_b32 v242, v240, v175
	s_waitcnt lgkmcnt(0)
;     __device__ __forceinline__ void operator()(const f32x4 (&acc)[2][2][4][2], const Unit& u, int wr, int wc, int fr, int fq) const {
;     ...
;         for (int ai = 0; ai < 2; ++ai)
; #pragma unroll
;             for (int m = 0; m < 4; ++m) {
;                 const int row = row0 + ai * HALF + m * 16;
;                 const size_t off = (size_t)row * ldc + col0;
;                 float q = 0.f;
; #pragma unroll
;                 for (int bj = 0; bj < 2; ++bj)
; #pragma unroll
;                     for (int n = 0; n < 2; ++n) {
;                         const f32x4 rv = *(const f32x4*)(rbase + off + bj * HALF + n * 16);
;                         const f32x4 v = rv + acc[ai][bj][m][n] * scale;
;                         if (out) *(f32x4*)(out + off + bj * HALF + n * 16) = v;
;                         if (xn) { q += (v.x * v.x + v.y * v.y) + (v.z * v.z + v.w * v.w); const f32x4 o = v * wv[bj][n];
;                             u32x2 p; p.x = pk2(o.x, o.y); p.y = pk2(o.z, o.w); *(u32x2*)(xn + off + bj * HALF + n * 16) = p; }
;                     }
;                 if (xn) { q += __shfl_xor(q, 16); q += __shfl_xor(q, 32); if (fq == 0) (void)__hip_atomic_fetch_add(ss + row, q, __ATOMIC_RELAXED, __HIP_MEMORY_SCOPE_AGENT); }
;             }
	v_add_f32_e32 v175, v175, v242
	s_mov_b64 exec, s[0:1]
	global_atomic_add_f32 v[206:207], v175, off
	s_mov_b64 exec, -1
	s_mov_b64 vcc, 64
	v_lshl_add_u64 v[206:207], v[206:207], 0, vcc
	v_mov_b32_dpp v236, v120 row_ror:8 row_mask:0xf bank_mask:0xf
	v_mov_b32_dpp v237, v121 row_ror:8 row_mask:0xf bank_mask:0xf
	v_mov_b32_dpp v238, v122 row_ror:8 row_mask:0xf bank_mask:0xf
	v_mov_b32_dpp v239, v123 row_ror:8 row_mask:0xf bank_mask:0xf
	v_cndmask_b32_e64 v120, v236, v124, s[34:35]
	v_cndmask_b32_e64 v121, v237, v125, s[34:35]
	v_cndmask_b32_e64 v122, v238, v126, s[34:35]
	v_cndmask_b32_e64 v123, v239, v127, s[34:35]
	v_cndmask_b32_e64 v124, v124, v236, s[34:35]
	v_cndmask_b32_e64 v125, v125, v237, s[34:35]
	v_cndmask_b32_e64 v126, v126, v238, s[34:35]
	v_cndmask_b32_e64 v127, v127, v239, s[34:35]
	v_mov_b32_dpp v236, v112 row_ror:8 row_mask:0xf bank_mask:0xf
	v_mov_b32_dpp v237, v113 row_ror:8 row_mask:0xf bank_mask:0xf
	v_mov_b32_dpp v238, v114 row_ror:8 row_mask:0xf bank_mask:0xf
	v_mov_b32_dpp v239, v115 row_ror:8 row_mask:0xf bank_mask:0xf
	v_cndmask_b32_e64 v112, v236, v116, s[34:35]
	v_cndmask_b32_e64 v113, v237, v117, s[34:35]
	v_cndmask_b32_e64 v114, v238, v118, s[34:35]
	v_cndmask_b32_e64 v115, v239, v119, s[34:35]
	v_cndmask_b32_e64 v116, v116, v236, s[34:35]
	v_cndmask_b32_e64 v117, v117, v237, s[34:35]
	v_cndmask_b32_e64 v118, v118, v238, s[34:35]
	v_cndmask_b32_e64 v119, v119, v239, s[34:35]
	s_waitcnt vmcnt(5)
	v_pk_fma_f32 v[122:123], v[122:123], 0.5, v[186:187] op_sel_hi:[1,0,1]
	v_pk_fma_f32 v[120:121], v[120:121], 0.5, v[184:185] op_sel_hi:[1,0,1]
	v_pk_fma_f32 v[114:115], v[114:115], 0.5, v[190:191] op_sel_hi:[1,0,1]
	v_pk_fma_f32 v[112:113], v[112:113], 0.5, v[188:189] op_sel_hi:[1,0,1]
	v_pk_fma_f32 v[126:127], v[126:127], 0.5, v[194:195] op_sel_hi:[1,0,1]
	v_pk_fma_f32 v[124:125], v[124:125], 0.5, v[192:193] op_sel_hi:[1,0,1]
	v_pk_fma_f32 v[118:119], v[118:119], 0.5, v[198:199] op_sel_hi:[1,0,1]
	v_pk_fma_f32 v[116:117], v[116:117], 0.5, v[196:197] op_sel_hi:[1,0,1]
	global_load_dwordx4 v[184:187], v[164:165], off
	global_load_dwordx4 v[188:191], v[164:165], off offset:512
	global_load_dwordx4 v[192:195], v[200:201], off
	global_load_dwordx4 v[196:199], v[200:201], off offset:512
	s_mov_b64 vcc, 0xa0000
	v_lshl_add_u64 v[164:165], v[164:165], 0, vcc
	v_lshl_add_u64 v[200:201], v[200:201], 0, vcc
	v_mul_f32_e32 v175, v120, v120
	v_fmac_f32_e32 v175, v121, v121
	v_fmac_f32_e32 v175, v122, v122
	v_fmac_f32_e32 v175, v123, v123
	v_fmac_f32_e32 v175, v112, v112
	v_fmac_f32_e32 v175, v113, v113
	v_fmac_f32_e32 v175, v114, v114
	v_fmac_f32_e32 v175, v115, v115
	v_mul_f32_e32 v234, v124, v124
	v_fmac_f32_e32 v234, v125, v125
	v_fmac_f32_e32 v234, v126, v126
	v_fmac_f32_e32 v234, v127, v127
	v_fmac_f32_e32 v234, v116, v116
	v_fmac_f32_e32 v234, v117, v117
	v_fmac_f32_e32 v234, v118, v118
	v_fmac_f32_e32 v234, v119, v119
	s_nop 1
	v_mov_b32_dpp v241, v175 row_ror:8 row_mask:0xf bank_mask:0xf
	v_mov_b32_dpp v242, v234 row_ror:8 row_mask:0xf bank_mask:0xf
	v_add_f32_e32 v175, v175, v241
	v_add_f32_e32 v234, v234, v242
	v_cndmask_b32_e64 v175, v234, v175, s[34:35]
	s_nop 0
	ds_bpermute_b32 v241, v235, v175
	s_waitcnt lgkmcnt(0)
	v_add_f32_e32 v175, v175, v241
	s_nop 0
	ds_bpermute_b32 v242, v240, v175
	s_waitcnt lgkmcnt(0)
	v_add_f32_e32 v175, v175, v242
	s_mov_b64 exec, s[0:1]
	global_atomic_add_f32 v[206:207], v175, off
	s_mov_b64 exec, -1
	s_mov_b64 vcc, 64
	v_lshl_add_u64 v[206:207], v[206:207], 0, vcc
	v_mov_b32_dpp v236, v104 row_ror:8 row_mask:0xf bank_mask:0xf
	v_mov_b32_dpp v237, v105 row_ror:8 row_mask:0xf bank_mask:0xf
	v_mov_b32_dpp v238, v106 row_ror:8 row_mask:0xf bank_mask:0xf
	v_mov_b32_dpp v239, v107 row_ror:8 row_mask:0xf bank_mask:0xf
	v_cndmask_b32_e64 v104, v236, v108, s[34:35]
	v_cndmask_b32_e64 v105, v237, v109, s[34:35]
	v_cndmask_b32_e64 v106, v238, v110, s[34:35]
	v_cndmask_b32_e64 v107, v239, v111, s[34:35]
	v_cndmask_b32_e64 v108, v108, v236, s[34:35]
	v_cndmask_b32_e64 v109, v109, v237, s[34:35]
	v_cndmask_b32_e64 v110, v110, v238, s[34:35]
	v_cndmask_b32_e64 v111, v111, v239, s[34:35]
	v_mov_b32_dpp v236, v96 row_ror:8 row_mask:0xf bank_mask:0xf
	v_mov_b32_dpp v237, v97 row_ror:8 row_mask:0xf bank_mask:0xf
	v_mov_b32_dpp v238, v98 row_ror:8 row_mask:0xf bank_mask:0xf
	v_mov_b32_dpp v239, v99 row_ror:8 row_mask:0xf bank_mask:0xf
	v_cndmask_b32_e64 v96, v236, v100, s[34:35]
	v_cndmask_b32_e64 v97, v237, v101, s[34:35]
	v_cndmask_b32_e64 v98, v238, v102, s[34:35]
	v_cndmask_b32_e64 v99, v239, v103, s[34:35]
	v_cndmask_b32_e64 v100, v100, v236, s[34:35]
	v_cndmask_b32_e64 v101, v101, v237, s[34:35]
	v_cndmask_b32_e64 v102, v102, v238, s[34:35]
	v_cndmask_b32_e64 v103, v103, v239, s[34:35]
	s_waitcnt vmcnt(6)
	v_pk_fma_f32 v[106:107], v[106:107], 0.5, v[158:159] op_sel_hi:[1,0,1]
	v_pk_fma_f32 v[104:105], v[104:105], 0.5, v[156:157] op_sel_hi:[1,0,1]
	v_pk_fma_f32 v[98:99], v[98:99], 0.5, v[162:163] op_sel_hi:[1,0,1]
	v_pk_fma_f32 v[96:97], v[96:97], 0.5, v[160:161] op_sel_hi:[1,0,1]
	v_pk_fma_f32 v[110:111], v[110:111], 0.5, v[178:179] op_sel_hi:[1,0,1]
	v_pk_fma_f32 v[108:109], v[108:109], 0.5, v[176:177] op_sel_hi:[1,0,1]
	v_pk_fma_f32 v[102:103], v[102:103], 0.5, v[182:183] op_sel_hi:[1,0,1]
	v_pk_fma_f32 v[100:101], v[100:101], 0.5, v[180:181] op_sel_hi:[1,0,1]
	global_load_dwordx4 v[156:159], v[164:165], off
	global_load_dwordx4 v[160:163], v[164:165], off offset:512
	global_load_dwordx4 v[176:179], v[200:201], off
	global_load_dwordx4 v[180:183], v[200:201], off offset:512
	s_mov_b64 vcc, 0x20000
	v_lshl_add_u64 v[164:165], v[164:165], 0, vcc
	v_lshl_add_u64 v[200:201], v[200:201], 0, vcc
	v_mul_f32_e32 v175, v104, v104
	v_fmac_f32_e32 v175, v105, v105
	v_fmac_f32_e32 v175, v106, v106
	v_fmac_f32_e32 v175, v107, v107
	v_fmac_f32_e32 v175, v96, v96
	v_fmac_f32_e32 v175, v97, v97
	v_fmac_f32_e32 v175, v98, v98
	v_fmac_f32_e32 v175, v99, v99
	v_mul_f32_e32 v234, v108, v108
	v_fmac_f32_e32 v234, v109, v109
	v_fmac_f32_e32 v234, v110, v110
	v_fmac_f32_e32 v234, v111, v111
	v_fmac_f32_e32 v234, v100, v100
	v_fmac_f32_e32 v234, v101, v101
	v_fmac_f32_e32 v234, v102, v102
	v_fmac_f32_e32 v234, v103, v103
	s_nop 1
	v_mov_b32_dpp v241, v175 row_ror:8 row_mask:0xf bank_mask:0xf
	v_mov_b32_dpp v242, v234 row_ror:8 row_mask:0xf bank_mask:0xf
	v_add_f32_e32 v175, v175, v241
	v_add_f32_e32 v234, v234, v242
	v_cndmask_b32_e64 v175, v234, v175, s[34:35]
	s_nop 0
	ds_bpermute_b32 v241, v235, v175
	s_waitcnt lgkmcnt(0)
;     __device__ __forceinline__ void operator()(const f32x4 (&acc)[2][2][4][2], const Unit& u, int wr, int wc, int fr, int fq) const {
;     ...
;         for (int ai = 0; ai < 2; ++ai)
; #pragma unroll
;             for (int m = 0; m < 4; ++m) {
;                 const int row = row0 + ai * HALF + m * 16;
;                 const size_t off = (size_t)row * ldc + col0;
;                 float q = 0.f;
; #pragma unroll
;                 for (int bj = 0; bj < 2; ++bj)
; #pragma unroll
;                     for (int n = 0; n < 2; ++n) {
;                         const f32x4 rv = *(const f32x4*)(rbase + off + bj * HALF + n * 16);
;                         const f32x4 v = rv + acc[ai][bj][m][n] * scale;
;                         if (out) *(f32x4*)(out + off + bj * HALF + n * 16) = v;
;                         if (xn) { q += (v.x * v.x + v.y * v.y) + (v.z * v.z + v.w * v.w); const f32x4 o = v * wv[bj][n];
;                             u32x2 p; p.x = pk2(o.x, o.y); p.y = pk2(o.z, o.w); *(u32x2*)(xn + off + bj * HALF + n * 16) = p; }
;                     }
;                 if (xn) { q += __shfl_xor(q, 16); q += __shfl_xor(q, 32); if (fq == 0) (void)__hip_atomic_fetch_add(ss + row, q, __ATOMIC_RELAXED, __HIP_MEMORY_SCOPE_AGENT); }
;             }
	v_add_f32_e32 v175, v175, v241
	s_nop 0
	ds_bpermute_b32 v242, v240, v175
	s_waitcnt lgkmcnt(0)
	v_add_f32_e32 v175, v175, v242
	s_mov_b64 exec, s[0:1]
	global_atomic_add_f32 v[206:207], v175, off
	s_mov_b64 exec, -1
	s_mov_b64 vcc, 64
	v_lshl_add_u64 v[206:207], v[206:207], 0, vcc
	v_mov_b32_dpp v236, v88 row_ror:8 row_mask:0xf bank_mask:0xf
	v_mov_b32_dpp v237, v89 row_ror:8 row_mask:0xf bank_mask:0xf
	v_mov_b32_dpp v238, v90 row_ror:8 row_mask:0xf bank_mask:0xf
	v_mov_b32_dpp v239, v91 row_ror:8 row_mask:0xf bank_mask:0xf
	v_cndmask_b32_e64 v88, v236, v92, s[34:35]
	v_cndmask_b32_e64 v89, v237, v93, s[34:35]
	v_cndmask_b32_e64 v90, v238, v94, s[34:35]
	v_cndmask_b32_e64 v91, v239, v95, s[34:35]
	v_cndmask_b32_e64 v92, v92, v236, s[34:35]
	v_cndmask_b32_e64 v93, v93, v237, s[34:35]
	v_cndmask_b32_e64 v94, v94, v238, s[34:35]
	v_cndmask_b32_e64 v95, v95, v239, s[34:35]
	v_mov_b32_dpp v236, v68 row_ror:8 row_mask:0xf bank_mask:0xf
	v_mov_b32_dpp v237, v69 row_ror:8 row_mask:0xf bank_mask:0xf
	v_mov_b32_dpp v238, v70 row_ror:8 row_mask:0xf bank_mask:0xf
	v_mov_b32_dpp v239, v71 row_ror:8 row_mask:0xf bank_mask:0xf
	v_cndmask_b32_e64 v68, v236, v76, s[34:35]
	v_cndmask_b32_e64 v69, v237, v77, s[34:35]
	v_cndmask_b32_e64 v70, v238, v78, s[34:35]
	v_cndmask_b32_e64 v71, v239, v79, s[34:35]
	v_cndmask_b32_e64 v76, v76, v236, s[34:35]
	v_cndmask_b32_e64 v77, v77, v237, s[34:35]
	v_cndmask_b32_e64 v78, v78, v238, s[34:35]
	v_cndmask_b32_e64 v79, v79, v239, s[34:35]
	s_waitcnt vmcnt(6)
	v_pk_fma_f32 v[90:91], v[90:91], 0.5, v[186:187] op_sel_hi:[1,0,1]
	v_pk_fma_f32 v[88:89], v[88:89], 0.5, v[184:185] op_sel_hi:[1,0,1]
	v_pk_fma_f32 v[70:71], v[70:71], 0.5, v[190:191] op_sel_hi:[1,0,1]
	v_pk_fma_f32 v[68:69], v[68:69], 0.5, v[188:189] op_sel_hi:[1,0,1]
	v_pk_fma_f32 v[94:95], v[94:95], 0.5, v[194:195] op_sel_hi:[1,0,1]
	v_pk_fma_f32 v[92:93], v[92:93], 0.5, v[192:193] op_sel_hi:[1,0,1]
	v_pk_fma_f32 v[78:79], v[78:79], 0.5, v[198:199] op_sel_hi:[1,0,1]
	v_pk_fma_f32 v[76:77], v[76:77], 0.5, v[196:197] op_sel_hi:[1,0,1]
	global_load_dwordx4 v[184:187], v[164:165], off
	global_load_dwordx4 v[188:191], v[164:165], off offset:512
	global_load_dwordx4 v[192:195], v[200:201], off
	global_load_dwordx4 v[196:199], v[200:201], off offset:512
	s_mov_b64 vcc, 0x20000
	v_lshl_add_u64 v[164:165], v[164:165], 0, vcc
	v_lshl_add_u64 v[200:201], v[200:201], 0, vcc
	v_mul_f32_e32 v175, v88, v88
	v_fmac_f32_e32 v175, v89, v89
	v_fmac_f32_e32 v175, v90, v90
	v_fmac_f32_e32 v175, v91, v91
	v_fmac_f32_e32 v175, v68, v68
	v_fmac_f32_e32 v175, v69, v69
	v_fmac_f32_e32 v175, v70, v70
	v_fmac_f32_e32 v175, v71, v71
	v_mul_f32_e32 v234, v92, v92
	v_fmac_f32_e32 v234, v93, v93
	v_fmac_f32_e32 v234, v94, v94
	v_fmac_f32_e32 v234, v95, v95
	v_fmac_f32_e32 v234, v76, v76
	v_fmac_f32_e32 v234, v77, v77
	v_fmac_f32_e32 v234, v78, v78
	v_fmac_f32_e32 v234, v79, v79
	s_nop 1
	v_mov_b32_dpp v241, v175 row_ror:8 row_mask:0xf bank_mask:0xf
	v_mov_b32_dpp v242, v234 row_ror:8 row_mask:0xf bank_mask:0xf
	v_add_f32_e32 v175, v175, v241
	v_add_f32_e32 v234, v234, v242
	v_cndmask_b32_e64 v175, v234, v175, s[34:35]
	s_nop 0
	ds_bpermute_b32 v241, v235, v175
	s_waitcnt lgkmcnt(0)
	v_add_f32_e32 v175, v175, v241
	s_nop 0
	ds_bpermute_b32 v242, v240, v175
	s_waitcnt lgkmcnt(0)
	v_add_f32_e32 v175, v175, v242
	s_mov_b64 exec, s[0:1]
	global_atomic_add_f32 v[206:207], v175, off
	s_mov_b64 exec, -1
	s_mov_b64 vcc, 320
	v_lshl_add_u64 v[206:207], v[206:207], 0, vcc
	v_mov_b32_dpp v236, v56 row_ror:8 row_mask:0xf bank_mask:0xf
	v_mov_b32_dpp v237, v57 row_ror:8 row_mask:0xf bank_mask:0xf
	v_mov_b32_dpp v238, v58 row_ror:8 row_mask:0xf bank_mask:0xf
	v_mov_b32_dpp v239, v59 row_ror:8 row_mask:0xf bank_mask:0xf
	v_cndmask_b32_e64 v56, v236, v60, s[34:35]
	v_cndmask_b32_e64 v57, v237, v61, s[34:35]
	v_cndmask_b32_e64 v58, v238, v62, s[34:35]
	v_cndmask_b32_e64 v59, v239, v63, s[34:35]
	v_cndmask_b32_e64 v60, v60, v236, s[34:35]
	v_cndmask_b32_e64 v61, v61, v237, s[34:35]
	v_cndmask_b32_e64 v62, v62, v238, s[34:35]
	v_cndmask_b32_e64 v63, v63, v239, s[34:35]
	v_mov_b32_dpp v236, v48 row_ror:8 row_mask:0xf bank_mask:0xf
	v_mov_b32_dpp v237, v49 row_ror:8 row_mask:0xf bank_mask:0xf
	v_mov_b32_dpp v238, v50 row_ror:8 row_mask:0xf bank_mask:0xf
	v_mov_b32_dpp v239, v51 row_ror:8 row_mask:0xf bank_mask:0xf
	v_cndmask_b32_e64 v48, v236, v52, s[34:35]
	v_cndmask_b32_e64 v49, v237, v53, s[34:35]
	v_cndmask_b32_e64 v50, v238, v54, s[34:35]
	v_cndmask_b32_e64 v51, v239, v55, s[34:35]
	v_cndmask_b32_e64 v52, v52, v236, s[34:35]
	v_cndmask_b32_e64 v53, v53, v237, s[34:35]
	v_cndmask_b32_e64 v54, v54, v238, s[34:35]
	v_cndmask_b32_e64 v55, v55, v239, s[34:35]
	s_waitcnt vmcnt(6)
	v_pk_fma_f32 v[58:59], v[58:59], 0.5, v[158:159] op_sel_hi:[1,0,1]
	v_pk_fma_f32 v[56:57], v[56:57], 0.5, v[156:157] op_sel_hi:[1,0,1]
	v_pk_fma_f32 v[50:51], v[50:51], 0.5, v[162:163] op_sel_hi:[1,0,1]
	v_pk_fma_f32 v[48:49], v[48:49], 0.5, v[160:161] op_sel_hi:[1,0,1]
	v_pk_fma_f32 v[62:63], v[62:63], 0.5, v[178:179] op_sel_hi:[1,0,1]
	v_pk_fma_f32 v[60:61], v[60:61], 0.5, v[176:177] op_sel_hi:[1,0,1]
	v_pk_fma_f32 v[54:55], v[54:55], 0.5, v[182:183] op_sel_hi:[1,0,1]
	v_pk_fma_f32 v[52:53], v[52:53], 0.5, v[180:181] op_sel_hi:[1,0,1]
	global_load_dwordx4 v[156:159], v[164:165], off
	global_load_dwordx4 v[160:163], v[164:165], off offset:512
	global_load_dwordx4 v[176:179], v[200:201], off
	global_load_dwordx4 v[180:183], v[200:201], off offset:512
	s_mov_b64 vcc, 0x20000
	v_lshl_add_u64 v[164:165], v[164:165], 0, vcc
	v_lshl_add_u64 v[200:201], v[200:201], 0, vcc
	v_mul_f32_e32 v175, v56, v56
	v_fmac_f32_e32 v175, v57, v57
	v_fmac_f32_e32 v175, v58, v58
	v_fmac_f32_e32 v175, v59, v59
	v_fmac_f32_e32 v175, v48, v48
	v_fmac_f32_e32 v175, v49, v49
	v_fmac_f32_e32 v175, v50, v50
	v_fmac_f32_e32 v175, v51, v51
	v_mul_f32_e32 v234, v60, v60
	v_fmac_f32_e32 v234, v61, v61
	v_fmac_f32_e32 v234, v62, v62
	v_fmac_f32_e32 v234, v63, v63
	v_fmac_f32_e32 v234, v52, v52
	v_fmac_f32_e32 v234, v53, v53
	v_fmac_f32_e32 v234, v54, v54
	v_fmac_f32_e32 v234, v55, v55
	s_nop 1
	v_mov_b32_dpp v241, v175 row_ror:8 row_mask:0xf bank_mask:0xf
	v_mov_b32_dpp v242, v234 row_ror:8 row_mask:0xf bank_mask:0xf
	v_add_f32_e32 v175, v175, v241
	v_add_f32_e32 v234, v234, v242
	v_cndmask_b32_e64 v175, v234, v175, s[34:35]
	s_nop 0
	ds_bpermute_b32 v241, v235, v175
	s_waitcnt lgkmcnt(0)
;     __device__ __forceinline__ void operator()(const f32x4 (&acc)[2][2][4][2], const Unit& u, int wr, int wc, int fr, int fq) const {
;     ...
;         for (int ai = 0; ai < 2; ++ai)
; #pragma unroll
;             for (int m = 0; m < 4; ++m) {
;                 const int row = row0 + ai * HALF + m * 16;
;                 const size_t off = (size_t)row * ldc + col0;
;                 float q = 0.f;
; #pragma unroll
;                 for (int bj = 0; bj < 2; ++bj)
; #pragma unroll
;                     for (int n = 0; n < 2; ++n) {
;                         const f32x4 rv = *(const f32x4*)(rbase + off + bj * HALF + n * 16);
;                         const f32x4 v = rv + acc[ai][bj][m][n] * scale;
;                         if (out) *(f32x4*)(out + off + bj * HALF + n * 16) = v;
;                         if (xn) { q += (v.x * v.x + v.y * v.y) + (v.z * v.z + v.w * v.w); const f32x4 o = v * wv[bj][n];
;                             u32x2 p; p.x = pk2(o.x, o.y); p.y = pk2(o.z, o.w); *(u32x2*)(xn + off + bj * HALF + n * 16) = p; }
;                     }
;                 if (xn) { q += __shfl_xor(q, 16); q += __shfl_xor(q, 32); if (fq == 0) (void)__hip_atomic_fetch_add(ss + row, q, __ATOMIC_RELAXED, __HIP_MEMORY_SCOPE_AGENT); }
;             }
	v_add_f32_e32 v175, v175, v241
	s_nop 0
	ds_bpermute_b32 v242, v240, v175
	s_waitcnt lgkmcnt(0)
	v_add_f32_e32 v175, v175, v242
	s_mov_b64 exec, s[0:1]
	global_atomic_add_f32 v[206:207], v175, off
	s_mov_b64 exec, -1
	s_mov_b64 vcc, 64
	v_lshl_add_u64 v[206:207], v[206:207], 0, vcc
	v_mov_b32_dpp v236, v40 row_ror:8 row_mask:0xf bank_mask:0xf
	v_mov_b32_dpp v237, v41 row_ror:8 row_mask:0xf bank_mask:0xf
	v_mov_b32_dpp v238, v42 row_ror:8 row_mask:0xf bank_mask:0xf
	v_mov_b32_dpp v239, v43 row_ror:8 row_mask:0xf bank_mask:0xf
	v_cndmask_b32_e64 v40, v236, v44, s[34:35]
	v_cndmask_b32_e64 v41, v237, v45, s[34:35]
	v_cndmask_b32_e64 v42, v238, v46, s[34:35]
	v_cndmask_b32_e64 v43, v239, v47, s[34:35]
	v_cndmask_b32_e64 v44, v44, v236, s[34:35]
	v_cndmask_b32_e64 v45, v45, v237, s[34:35]
	v_cndmask_b32_e64 v46, v46, v238, s[34:35]
	v_cndmask_b32_e64 v47, v47, v239, s[34:35]
	v_mov_b32_dpp v236, v32 row_ror:8 row_mask:0xf bank_mask:0xf
	v_mov_b32_dpp v237, v33 row_ror:8 row_mask:0xf bank_mask:0xf
	v_mov_b32_dpp v238, v34 row_ror:8 row_mask:0xf bank_mask:0xf
	v_mov_b32_dpp v239, v35 row_ror:8 row_mask:0xf bank_mask:0xf
	v_cndmask_b32_e64 v32, v236, v36, s[34:35]
	v_cndmask_b32_e64 v33, v237, v37, s[34:35]
	v_cndmask_b32_e64 v34, v238, v38, s[34:35]
	v_cndmask_b32_e64 v35, v239, v39, s[34:35]
	v_cndmask_b32_e64 v36, v36, v236, s[34:35]
	v_cndmask_b32_e64 v37, v37, v237, s[34:35]
	v_cndmask_b32_e64 v38, v38, v238, s[34:35]
	v_cndmask_b32_e64 v39, v39, v239, s[34:35]
	s_waitcnt vmcnt(6)
	v_pk_fma_f32 v[42:43], v[42:43], 0.5, v[186:187] op_sel_hi:[1,0,1]
	v_pk_fma_f32 v[40:41], v[40:41], 0.5, v[184:185] op_sel_hi:[1,0,1]
	v_pk_fma_f32 v[34:35], v[34:35], 0.5, v[190:191] op_sel_hi:[1,0,1]
	v_pk_fma_f32 v[32:33], v[32:33], 0.5, v[188:189] op_sel_hi:[1,0,1]
	v_pk_fma_f32 v[46:47], v[46:47], 0.5, v[194:195] op_sel_hi:[1,0,1]
	v_pk_fma_f32 v[44:45], v[44:45], 0.5, v[192:193] op_sel_hi:[1,0,1]
	v_pk_fma_f32 v[38:39], v[38:39], 0.5, v[198:199] op_sel_hi:[1,0,1]
	v_pk_fma_f32 v[36:37], v[36:37], 0.5, v[196:197] op_sel_hi:[1,0,1]
	global_load_dwordx4 v[184:187], v[164:165], off
	global_load_dwordx4 v[188:191], v[164:165], off offset:512
	global_load_dwordx4 v[192:195], v[200:201], off
	global_load_dwordx4 v[196:199], v[200:201], off offset:512
	v_mul_f32_e32 v175, v40, v40
	v_fmac_f32_e32 v175, v41, v41
	v_fmac_f32_e32 v175, v42, v42
	v_fmac_f32_e32 v175, v43, v43
	v_fmac_f32_e32 v175, v32, v32
	v_fmac_f32_e32 v175, v33, v33
	v_fmac_f32_e32 v175, v34, v34
	v_fmac_f32_e32 v175, v35, v35
	v_mul_f32_e32 v234, v44, v44
	v_fmac_f32_e32 v234, v45, v45
	v_fmac_f32_e32 v234, v46, v46
	v_fmac_f32_e32 v234, v47, v47
	v_fmac_f32_e32 v234, v36, v36
	v_fmac_f32_e32 v234, v37, v37
	v_fmac_f32_e32 v234, v38, v38
	v_fmac_f32_e32 v234, v39, v39
	s_nop 1
	v_mov_b32_dpp v241, v175 row_ror:8 row_mask:0xf bank_mask:0xf
	v_mov_b32_dpp v242, v234 row_ror:8 row_mask:0xf bank_mask:0xf
	v_add_f32_e32 v175, v175, v241
	v_add_f32_e32 v234, v234, v242
	v_cndmask_b32_e64 v175, v234, v175, s[34:35]
	s_nop 0
	ds_bpermute_b32 v241, v235, v175
	s_waitcnt lgkmcnt(0)
	v_add_f32_e32 v175, v175, v241
	s_nop 0
	ds_bpermute_b32 v242, v240, v175
	s_waitcnt lgkmcnt(0)
	v_add_f32_e32 v175, v175, v242
	s_mov_b64 exec, s[0:1]
	global_atomic_add_f32 v[206:207], v175, off
	s_mov_b64 exec, -1
	s_mov_b64 vcc, 64
	v_lshl_add_u64 v[206:207], v[206:207], 0, vcc
	v_mov_b32_dpp v236, v24 row_ror:8 row_mask:0xf bank_mask:0xf
	v_mov_b32_dpp v237, v25 row_ror:8 row_mask:0xf bank_mask:0xf
	v_mov_b32_dpp v238, v26 row_ror:8 row_mask:0xf bank_mask:0xf
	v_mov_b32_dpp v239, v27 row_ror:8 row_mask:0xf bank_mask:0xf
	v_cndmask_b32_e64 v24, v236, v28, s[34:35]
	v_cndmask_b32_e64 v25, v237, v29, s[34:35]
	v_cndmask_b32_e64 v26, v238, v30, s[34:35]
	v_cndmask_b32_e64 v27, v239, v31, s[34:35]
	v_cndmask_b32_e64 v28, v28, v236, s[34:35]
	v_cndmask_b32_e64 v29, v29, v237, s[34:35]
	v_cndmask_b32_e64 v30, v30, v238, s[34:35]
	v_cndmask_b32_e64 v31, v31, v239, s[34:35]
	v_mov_b32_dpp v236, v16 row_ror:8 row_mask:0xf bank_mask:0xf
	v_mov_b32_dpp v237, v17 row_ror:8 row_mask:0xf bank_mask:0xf
	v_mov_b32_dpp v238, v18 row_ror:8 row_mask:0xf bank_mask:0xf
	v_mov_b32_dpp v239, v19 row_ror:8 row_mask:0xf bank_mask:0xf
	v_cndmask_b32_e64 v16, v236, v20, s[34:35]
	v_cndmask_b32_e64 v17, v237, v21, s[34:35]
	v_cndmask_b32_e64 v18, v238, v22, s[34:35]
	v_cndmask_b32_e64 v19, v239, v23, s[34:35]
	v_cndmask_b32_e64 v20, v20, v236, s[34:35]
	v_cndmask_b32_e64 v21, v21, v237, s[34:35]
	v_cndmask_b32_e64 v22, v22, v238, s[34:35]
	v_cndmask_b32_e64 v23, v23, v239, s[34:35]
	s_waitcnt vmcnt(6)
	v_pk_fma_f32 v[26:27], v[26:27], 0.5, v[158:159] op_sel_hi:[1,0,1]
	v_pk_fma_f32 v[24:25], v[24:25], 0.5, v[156:157] op_sel_hi:[1,0,1]
	v_pk_fma_f32 v[18:19], v[18:19], 0.5, v[162:163] op_sel_hi:[1,0,1]
	v_pk_fma_f32 v[16:17], v[16:17], 0.5, v[160:161] op_sel_hi:[1,0,1]
	v_pk_fma_f32 v[30:31], v[30:31], 0.5, v[178:179] op_sel_hi:[1,0,1]
	v_pk_fma_f32 v[28:29], v[28:29], 0.5, v[176:177] op_sel_hi:[1,0,1]
	v_pk_fma_f32 v[22:23], v[22:23], 0.5, v[182:183] op_sel_hi:[1,0,1]
	v_pk_fma_f32 v[20:21], v[20:21], 0.5, v[180:181] op_sel_hi:[1,0,1]
	v_mul_f32_e32 v175, v24, v24
	v_fmac_f32_e32 v175, v25, v25
	v_fmac_f32_e32 v175, v26, v26
	v_fmac_f32_e32 v175, v27, v27
	v_fmac_f32_e32 v175, v16, v16
	v_fmac_f32_e32 v175, v17, v17
	v_fmac_f32_e32 v175, v18, v18
	v_fmac_f32_e32 v175, v19, v19
	v_mul_f32_e32 v234, v28, v28
	v_fmac_f32_e32 v234, v29, v29
	v_fmac_f32_e32 v234, v30, v30
	v_fmac_f32_e32 v234, v31, v31
	v_fmac_f32_e32 v234, v20, v20
	v_fmac_f32_e32 v234, v21, v21
	v_fmac_f32_e32 v234, v22, v22
	v_fmac_f32_e32 v234, v23, v23
	s_nop 1
	v_mov_b32_dpp v241, v175 row_ror:8 row_mask:0xf bank_mask:0xf
	v_mov_b32_dpp v242, v234 row_ror:8 row_mask:0xf bank_mask:0xf
	v_add_f32_e32 v175, v175, v241
	v_add_f32_e32 v234, v234, v242
	v_cndmask_b32_e64 v175, v234, v175, s[34:35]
	s_nop 0
	ds_bpermute_b32 v241, v235, v175
	s_waitcnt lgkmcnt(0)
;     __device__ __forceinline__ void operator()(const f32x4 (&acc)[2][2][4][2], const Unit& u, int wr, int wc, int fr, int fq) const {
;     ...
;         for (int ai = 0; ai < 2; ++ai)
; #pragma unroll
;             for (int m = 0; m < 4; ++m) {
;                 const int row = row0 + ai * HALF + m * 16;
;                 const size_t off = (size_t)row * ldc + col0;
;                 float q = 0.f;
; #pragma unroll
;                 for (int bj = 0; bj < 2; ++bj)
; #pragma unroll
;                     for (int n = 0; n < 2; ++n) {
;                         const f32x4 rv = *(const f32x4*)(rbase + off + bj * HALF + n * 16);
;                         const f32x4 v = rv + acc[ai][bj][m][n] * scale;
;                         if (out) *(f32x4*)(out + off + bj * HALF + n * 16) = v;
;                         if (xn) { q += (v.x * v.x + v.y * v.y) + (v.z * v.z + v.w * v.w); const f32x4 o = v * wv[bj][n];
;                             u32x2 p; p.x = pk2(o.x, o.y); p.y = pk2(o.z, o.w); *(u32x2*)(xn + off + bj * HALF + n * 16) = p; }
;                     }
;                 if (xn) { q += __shfl_xor(q, 16); q += __shfl_xor(q, 32); if (fq == 0) (void)__hip_atomic_fetch_add(ss + row, q, __ATOMIC_RELAXED, __HIP_MEMORY_SCOPE_AGENT); }
	v_add_f32_e32 v175, v175, v241
	s_nop 0
	ds_bpermute_b32 v242, v240, v175
	s_waitcnt lgkmcnt(0)
	v_add_f32_e32 v175, v175, v242
	s_mov_b64 exec, s[0:1]
	global_atomic_add_f32 v[206:207], v175, off
	s_mov_b64 exec, -1
	s_mov_b64 vcc, 64
	v_lshl_add_u64 v[206:207], v[206:207], 0, vcc
	v_mov_b32_dpp v236, v8 row_ror:8 row_mask:0xf bank_mask:0xf
	v_mov_b32_dpp v237, v9 row_ror:8 row_mask:0xf bank_mask:0xf
	v_mov_b32_dpp v238, v10 row_ror:8 row_mask:0xf bank_mask:0xf
	v_mov_b32_dpp v239, v11 row_ror:8 row_mask:0xf bank_mask:0xf
	v_cndmask_b32_e64 v8, v236, v12, s[34:35]
	v_cndmask_b32_e64 v9, v237, v13, s[34:35]
	v_cndmask_b32_e64 v10, v238, v14, s[34:35]
	v_cndmask_b32_e64 v11, v239, v15, s[34:35]
	v_cndmask_b32_e64 v12, v12, v236, s[34:35]
	v_cndmask_b32_e64 v13, v13, v237, s[34:35]
	v_cndmask_b32_e64 v14, v14, v238, s[34:35]
	v_cndmask_b32_e64 v15, v15, v239, s[34:35]
	v_mov_b32_dpp v236, v0 row_ror:8 row_mask:0xf bank_mask:0xf
	v_mov_b32_dpp v237, v1 row_ror:8 row_mask:0xf bank_mask:0xf
	v_mov_b32_dpp v238, v2 row_ror:8 row_mask:0xf bank_mask:0xf
	v_mov_b32_dpp v239, v3 row_ror:8 row_mask:0xf bank_mask:0xf
	v_cndmask_b32_e64 v0, v236, v4, s[34:35]
	v_cndmask_b32_e64 v1, v237, v5, s[34:35]
	v_cndmask_b32_e64 v2, v238, v6, s[34:35]
	v_cndmask_b32_e64 v3, v239, v7, s[34:35]
	v_cndmask_b32_e64 v4, v4, v236, s[34:35]
	v_cndmask_b32_e64 v5, v5, v237, s[34:35]
	v_cndmask_b32_e64 v6, v6, v238, s[34:35]
	v_cndmask_b32_e64 v7, v7, v239, s[34:35]
	s_waitcnt vmcnt(2)
	v_pk_fma_f32 v[10:11], v[10:11], 0.5, v[186:187] op_sel_hi:[1,0,1]
	v_pk_fma_f32 v[8:9], v[8:9], 0.5, v[184:185] op_sel_hi:[1,0,1]
	v_pk_fma_f32 v[2:3], v[2:3], 0.5, v[190:191] op_sel_hi:[1,0,1]
	v_pk_fma_f32 v[0:1], v[0:1], 0.5, v[188:189] op_sel_hi:[1,0,1]
	v_pk_fma_f32 v[14:15], v[14:15], 0.5, v[194:195] op_sel_hi:[1,0,1]
	v_pk_fma_f32 v[12:13], v[12:13], 0.5, v[192:193] op_sel_hi:[1,0,1]
	v_pk_fma_f32 v[6:7], v[6:7], 0.5, v[198:199] op_sel_hi:[1,0,1]
	v_pk_fma_f32 v[4:5], v[4:5], 0.5, v[196:197] op_sel_hi:[1,0,1]
	v_mul_f32_e32 v175, v8, v8
	v_fmac_f32_e32 v175, v9, v9
	v_fmac_f32_e32 v175, v10, v10
	v_fmac_f32_e32 v175, v11, v11
	v_fmac_f32_e32 v175, v0, v0
	v_fmac_f32_e32 v175, v1, v1
	v_fmac_f32_e32 v175, v2, v2
	v_fmac_f32_e32 v175, v3, v3
	v_mul_f32_e32 v234, v12, v12
	v_fmac_f32_e32 v234, v13, v13
	v_fmac_f32_e32 v234, v14, v14
	v_fmac_f32_e32 v234, v15, v15
	v_fmac_f32_e32 v234, v4, v4
	v_fmac_f32_e32 v234, v5, v5
	v_fmac_f32_e32 v234, v6, v6
	v_fmac_f32_e32 v234, v7, v7
	s_nop 1
	v_mov_b32_dpp v241, v175 row_ror:8 row_mask:0xf bank_mask:0xf
	v_mov_b32_dpp v242, v234 row_ror:8 row_mask:0xf bank_mask:0xf
	v_add_f32_e32 v175, v175, v241
	v_add_f32_e32 v234, v234, v242
	v_cndmask_b32_e64 v175, v234, v175, s[34:35]
	s_nop 0
	ds_bpermute_b32 v241, v235, v175
	s_waitcnt lgkmcnt(0)
	v_add_f32_e32 v175, v175, v241
	s_nop 0
	ds_bpermute_b32 v242, v240, v175
	s_waitcnt lgkmcnt(0)
	v_add_f32_e32 v175, v175, v242
	s_mov_b64 exec, s[0:1]
	global_atomic_add_f32 v[206:207], v175, off
	s_mov_b64 exec, -1
	global_store_dwordx4 v[218:219], v[136:139], off
	v_pk_mul_f32 v[224:225], v[64:65], v[136:137]
	v_pk_mul_f32 v[226:227], v[66:67], v[138:139]
	v_add_u32_e32 v224, 0x8000, v224
	v_add_u32_e32 v225, 0x8000, v225
	v_add_u32_e32 v226, 0x8000, v226
	v_add_u32_e32 v227, 0x8000, v227
	v_perm_b32 v222, v225, v224, s58
	v_perm_b32 v223, v227, v226, s58
	global_store_dwordx2 v[202:203], v[222:223], off
	global_store_dwordx4 v[218:219], v[128:131], off offset:512
	v_pk_mul_f32 v[228:229], v[72:73], v[128:129]
	v_pk_mul_f32 v[230:231], v[74:75], v[130:131]
	v_add_u32_e32 v228, 0x8000, v228
	v_add_u32_e32 v229, 0x8000, v229
	v_add_u32_e32 v230, 0x8000, v230
	v_add_u32_e32 v231, 0x8000, v231
	v_perm_b32 v232, v229, v228, s58
	v_perm_b32 v233, v231, v230, s58
	global_store_dwordx2 v[202:203], v[232:233], off offset:256
	global_store_dwordx4 v[220:221], v[140:143], off
	v_pk_mul_f32 v[224:225], v[80:81], v[140:141]
	v_pk_mul_f32 v[226:227], v[82:83], v[142:143]
	v_add_u32_e32 v224, 0x8000, v224
	v_add_u32_e32 v225, 0x8000, v225
	v_add_u32_e32 v226, 0x8000, v226
	v_add_u32_e32 v227, 0x8000, v227
	v_perm_b32 v222, v225, v224, s58
	v_perm_b32 v223, v227, v226, s58
	global_store_dwordx2 v[204:205], v[222:223], off
	global_store_dwordx4 v[220:221], v[132:135], off offset:512
	v_pk_mul_f32 v[228:229], v[84:85], v[132:133]
	v_pk_mul_f32 v[230:231], v[86:87], v[134:135]
	v_add_u32_e32 v228, 0x8000, v228
	v_add_u32_e32 v229, 0x8000, v229
	v_add_u32_e32 v230, 0x8000, v230
	v_add_u32_e32 v231, 0x8000, v231
	v_perm_b32 v232, v229, v228, s58
	v_perm_b32 v233, v231, v230, s58
	global_store_dwordx2 v[204:205], v[232:233], off offset:256
	s_mov_b64 vcc, 0x20000
	v_lshl_add_u64 v[218:219], v[218:219], 0, vcc
	v_lshl_add_u64 v[220:221], v[220:221], 0, vcc
	s_mov_b64 vcc, 0x10000
	v_lshl_add_u64 v[202:203], v[202:203], 0, vcc
	v_lshl_add_u64 v[204:205], v[204:205], 0, vcc
	global_store_dwordx4 v[218:219], v[120:123], off
	v_pk_mul_f32 v[224:225], v[64:65], v[120:121]
	v_pk_mul_f32 v[226:227], v[66:67], v[122:123]
	v_add_u32_e32 v224, 0x8000, v224
	v_add_u32_e32 v225, 0x8000, v225
	v_add_u32_e32 v226, 0x8000, v226
	v_add_u32_e32 v227, 0x8000, v227
	v_perm_b32 v222, v225, v224, s58
	v_perm_b32 v223, v227, v226, s58
	global_store_dwordx2 v[202:203], v[222:223], off
	global_store_dwordx4 v[218:219], v[112:115], off offset:512
	v_pk_mul_f32 v[228:229], v[72:73], v[112:113]
	v_pk_mul_f32 v[230:231], v[74:75], v[114:115]
	v_add_u32_e32 v228, 0x8000, v228
	v_add_u32_e32 v229, 0x8000, v229
	v_add_u32_e32 v230, 0x8000, v230
	v_add_u32_e32 v231, 0x8000, v231
	v_perm_b32 v232, v229, v228, s58
	v_perm_b32 v233, v231, v230, s58
;     __device__ __forceinline__ void operator()(const f32x4 (&acc)[2][2][4][2], const Unit& u, int wr, int wc, int fr, int fq) const {
;     ...
;                         const f32x4 rv = *(const f32x4*)(rbase + off + bj * HALF + n * 16);
;                         const f32x4 v = rv + acc[ai][bj][m][n] * scale;
;                         if (out) *(f32x4*)(out + off + bj * HALF + n * 16) = v;
;                         if (xn) { q += (v.x * v.x + v.y * v.y) + (v.z * v.z + v.w * v.w); const f32x4 o = v * wv[bj][n];
;                             u32x2 p; p.x = pk2(o.x, o.y); p.y = pk2(o.z, o.w); *(u32x2*)(xn + off + bj * HALF + n * 16) = p; }
	global_store_dwordx2 v[202:203], v[232:233], off offset:256
	global_store_dwordx4 v[220:221], v[124:127], off
	v_pk_mul_f32 v[224:225], v[80:81], v[124:125]
	v_pk_mul_f32 v[226:227], v[82:83], v[126:127]
	v_add_u32_e32 v224, 0x8000, v224
	v_add_u32_e32 v225, 0x8000, v225
	v_add_u32_e32 v226, 0x8000, v226
	v_add_u32_e32 v227, 0x8000, v227
	v_perm_b32 v222, v225, v224, s58
	v_perm_b32 v223, v227, v226, s58
	global_store_dwordx2 v[204:205], v[222:223], off
	global_store_dwordx4 v[220:221], v[116:119], off offset:512
	v_pk_mul_f32 v[228:229], v[84:85], v[116:117]
	v_pk_mul_f32 v[230:231], v[86:87], v[118:119]
	v_add_u32_e32 v228, 0x8000, v228
	v_add_u32_e32 v229, 0x8000, v229
	v_add_u32_e32 v230, 0x8000, v230
	v_add_u32_e32 v231, 0x8000, v231
	v_perm_b32 v232, v229, v228, s58
	v_perm_b32 v233, v231, v230, s58
	global_store_dwordx2 v[204:205], v[232:233], off offset:256
	s_mov_b64 vcc, 0x20000
	v_lshl_add_u64 v[218:219], v[218:219], 0, vcc
	v_lshl_add_u64 v[220:221], v[220:221], 0, vcc
	s_mov_b64 vcc, 0x10000
	v_lshl_add_u64 v[202:203], v[202:203], 0, vcc
	v_lshl_add_u64 v[204:205], v[204:205], 0, vcc
	global_store_dwordx4 v[218:219], v[104:107], off
	v_pk_mul_f32 v[224:225], v[64:65], v[104:105]
	v_pk_mul_f32 v[226:227], v[66:67], v[106:107]
	v_add_u32_e32 v224, 0x8000, v224
	v_add_u32_e32 v225, 0x8000, v225
	v_add_u32_e32 v226, 0x8000, v226
	v_add_u32_e32 v227, 0x8000, v227
	v_perm_b32 v222, v225, v224, s58
	v_perm_b32 v223, v227, v226, s58
	global_store_dwordx2 v[202:203], v[222:223], off
	global_store_dwordx4 v[218:219], v[96:99], off offset:512
	v_pk_mul_f32 v[228:229], v[72:73], v[96:97]
	v_pk_mul_f32 v[230:231], v[74:75], v[98:99]
	v_add_u32_e32 v228, 0x8000, v228
	v_add_u32_e32 v229, 0x8000, v229
	v_add_u32_e32 v230, 0x8000, v230
	v_add_u32_e32 v231, 0x8000, v231
	v_perm_b32 v232, v229, v228, s58
	v_perm_b32 v233, v231, v230, s58
	global_store_dwordx2 v[202:203], v[232:233], off offset:256
	global_store_dwordx4 v[220:221], v[108:111], off
	v_pk_mul_f32 v[224:225], v[80:81], v[108:109]
	v_pk_mul_f32 v[226:227], v[82:83], v[110:111]
	v_add_u32_e32 v224, 0x8000, v224
	v_add_u32_e32 v225, 0x8000, v225
	v_add_u32_e32 v226, 0x8000, v226
	v_add_u32_e32 v227, 0x8000, v227
	v_perm_b32 v222, v225, v224, s58
	v_perm_b32 v223, v227, v226, s58
	global_store_dwordx2 v[204:205], v[222:223], off
	global_store_dwordx4 v[220:221], v[100:103], off offset:512
	v_pk_mul_f32 v[228:229], v[84:85], v[100:101]
	v_pk_mul_f32 v[230:231], v[86:87], v[102:103]
	v_add_u32_e32 v228, 0x8000, v228
	v_add_u32_e32 v229, 0x8000, v229
	v_add_u32_e32 v230, 0x8000, v230
	v_add_u32_e32 v231, 0x8000, v231
	v_perm_b32 v232, v229, v228, s58
	v_perm_b32 v233, v231, v230, s58
	global_store_dwordx2 v[204:205], v[232:233], off offset:256
	s_mov_b64 vcc, 0x20000
	v_lshl_add_u64 v[218:219], v[218:219], 0, vcc
	v_lshl_add_u64 v[220:221], v[220:221], 0, vcc
	s_mov_b64 vcc, 0x10000
	v_lshl_add_u64 v[202:203], v[202:203], 0, vcc
	v_lshl_add_u64 v[204:205], v[204:205], 0, vcc
	global_store_dwordx4 v[218:219], v[88:91], off
	v_pk_mul_f32 v[224:225], v[64:65], v[88:89]
	v_pk_mul_f32 v[226:227], v[66:67], v[90:91]
	v_add_u32_e32 v224, 0x8000, v224
	v_add_u32_e32 v225, 0x8000, v225
	v_add_u32_e32 v226, 0x8000, v226
	v_add_u32_e32 v227, 0x8000, v227
	v_perm_b32 v222, v225, v224, s58
	v_perm_b32 v223, v227, v226, s58
	global_store_dwordx2 v[202:203], v[222:223], off
	global_store_dwordx4 v[218:219], v[68:71], off offset:512
	v_pk_mul_f32 v[228:229], v[72:73], v[68:69]
	v_pk_mul_f32 v[230:231], v[74:75], v[70:71]
	v_add_u32_e32 v228, 0x8000, v228
	v_add_u32_e32 v229, 0x8000, v229
	v_add_u32_e32 v230, 0x8000, v230
	v_add_u32_e32 v231, 0x8000, v231
	v_perm_b32 v232, v229, v228, s58
	v_perm_b32 v233, v231, v230, s58
	global_store_dwordx2 v[202:203], v[232:233], off offset:256
	global_store_dwordx4 v[220:221], v[92:95], off
	v_pk_mul_f32 v[224:225], v[80:81], v[92:93]
	v_pk_mul_f32 v[226:227], v[82:83], v[94:95]
	v_add_u32_e32 v224, 0x8000, v224
	v_add_u32_e32 v225, 0x8000, v225
	v_add_u32_e32 v226, 0x8000, v226
	v_add_u32_e32 v227, 0x8000, v227
	v_perm_b32 v222, v225, v224, s58
	v_perm_b32 v223, v227, v226, s58
	global_store_dwordx2 v[204:205], v[222:223], off
	global_store_dwordx4 v[220:221], v[76:79], off offset:512
	v_pk_mul_f32 v[228:229], v[84:85], v[76:77]
	v_pk_mul_f32 v[230:231], v[86:87], v[78:79]
	v_add_u32_e32 v228, 0x8000, v228
	v_add_u32_e32 v229, 0x8000, v229
	v_add_u32_e32 v230, 0x8000, v230
	v_add_u32_e32 v231, 0x8000, v231
	v_perm_b32 v232, v229, v228, s58
	v_perm_b32 v233, v231, v230, s58
	global_store_dwordx2 v[204:205], v[232:233], off offset:256
	s_mov_b64 vcc, 0xa0000
	v_lshl_add_u64 v[218:219], v[218:219], 0, vcc
	v_lshl_add_u64 v[220:221], v[220:221], 0, vcc
	s_mov_b64 vcc, 0x50000
	v_lshl_add_u64 v[202:203], v[202:203], 0, vcc
	v_lshl_add_u64 v[204:205], v[204:205], 0, vcc
	global_store_dwordx4 v[218:219], v[56:59], off
	v_pk_mul_f32 v[224:225], v[64:65], v[56:57]
	v_pk_mul_f32 v[226:227], v[66:67], v[58:59]
	v_add_u32_e32 v224, 0x8000, v224
	v_add_u32_e32 v225, 0x8000, v225
	v_add_u32_e32 v226, 0x8000, v226
	v_add_u32_e32 v227, 0x8000, v227
	v_perm_b32 v222, v225, v224, s58
	v_perm_b32 v223, v227, v226, s58
	global_store_dwordx2 v[202:203], v[222:223], off
	global_store_dwordx4 v[218:219], v[48:51], off offset:512
	v_pk_mul_f32 v[228:229], v[72:73], v[48:49]
	v_pk_mul_f32 v[230:231], v[74:75], v[50:51]
	v_add_u32_e32 v228, 0x8000, v228
	v_add_u32_e32 v229, 0x8000, v229
	v_add_u32_e32 v230, 0x8000, v230
	v_add_u32_e32 v231, 0x8000, v231
	v_perm_b32 v232, v229, v228, s58
	v_perm_b32 v233, v231, v230, s58
	global_store_dwordx2 v[202:203], v[232:233], off offset:256
; #define PG8_BAR __builtin_amdgcn_s_barrier()
;     __device__ __forceinline__ void operator()(const f32x4 (&acc)[2][2][4][2], const Unit& u, int wr, int wc, int fr, int fq) const {
;     ...
;                         const f32x4 rv = *(const f32x4*)(rbase + off + bj * HALF + n * 16);
;                         const f32x4 v = rv + acc[ai][bj][m][n] * scale;
;                         if (out) *(f32x4*)(out + off + bj * HALF + n * 16) = v;
;                         if (xn) { q += (v.x * v.x + v.y * v.y) + (v.z * v.z + v.w * v.w); const f32x4 o = v * wv[bj][n];
;                             u32x2 p; p.x = pk2(o.x, o.y); p.y = pk2(o.z, o.w); *(u32x2*)(xn + off + bj * HALF + n * 16) = p; }
; template <class Epi, bool ALIGN_EPI>
; __device__ __forceinline__ void gemm_phase(LAS unsigned char* lds, const Gemm g, const StaticOrder& S, const Epi& E) {
;     ...
; #pragma unroll
;         for (int a = 0; a < 2; ++a)
; #pragma unroll
;             for (int b = 0; b < 2; ++b)
; #pragma unroll
;                 for (int m = 0; m < 4; ++m)
; #pragma unroll
;                     for (int n = 0; n < 2; ++n) acc[a][b][m][n] = (f32x4){0.f, 0.f, 0.f, 0.f};
;         cur = nxt; cA = nA; cB = nB; ++ui;
;         if constexpr (ALIGN_EPI) { if (wr == 1) PG8_BAR; }
	global_store_dwordx4 v[220:221], v[60:63], off
	v_pk_mul_f32 v[224:225], v[80:81], v[60:61]
	v_pk_mul_f32 v[226:227], v[82:83], v[62:63]
	v_add_u32_e32 v224, 0x8000, v224
	v_add_u32_e32 v225, 0x8000, v225
	v_add_u32_e32 v226, 0x8000, v226
	v_add_u32_e32 v227, 0x8000, v227
	v_perm_b32 v222, v225, v224, s58
	v_perm_b32 v223, v227, v226, s58
	global_store_dwordx2 v[204:205], v[222:223], off
	global_store_dwordx4 v[220:221], v[52:55], off offset:512
	v_pk_mul_f32 v[228:229], v[84:85], v[52:53]
	v_pk_mul_f32 v[230:231], v[86:87], v[54:55]
	v_add_u32_e32 v228, 0x8000, v228
	v_add_u32_e32 v229, 0x8000, v229
	v_add_u32_e32 v230, 0x8000, v230
	v_add_u32_e32 v231, 0x8000, v231
	v_perm_b32 v232, v229, v228, s58
	v_perm_b32 v233, v231, v230, s58
	global_store_dwordx2 v[204:205], v[232:233], off offset:256
	s_mov_b64 vcc, 0x20000
	v_lshl_add_u64 v[218:219], v[218:219], 0, vcc
	v_lshl_add_u64 v[220:221], v[220:221], 0, vcc
	s_mov_b64 vcc, 0x10000
	v_lshl_add_u64 v[202:203], v[202:203], 0, vcc
	v_lshl_add_u64 v[204:205], v[204:205], 0, vcc
	global_store_dwordx4 v[218:219], v[40:43], off
	v_pk_mul_f32 v[224:225], v[64:65], v[40:41]
	v_pk_mul_f32 v[226:227], v[66:67], v[42:43]
	v_add_u32_e32 v224, 0x8000, v224
	v_add_u32_e32 v225, 0x8000, v225
	v_add_u32_e32 v226, 0x8000, v226
	v_add_u32_e32 v227, 0x8000, v227
	v_perm_b32 v222, v225, v224, s58
	v_perm_b32 v223, v227, v226, s58
	global_store_dwordx2 v[202:203], v[222:223], off
	global_store_dwordx4 v[218:219], v[32:35], off offset:512
	v_pk_mul_f32 v[228:229], v[72:73], v[32:33]
	v_pk_mul_f32 v[230:231], v[74:75], v[34:35]
	v_add_u32_e32 v228, 0x8000, v228
	v_add_u32_e32 v229, 0x8000, v229
	v_add_u32_e32 v230, 0x8000, v230
	v_add_u32_e32 v231, 0x8000, v231
	v_perm_b32 v232, v229, v228, s58
	v_perm_b32 v233, v231, v230, s58
	global_store_dwordx2 v[202:203], v[232:233], off offset:256
	global_store_dwordx4 v[220:221], v[44:47], off
	v_pk_mul_f32 v[224:225], v[80:81], v[44:45]
	v_pk_mul_f32 v[226:227], v[82:83], v[46:47]
	v_add_u32_e32 v224, 0x8000, v224
	v_add_u32_e32 v225, 0x8000, v225
	v_add_u32_e32 v226, 0x8000, v226
	v_add_u32_e32 v227, 0x8000, v227
	v_perm_b32 v222, v225, v224, s58
	v_perm_b32 v223, v227, v226, s58
	global_store_dwordx2 v[204:205], v[222:223], off
	global_store_dwordx4 v[220:221], v[36:39], off offset:512
	v_pk_mul_f32 v[228:229], v[84:85], v[36:37]
	v_pk_mul_f32 v[230:231], v[86:87], v[38:39]
	v_add_u32_e32 v228, 0x8000, v228
	v_add_u32_e32 v229, 0x8000, v229
	v_add_u32_e32 v230, 0x8000, v230
	v_add_u32_e32 v231, 0x8000, v231
	v_perm_b32 v232, v229, v228, s58
	v_perm_b32 v233, v231, v230, s58
	global_store_dwordx2 v[204:205], v[232:233], off offset:256
	s_mov_b64 vcc, 0x20000
	v_lshl_add_u64 v[218:219], v[218:219], 0, vcc
	v_lshl_add_u64 v[220:221], v[220:221], 0, vcc
	s_mov_b64 vcc, 0x10000
	v_lshl_add_u64 v[202:203], v[202:203], 0, vcc
	v_lshl_add_u64 v[204:205], v[204:205], 0, vcc
	global_store_dwordx4 v[218:219], v[24:27], off
	v_pk_mul_f32 v[224:225], v[64:65], v[24:25]
	v_pk_mul_f32 v[226:227], v[66:67], v[26:27]
	v_add_u32_e32 v224, 0x8000, v224
	v_add_u32_e32 v225, 0x8000, v225
	v_add_u32_e32 v226, 0x8000, v226
	v_add_u32_e32 v227, 0x8000, v227
	v_perm_b32 v222, v225, v224, s58
	v_perm_b32 v223, v227, v226, s58
	global_store_dwordx2 v[202:203], v[222:223], off
	global_store_dwordx4 v[218:219], v[16:19], off offset:512
	v_pk_mul_f32 v[228:229], v[72:73], v[16:17]
	v_pk_mul_f32 v[230:231], v[74:75], v[18:19]
	v_add_u32_e32 v228, 0x8000, v228
	v_add_u32_e32 v229, 0x8000, v229
	v_add_u32_e32 v230, 0x8000, v230
	v_add_u32_e32 v231, 0x8000, v231
	v_perm_b32 v232, v229, v228, s58
	v_perm_b32 v233, v231, v230, s58
	global_store_dwordx2 v[202:203], v[232:233], off offset:256
	global_store_dwordx4 v[220:221], v[28:31], off
	v_pk_mul_f32 v[224:225], v[80:81], v[28:29]
	v_pk_mul_f32 v[226:227], v[82:83], v[30:31]
	v_add_u32_e32 v224, 0x8000, v224
	v_add_u32_e32 v225, 0x8000, v225
	v_add_u32_e32 v226, 0x8000, v226
	v_add_u32_e32 v227, 0x8000, v227
	v_perm_b32 v222, v225, v224, s58
	v_perm_b32 v223, v227, v226, s58
	global_store_dwordx2 v[204:205], v[222:223], off
	global_store_dwordx4 v[220:221], v[20:23], off offset:512
	v_pk_mul_f32 v[228:229], v[84:85], v[20:21]
	v_pk_mul_f32 v[230:231], v[86:87], v[22:23]
	v_add_u32_e32 v228, 0x8000, v228
	v_add_u32_e32 v229, 0x8000, v229
	v_add_u32_e32 v230, 0x8000, v230
	v_add_u32_e32 v231, 0x8000, v231
	v_perm_b32 v232, v229, v228, s58
	v_perm_b32 v233, v231, v230, s58
	global_store_dwordx2 v[204:205], v[232:233], off offset:256
	s_mov_b64 vcc, 0x20000
	v_lshl_add_u64 v[218:219], v[218:219], 0, vcc
	v_lshl_add_u64 v[220:221], v[220:221], 0, vcc
	s_mov_b64 vcc, 0x10000
	v_lshl_add_u64 v[202:203], v[202:203], 0, vcc
	v_lshl_add_u64 v[204:205], v[204:205], 0, vcc
	global_store_dwordx4 v[218:219], v[8:11], off
	v_pk_mul_f32 v[224:225], v[64:65], v[8:9]
	v_pk_mul_f32 v[226:227], v[66:67], v[10:11]
	v_add_u32_e32 v224, 0x8000, v224
	v_add_u32_e32 v225, 0x8000, v225
	v_add_u32_e32 v226, 0x8000, v226
	v_add_u32_e32 v227, 0x8000, v227
	v_perm_b32 v222, v225, v224, s58
	v_perm_b32 v223, v227, v226, s58
	global_store_dwordx2 v[202:203], v[222:223], off
	global_store_dwordx4 v[218:219], v[0:3], off offset:512
	v_pk_mul_f32 v[228:229], v[72:73], v[0:1]
	v_pk_mul_f32 v[230:231], v[74:75], v[2:3]
	v_add_u32_e32 v228, 0x8000, v228
	v_add_u32_e32 v229, 0x8000, v229
	v_add_u32_e32 v230, 0x8000, v230
	v_add_u32_e32 v231, 0x8000, v231
	v_perm_b32 v232, v229, v228, s58
	v_perm_b32 v233, v231, v230, s58
	global_store_dwordx2 v[202:203], v[232:233], off offset:256
	global_store_dwordx4 v[220:221], v[12:15], off
	v_pk_mul_f32 v[224:225], v[80:81], v[12:13]
	v_pk_mul_f32 v[226:227], v[82:83], v[14:15]
	v_add_u32_e32 v224, 0x8000, v224
	v_add_u32_e32 v225, 0x8000, v225
	v_add_u32_e32 v226, 0x8000, v226
	v_add_u32_e32 v227, 0x8000, v227
	v_perm_b32 v222, v225, v224, s58
	v_perm_b32 v223, v227, v226, s58
	global_store_dwordx2 v[204:205], v[222:223], off
	global_store_dwordx4 v[220:221], v[4:7], off offset:512
	v_pk_mul_f32 v[228:229], v[84:85], v[4:5]
	v_pk_mul_f32 v[230:231], v[86:87], v[6:7]
	v_add_u32_e32 v228, 0x8000, v228
	v_add_u32_e32 v229, 0x8000, v229
	v_add_u32_e32 v230, 0x8000, v230
	v_add_u32_e32 v231, 0x8000, v231
	v_perm_b32 v232, v229, v228, s58
	v_perm_b32 v233, v231, v230, s58
	global_store_dwordx2 v[204:205], v[232:233], off offset:256
	s_and_b64 vcc, exec, s[6:7]
	s_mov_b64 s[4:5], -1
	s_cbranch_vccnz .LBB0_301
	s_andn2_b64 vcc, exec, s[12:13]
	s_cbranch_vccnz .LBB0_300
	s_barrier
	s_branch .LBB0_300

;     __device__ __forceinline__ void operator()(const f32x4 (&acc)[2][2][4][2], const Unit& u, int wr, int wc, int fr, int fq) const {
;         const int row0 = u.pm * BM + wr * 64 + fr, col0 = u.pn * BM + wc * 32 + 4 * fq;
;         const float* rbase = (u.pm * BM < SEQ_P) ? resA : (resB - (size_t)SEQ_P * ldc);
;         f32x4 wv[2][2];
;         if (xn) {
; #pragma unroll
;             for (int bj = 0; bj < 2; ++bj)
; #pragma unroll
;                 for (int n = 0; n < 2; ++n) wv[bj][n] = *(const f32x4*)(wn + col0 + bj * HALF + n * 16);
;         }
; #pragma unroll
;         for (int ai = 0; ai < 2; ++ai)
; #pragma unroll
;             for (int m = 0; m < 4; ++m) {
;                 const int row = row0 + ai * HALF + m * 16;
;                 const size_t off = (size_t)row * ldc + col0;
;                 float q = 0.f;
; #pragma unroll
;                 for (int bj = 0; bj < 2; ++bj)
; #pragma unroll
;                     for (int n = 0; n < 2; ++n) {
;                         const f32x4 rv = *(const f32x4*)(rbase + off + bj * HALF + n * 16);
;                         const f32x4 v = rv + acc[ai][bj][m][n] * scale;
;                         if (out) *(f32x4*)(out + off + bj * HALF + n * 16) = v;
;                         if (xn) { q += (v.x * v.x + v.y * v.y) + (v.z * v.z + v.w * v.w); const f32x4 o = v * wv[bj][n];
;                             u32x2 p; p.x = pk2(o.x, o.y); p.y = pk2(o.z, o.w); *(u32x2*)(xn + off + bj * HALF + n * 16) = p; }
;                     }
;                 if (xn) { q += __shfl_xor(q, 16); q += __shfl_xor(q, 32); if (fq == 0) (void)__hip_atomic_fetch_add(ss + row, q, __ATOMIC_RELAXED, __HIP_MEMORY_SCOPE_AGENT); }
.LBB0_1085:
	v_lshl_add_u32 v212, s34, 8, v164
	v_lshl_or_b32 v214, s4, 8, v168
	v_and_b32_e32 v243, 8, v172
	v_mov_b32_e32 v213, 0
	v_cmp_eq_u32_e64 s[34:35], 0, v243
	v_lshlrev_b32_e32 v173, 1, v243
	v_add_u32_e32 v216, v214, v173
	v_sub_u32_e32 v234, 16, v173
	v_add_u32_e32 v234, v214, v234
	v_mov_b32_e32 v214, v216
	v_mov_b32_e32 v216, v234
	v_mov_b32_e32 v215, 0
	v_mov_b32_e32 v217, 0
	v_sub_u32_e32 v210, v212, v243
	v_mov_b32_e32 v211, 0
	v_lshlrev_b64 v[208:209], 11, v[210:211]
	v_add_u32_e32 v210, 8, v210
	v_lshlrev_b64 v[210:211], 11, v[210:211]
	v_lshl_add_u64 v[208:209], v[208:209], 0, v[214:215]
	v_lshl_add_u64 v[210:211], v[210:211], 0, v[216:217]
	v_lshl_add_u64 v[174:175], v[208:209], 2, s[8:9]
	v_lshl_add_u64 v[200:201], v[210:211], 2, s[8:9]
	v_lshl_add_u64 v[202:203], v[214:215], 2, s[10:11]
	v_lshl_add_u64 v[204:205], v[216:217], 2, s[10:11]
	global_load_dwordx4 v[64:67], v[202:203], off
	global_load_dwordx4 v[72:75], v[202:203], off offset:512
	global_load_dwordx4 v[76:79], v[204:205], off
	global_load_dwordx4 v[84:87], v[204:205], off offset:512
	global_load_dwordx4 v[156:159], v[174:175], off
	global_load_dwordx4 v[160:163], v[174:175], off offset:512
	global_load_dwordx4 v[176:179], v[200:201], off
	global_load_dwordx4 v[180:183], v[200:201], off offset:512
	s_mov_b64 vcc, 0x20000
	v_lshl_add_u64 v[174:175], v[174:175], 0, vcc
	v_lshl_add_u64 v[200:201], v[200:201], 0, vcc
	global_load_dwordx4 v[184:187], v[174:175], off
	global_load_dwordx4 v[188:191], v[174:175], off offset:512
	global_load_dwordx4 v[192:195], v[200:201], off
	global_load_dwordx4 v[196:199], v[200:201], off offset:512
	s_mov_b64 vcc, 0x20000
	v_lshl_add_u64 v[174:175], v[174:175], 0, vcc
	v_lshl_add_u64 v[200:201], v[200:201], 0, vcc
	v_lshl_add_u64 v[218:219], v[208:209], 2, s[8:9]
	v_lshl_add_u64 v[220:221], v[210:211], 2, s[8:9]
	v_lshl_add_u64 v[202:203], v[208:209], 1, s[14:15]
	v_lshl_add_u64 v[204:205], v[210:211], 1, s[14:15]
	v_lshl_add_u64 v[206:207], v[212:213], 2, s[16:17]
	v_xor_b32_e32 v235, 16, v172
	v_xor_b32_e32 v240, 32, v172
	v_lshlrev_b32_e32 v235, 2, v235
	v_lshlrev_b32_e32 v240, 2, v240
	v_mov_b32_dpp v236, v136 row_ror:8 row_mask:0xf bank_mask:0xf
	v_mov_b32_dpp v237, v137 row_ror:8 row_mask:0xf bank_mask:0xf
	v_mov_b32_dpp v238, v138 row_ror:8 row_mask:0xf bank_mask:0xf
	v_mov_b32_dpp v239, v139 row_ror:8 row_mask:0xf bank_mask:0xf
	v_cndmask_b32_e64 v136, v236, v140, s[34:35]
	v_cndmask_b32_e64 v137, v237, v141, s[34:35]
	v_cndmask_b32_e64 v138, v238, v142, s[34:35]
	v_cndmask_b32_e64 v139, v239, v143, s[34:35]
	v_cndmask_b32_e64 v140, v140, v236, s[34:35]
	v_cndmask_b32_e64 v141, v141, v237, s[34:35]
	v_cndmask_b32_e64 v142, v142, v238, s[34:35]
	v_cndmask_b32_e64 v143, v143, v239, s[34:35]
	v_mov_b32_dpp v236, v128 row_ror:8 row_mask:0xf bank_mask:0xf
	v_mov_b32_dpp v237, v129 row_ror:8 row_mask:0xf bank_mask:0xf
	v_mov_b32_dpp v238, v130 row_ror:8 row_mask:0xf bank_mask:0xf
	v_mov_b32_dpp v239, v131 row_ror:8 row_mask:0xf bank_mask:0xf
	v_cndmask_b32_e64 v128, v236, v132, s[34:35]
	v_cndmask_b32_e64 v129, v237, v133, s[34:35]
	v_cndmask_b32_e64 v130, v238, v134, s[34:35]
	v_cndmask_b32_e64 v131, v239, v135, s[34:35]
	v_cndmask_b32_e64 v132, v132, v236, s[34:35]
	v_cndmask_b32_e64 v133, v133, v237, s[34:35]
	v_cndmask_b32_e64 v134, v134, v238, s[34:35]
	v_cndmask_b32_e64 v135, v135, v239, s[34:35]
	s_waitcnt vmcnt(4)
	v_pk_add_f32 v[138:139], v[138:139], v[158:159]
	v_pk_add_f32 v[136:137], v[136:137], v[156:157]
	v_pk_add_f32 v[130:131], v[130:131], v[162:163]
	v_pk_add_f32 v[128:129], v[128:129], v[160:161]
	v_pk_add_f32 v[142:143], v[142:143], v[178:179]
	v_pk_add_f32 v[140:141], v[140:141], v[176:177]
	v_pk_add_f32 v[134:135], v[134:135], v[182:183]
	v_pk_add_f32 v[132:133], v[132:133], v[180:181]
	global_load_dwordx4 v[156:159], v[174:175], off
	global_load_dwordx4 v[160:163], v[174:175], off offset:512
	global_load_dwordx4 v[176:179], v[200:201], off
	global_load_dwordx4 v[180:183], v[200:201], off offset:512
	s_mov_b64 vcc, 0x20000
	v_lshl_add_u64 v[174:175], v[174:175], 0, vcc
	v_lshl_add_u64 v[200:201], v[200:201], 0, vcc
	v_mul_f32_e32 v173, v136, v136
	v_fmac_f32_e32 v173, v137, v137
	v_fmac_f32_e32 v173, v138, v138
	v_fmac_f32_e32 v173, v139, v139
	v_fmac_f32_e32 v173, v128, v128
	v_fmac_f32_e32 v173, v129, v129
	v_fmac_f32_e32 v173, v130, v130
	v_fmac_f32_e32 v173, v131, v131
	v_mul_f32_e32 v234, v140, v140
	v_fmac_f32_e32 v234, v141, v141
	v_fmac_f32_e32 v234, v142, v142
	v_fmac_f32_e32 v234, v143, v143
	v_fmac_f32_e32 v234, v132, v132
	v_fmac_f32_e32 v234, v133, v133
	v_fmac_f32_e32 v234, v134, v134
	v_fmac_f32_e32 v234, v135, v135
	s_nop 1
	v_mov_b32_dpp v241, v173 row_ror:8 row_mask:0xf bank_mask:0xf
	v_mov_b32_dpp v242, v234 row_ror:8 row_mask:0xf bank_mask:0xf
	v_add_f32_e32 v173, v173, v241
	v_add_f32_e32 v234, v234, v242
	v_cndmask_b32_e64 v173, v234, v173, s[34:35]
	s_nop 0
	ds_bpermute_b32 v241, v235, v173
	s_waitcnt lgkmcnt(0)
	v_add_f32_e32 v173, v173, v241
	s_nop 0
	ds_bpermute_b32 v242, v240, v173
	s_waitcnt lgkmcnt(0)
;     __device__ __forceinline__ void operator()(const f32x4 (&acc)[2][2][4][2], const Unit& u, int wr, int wc, int fr, int fq) const {
;     ...
;         for (int ai = 0; ai < 2; ++ai)
; #pragma unroll
;             for (int m = 0; m < 4; ++m) {
;                 const int row = row0 + ai * HALF + m * 16;
;                 const size_t off = (size_t)row * ldc + col0;
;                 float q = 0.f;
; #pragma unroll
;                 for (int bj = 0; bj < 2; ++bj)
; #pragma unroll
;                     for (int n = 0; n < 2; ++n) {
;                         const f32x4 rv = *(const f32x4*)(rbase + off + bj * HALF + n * 16);
;                         const f32x4 v = rv + acc[ai][bj][m][n] * scale;
;                         if (out) *(f32x4*)(out + off + bj * HALF + n * 16) = v;
;                         if (xn) { q += (v.x * v.x + v.y * v.y) + (v.z * v.z + v.w * v.w); const f32x4 o = v * wv[bj][n];
;                             u32x2 p; p.x = pk2(o.x, o.y); p.y = pk2(o.z, o.w); *(u32x2*)(xn + off + bj * HALF + n * 16) = p; }
;                     }
;                 if (xn) { q += __shfl_xor(q, 16); q += __shfl_xor(q, 32); if (fq == 0) (void)__hip_atomic_fetch_add(ss + row, q, __ATOMIC_RELAXED, __HIP_MEMORY_SCOPE_AGENT); }
	v_add_f32_e32 v173, v173, v242
	s_mov_b64 exec, s[0:1]
	global_atomic_add_f32 v[206:207], v173, off
	s_mov_b64 exec, -1
	s_mov_b64 vcc, 64
	v_lshl_add_u64 v[206:207], v[206:207], 0, vcc
	v_mov_b32_dpp v236, v120 row_ror:8 row_mask:0xf bank_mask:0xf
	v_mov_b32_dpp v237, v121 row_ror:8 row_mask:0xf bank_mask:0xf
	v_mov_b32_dpp v238, v122 row_ror:8 row_mask:0xf bank_mask:0xf
	v_mov_b32_dpp v239, v123 row_ror:8 row_mask:0xf bank_mask:0xf
	v_cndmask_b32_e64 v120, v236, v124, s[34:35]
	v_cndmask_b32_e64 v121, v237, v125, s[34:35]
	v_cndmask_b32_e64 v122, v238, v126, s[34:35]
	v_cndmask_b32_e64 v123, v239, v127, s[34:35]
	v_cndmask_b32_e64 v124, v124, v236, s[34:35]
	v_cndmask_b32_e64 v125, v125, v237, s[34:35]
	v_cndmask_b32_e64 v126, v126, v238, s[34:35]
	v_cndmask_b32_e64 v127, v127, v239, s[34:35]
	v_mov_b32_dpp v236, v112 row_ror:8 row_mask:0xf bank_mask:0xf
	v_mov_b32_dpp v237, v113 row_ror:8 row_mask:0xf bank_mask:0xf
	v_mov_b32_dpp v238, v114 row_ror:8 row_mask:0xf bank_mask:0xf
	v_mov_b32_dpp v239, v115 row_ror:8 row_mask:0xf bank_mask:0xf
	v_cndmask_b32_e64 v112, v236, v116, s[34:35]
	v_cndmask_b32_e64 v113, v237, v117, s[34:35]
	v_cndmask_b32_e64 v114, v238, v118, s[34:35]
	v_cndmask_b32_e64 v115, v239, v119, s[34:35]
	v_cndmask_b32_e64 v116, v116, v236, s[34:35]
	v_cndmask_b32_e64 v117, v117, v237, s[34:35]
	v_cndmask_b32_e64 v118, v118, v238, s[34:35]
	v_cndmask_b32_e64 v119, v119, v239, s[34:35]
	s_waitcnt vmcnt(5)
	v_pk_add_f32 v[122:123], v[122:123], v[186:187]
	v_pk_add_f32 v[120:121], v[120:121], v[184:185]
	v_pk_add_f32 v[114:115], v[114:115], v[190:191]
	v_pk_add_f32 v[112:113], v[112:113], v[188:189]
	v_pk_add_f32 v[126:127], v[126:127], v[194:195]
	v_pk_add_f32 v[124:125], v[124:125], v[192:193]
	v_pk_add_f32 v[118:119], v[118:119], v[198:199]
	v_pk_add_f32 v[116:117], v[116:117], v[196:197]
	global_load_dwordx4 v[184:187], v[174:175], off
	global_load_dwordx4 v[188:191], v[174:175], off offset:512
	global_load_dwordx4 v[192:195], v[200:201], off
	global_load_dwordx4 v[196:199], v[200:201], off offset:512
	s_mov_b64 vcc, 0xa0000
	v_lshl_add_u64 v[174:175], v[174:175], 0, vcc
	v_lshl_add_u64 v[200:201], v[200:201], 0, vcc
	v_mul_f32_e32 v173, v120, v120
	v_fmac_f32_e32 v173, v121, v121
	v_fmac_f32_e32 v173, v122, v122
	v_fmac_f32_e32 v173, v123, v123
	v_fmac_f32_e32 v173, v112, v112
	v_fmac_f32_e32 v173, v113, v113
	v_fmac_f32_e32 v173, v114, v114
	v_fmac_f32_e32 v173, v115, v115
	v_mul_f32_e32 v234, v124, v124
	v_fmac_f32_e32 v234, v125, v125
	v_fmac_f32_e32 v234, v126, v126
	v_fmac_f32_e32 v234, v127, v127
	v_fmac_f32_e32 v234, v116, v116
	v_fmac_f32_e32 v234, v117, v117
	v_fmac_f32_e32 v234, v118, v118
	v_fmac_f32_e32 v234, v119, v119
	s_nop 1
	v_mov_b32_dpp v241, v173 row_ror:8 row_mask:0xf bank_mask:0xf
	v_mov_b32_dpp v242, v234 row_ror:8 row_mask:0xf bank_mask:0xf
	v_add_f32_e32 v173, v173, v241
	v_add_f32_e32 v234, v234, v242
	v_cndmask_b32_e64 v173, v234, v173, s[34:35]
	s_nop 0
	ds_bpermute_b32 v241, v235, v173
	s_waitcnt lgkmcnt(0)
	v_add_f32_e32 v173, v173, v241
	s_nop 0
	ds_bpermute_b32 v242, v240, v173
	s_waitcnt lgkmcnt(0)
	v_add_f32_e32 v173, v173, v242
	s_mov_b64 exec, s[0:1]
	global_atomic_add_f32 v[206:207], v173, off
	s_mov_b64 exec, -1
	s_mov_b64 vcc, 64
	v_lshl_add_u64 v[206:207], v[206:207], 0, vcc
	v_mov_b32_dpp v236, v104 row_ror:8 row_mask:0xf bank_mask:0xf
	v_mov_b32_dpp v237, v105 row_ror:8 row_mask:0xf bank_mask:0xf
	v_mov_b32_dpp v238, v106 row_ror:8 row_mask:0xf bank_mask:0xf
	v_mov_b32_dpp v239, v107 row_ror:8 row_mask:0xf bank_mask:0xf
	v_cndmask_b32_e64 v104, v236, v108, s[34:35]
	v_cndmask_b32_e64 v105, v237, v109, s[34:35]
	v_cndmask_b32_e64 v106, v238, v110, s[34:35]
	v_cndmask_b32_e64 v107, v239, v111, s[34:35]
	v_cndmask_b32_e64 v108, v108, v236, s[34:35]
	v_cndmask_b32_e64 v109, v109, v237, s[34:35]
	v_cndmask_b32_e64 v110, v110, v238, s[34:35]
	v_cndmask_b32_e64 v111, v111, v239, s[34:35]
	v_mov_b32_dpp v236, v96 row_ror:8 row_mask:0xf bank_mask:0xf
	v_mov_b32_dpp v237, v97 row_ror:8 row_mask:0xf bank_mask:0xf
	v_mov_b32_dpp v238, v98 row_ror:8 row_mask:0xf bank_mask:0xf
	v_mov_b32_dpp v239, v99 row_ror:8 row_mask:0xf bank_mask:0xf
	v_cndmask_b32_e64 v96, v236, v100, s[34:35]
	v_cndmask_b32_e64 v97, v237, v101, s[34:35]
	v_cndmask_b32_e64 v98, v238, v102, s[34:35]
	v_cndmask_b32_e64 v99, v239, v103, s[34:35]
	v_cndmask_b32_e64 v100, v100, v236, s[34:35]
	v_cndmask_b32_e64 v101, v101, v237, s[34:35]
	v_cndmask_b32_e64 v102, v102, v238, s[34:35]
	v_cndmask_b32_e64 v103, v103, v239, s[34:35]
	s_waitcnt vmcnt(6)
	v_pk_add_f32 v[106:107], v[106:107], v[158:159]
	v_pk_add_f32 v[104:105], v[104:105], v[156:157]
	v_pk_add_f32 v[98:99], v[98:99], v[162:163]
	v_pk_add_f32 v[96:97], v[96:97], v[160:161]
	v_pk_add_f32 v[110:111], v[110:111], v[178:179]
	v_pk_add_f32 v[108:109], v[108:109], v[176:177]
	v_pk_add_f32 v[102:103], v[102:103], v[182:183]
	v_pk_add_f32 v[100:101], v[100:101], v[180:181]
	global_load_dwordx4 v[156:159], v[174:175], off
	global_load_dwordx4 v[160:163], v[174:175], off offset:512
	global_load_dwordx4 v[176:179], v[200:201], off
	global_load_dwordx4 v[180:183], v[200:201], off offset:512
	s_mov_b64 vcc, 0x20000
	v_lshl_add_u64 v[174:175], v[174:175], 0, vcc
	v_lshl_add_u64 v[200:201], v[200:201], 0, vcc
	v_mul_f32_e32 v173, v104, v104
	v_fmac_f32_e32 v173, v105, v105
	v_fmac_f32_e32 v173, v106, v106
	v_fmac_f32_e32 v173, v107, v107
	v_fmac_f32_e32 v173, v96, v96
	v_fmac_f32_e32 v173, v97, v97
	v_fmac_f32_e32 v173, v98, v98
	v_fmac_f32_e32 v173, v99, v99
	v_mul_f32_e32 v234, v108, v108
	v_fmac_f32_e32 v234, v109, v109
	v_fmac_f32_e32 v234, v110, v110
	v_fmac_f32_e32 v234, v111, v111
	v_fmac_f32_e32 v234, v100, v100
	v_fmac_f32_e32 v234, v101, v101
	v_fmac_f32_e32 v234, v102, v102
	v_fmac_f32_e32 v234, v103, v103
	s_nop 1
	v_mov_b32_dpp v241, v173 row_ror:8 row_mask:0xf bank_mask:0xf
	v_mov_b32_dpp v242, v234 row_ror:8 row_mask:0xf bank_mask:0xf
	v_add_f32_e32 v173, v173, v241
	v_add_f32_e32 v234, v234, v242
	v_cndmask_b32_e64 v173, v234, v173, s[34:35]
	s_nop 0
	ds_bpermute_b32 v241, v235, v173
	s_waitcnt lgkmcnt(0)
;     __device__ __forceinline__ void operator()(const f32x4 (&acc)[2][2][4][2], const Unit& u, int wr, int wc, int fr, int fq) const {
;     ...
;         for (int ai = 0; ai < 2; ++ai)
; #pragma unroll
;             for (int m = 0; m < 4; ++m) {
;                 const int row = row0 + ai * HALF + m * 16;
;                 const size_t off = (size_t)row * ldc + col0;
;                 float q = 0.f;
; #pragma unroll
;                 for (int bj = 0; bj < 2; ++bj)
; #pragma unroll
;                     for (int n = 0; n < 2; ++n) {
;                         const f32x4 rv = *(const f32x4*)(rbase + off + bj * HALF + n * 16);
;                         const f32x4 v = rv + acc[ai][bj][m][n] * scale;
;                         if (out) *(f32x4*)(out + off + bj * HALF + n * 16) = v;
;                         if (xn) { q += (v.x * v.x + v.y * v.y) + (v.z * v.z + v.w * v.w); const f32x4 o = v * wv[bj][n];
;                             u32x2 p; p.x = pk2(o.x, o.y); p.y = pk2(o.z, o.w); *(u32x2*)(xn + off + bj * HALF + n * 16) = p; }
;                     }
;                 if (xn) { q += __shfl_xor(q, 16); q += __shfl_xor(q, 32); if (fq == 0) (void)__hip_atomic_fetch_add(ss + row, q, __ATOMIC_RELAXED, __HIP_MEMORY_SCOPE_AGENT); }
	v_add_f32_e32 v173, v173, v241
	s_nop 0
	ds_bpermute_b32 v242, v240, v173
	s_waitcnt lgkmcnt(0)
	v_add_f32_e32 v173, v173, v242
	s_mov_b64 exec, s[0:1]
	global_atomic_add_f32 v[206:207], v173, off
	s_mov_b64 exec, -1
	s_mov_b64 vcc, 64
	v_lshl_add_u64 v[206:207], v[206:207], 0, vcc
	v_mov_b32_dpp v236, v88 row_ror:8 row_mask:0xf bank_mask:0xf
	v_mov_b32_dpp v237, v89 row_ror:8 row_mask:0xf bank_mask:0xf
	v_mov_b32_dpp v238, v90 row_ror:8 row_mask:0xf bank_mask:0xf
	v_mov_b32_dpp v239, v91 row_ror:8 row_mask:0xf bank_mask:0xf
	v_cndmask_b32_e64 v88, v236, v92, s[34:35]
	v_cndmask_b32_e64 v89, v237, v93, s[34:35]
	v_cndmask_b32_e64 v90, v238, v94, s[34:35]
	v_cndmask_b32_e64 v91, v239, v95, s[34:35]
	v_cndmask_b32_e64 v92, v92, v236, s[34:35]
	v_cndmask_b32_e64 v93, v93, v237, s[34:35]
	v_cndmask_b32_e64 v94, v94, v238, s[34:35]
	v_cndmask_b32_e64 v95, v95, v239, s[34:35]
	v_mov_b32_dpp v236, v68 row_ror:8 row_mask:0xf bank_mask:0xf
	v_mov_b32_dpp v237, v69 row_ror:8 row_mask:0xf bank_mask:0xf
	v_mov_b32_dpp v238, v70 row_ror:8 row_mask:0xf bank_mask:0xf
	v_mov_b32_dpp v239, v71 row_ror:8 row_mask:0xf bank_mask:0xf
	v_cndmask_b32_e64 v68, v236, v80, s[34:35]
	v_cndmask_b32_e64 v69, v237, v81, s[34:35]
	v_cndmask_b32_e64 v70, v238, v82, s[34:35]
	v_cndmask_b32_e64 v71, v239, v83, s[34:35]
	v_cndmask_b32_e64 v80, v80, v236, s[34:35]
	v_cndmask_b32_e64 v81, v81, v237, s[34:35]
	v_cndmask_b32_e64 v82, v82, v238, s[34:35]
	v_cndmask_b32_e64 v83, v83, v239, s[34:35]
	s_waitcnt vmcnt(6)
	v_pk_add_f32 v[90:91], v[90:91], v[186:187]
	v_pk_add_f32 v[88:89], v[88:89], v[184:185]
	v_pk_add_f32 v[70:71], v[70:71], v[190:191]
	v_pk_add_f32 v[68:69], v[68:69], v[188:189]
	v_pk_add_f32 v[94:95], v[94:95], v[194:195]
	v_pk_add_f32 v[92:93], v[92:93], v[192:193]
	v_pk_add_f32 v[82:83], v[82:83], v[198:199]
	v_pk_add_f32 v[80:81], v[80:81], v[196:197]
	global_load_dwordx4 v[184:187], v[174:175], off
	global_load_dwordx4 v[188:191], v[174:175], off offset:512
	global_load_dwordx4 v[192:195], v[200:201], off
	global_load_dwordx4 v[196:199], v[200:201], off offset:512
	s_mov_b64 vcc, 0x20000
	v_lshl_add_u64 v[174:175], v[174:175], 0, vcc
	v_lshl_add_u64 v[200:201], v[200:201], 0, vcc
	v_mul_f32_e32 v173, v88, v88
	v_fmac_f32_e32 v173, v89, v89
	v_fmac_f32_e32 v173, v90, v90
	v_fmac_f32_e32 v173, v91, v91
	v_fmac_f32_e32 v173, v68, v68
	v_fmac_f32_e32 v173, v69, v69
	v_fmac_f32_e32 v173, v70, v70
	v_fmac_f32_e32 v173, v71, v71
	v_mul_f32_e32 v234, v92, v92
	v_fmac_f32_e32 v234, v93, v93
	v_fmac_f32_e32 v234, v94, v94
	v_fmac_f32_e32 v234, v95, v95
	v_fmac_f32_e32 v234, v80, v80
	v_fmac_f32_e32 v234, v81, v81
	v_fmac_f32_e32 v234, v82, v82
	v_fmac_f32_e32 v234, v83, v83
	s_nop 1
	v_mov_b32_dpp v241, v173 row_ror:8 row_mask:0xf bank_mask:0xf
	v_mov_b32_dpp v242, v234 row_ror:8 row_mask:0xf bank_mask:0xf
	v_add_f32_e32 v173, v173, v241
	v_add_f32_e32 v234, v234, v242
	v_cndmask_b32_e64 v173, v234, v173, s[34:35]
	s_nop 0
	ds_bpermute_b32 v241, v235, v173
	s_waitcnt lgkmcnt(0)
	v_add_f32_e32 v173, v173, v241
	s_nop 0
	ds_bpermute_b32 v242, v240, v173
	s_waitcnt lgkmcnt(0)
	v_add_f32_e32 v173, v173, v242
	s_mov_b64 exec, s[0:1]
	global_atomic_add_f32 v[206:207], v173, off
	s_mov_b64 exec, -1
	s_mov_b64 vcc, 320
	v_lshl_add_u64 v[206:207], v[206:207], 0, vcc
	v_mov_b32_dpp v236, v56 row_ror:8 row_mask:0xf bank_mask:0xf
	v_mov_b32_dpp v237, v57 row_ror:8 row_mask:0xf bank_mask:0xf
	v_mov_b32_dpp v238, v58 row_ror:8 row_mask:0xf bank_mask:0xf
	v_mov_b32_dpp v239, v59 row_ror:8 row_mask:0xf bank_mask:0xf
	v_cndmask_b32_e64 v56, v236, v60, s[34:35]
	v_cndmask_b32_e64 v57, v237, v61, s[34:35]
	v_cndmask_b32_e64 v58, v238, v62, s[34:35]
	v_cndmask_b32_e64 v59, v239, v63, s[34:35]
	v_cndmask_b32_e64 v60, v60, v236, s[34:35]
	v_cndmask_b32_e64 v61, v61, v237, s[34:35]
	v_cndmask_b32_e64 v62, v62, v238, s[34:35]
	v_cndmask_b32_e64 v63, v63, v239, s[34:35]
	v_mov_b32_dpp v236, v48 row_ror:8 row_mask:0xf bank_mask:0xf
	v_mov_b32_dpp v237, v49 row_ror:8 row_mask:0xf bank_mask:0xf
	v_mov_b32_dpp v238, v50 row_ror:8 row_mask:0xf bank_mask:0xf
	v_mov_b32_dpp v239, v51 row_ror:8 row_mask:0xf bank_mask:0xf
	v_cndmask_b32_e64 v48, v236, v52, s[34:35]
	v_cndmask_b32_e64 v49, v237, v53, s[34:35]
	v_cndmask_b32_e64 v50, v238, v54, s[34:35]
	v_cndmask_b32_e64 v51, v239, v55, s[34:35]
	v_cndmask_b32_e64 v52, v52, v236, s[34:35]
	v_cndmask_b32_e64 v53, v53, v237, s[34:35]
	v_cndmask_b32_e64 v54, v54, v238, s[34:35]
	v_cndmask_b32_e64 v55, v55, v239, s[34:35]
	s_waitcnt vmcnt(6)
	v_pk_add_f32 v[58:59], v[58:59], v[158:159]
	v_pk_add_f32 v[56:57], v[56:57], v[156:157]
	v_pk_add_f32 v[50:51], v[50:51], v[162:163]
	v_pk_add_f32 v[48:49], v[48:49], v[160:161]
	v_pk_add_f32 v[62:63], v[62:63], v[178:179]
	v_pk_add_f32 v[60:61], v[60:61], v[176:177]
	v_pk_add_f32 v[54:55], v[54:55], v[182:183]
	v_pk_add_f32 v[52:53], v[52:53], v[180:181]
	global_load_dwordx4 v[156:159], v[174:175], off
	global_load_dwordx4 v[160:163], v[174:175], off offset:512
	global_load_dwordx4 v[176:179], v[200:201], off
	global_load_dwordx4 v[180:183], v[200:201], off offset:512
	s_mov_b64 vcc, 0x20000
	v_lshl_add_u64 v[174:175], v[174:175], 0, vcc
	v_lshl_add_u64 v[200:201], v[200:201], 0, vcc
	v_mul_f32_e32 v173, v56, v56
	v_fmac_f32_e32 v173, v57, v57
	v_fmac_f32_e32 v173, v58, v58
	v_fmac_f32_e32 v173, v59, v59
	v_fmac_f32_e32 v173, v48, v48
	v_fmac_f32_e32 v173, v49, v49
	v_fmac_f32_e32 v173, v50, v50
	v_fmac_f32_e32 v173, v51, v51
	v_mul_f32_e32 v234, v60, v60
	v_fmac_f32_e32 v234, v61, v61
	v_fmac_f32_e32 v234, v62, v62
	v_fmac_f32_e32 v234, v63, v63
	v_fmac_f32_e32 v234, v52, v52
	v_fmac_f32_e32 v234, v53, v53
	v_fmac_f32_e32 v234, v54, v54
	v_fmac_f32_e32 v234, v55, v55
	s_nop 1
	v_mov_b32_dpp v241, v173 row_ror:8 row_mask:0xf bank_mask:0xf
	v_mov_b32_dpp v242, v234 row_ror:8 row_mask:0xf bank_mask:0xf
	v_add_f32_e32 v173, v173, v241
	v_add_f32_e32 v234, v234, v242
	v_cndmask_b32_e64 v173, v234, v173, s[34:35]
	s_nop 0
	ds_bpermute_b32 v241, v235, v173
	s_waitcnt lgkmcnt(0)
;     __device__ __forceinline__ void operator()(const f32x4 (&acc)[2][2][4][2], const Unit& u, int wr, int wc, int fr, int fq) const {
;     ...
;         for (int ai = 0; ai < 2; ++ai)
; #pragma unroll
;             for (int m = 0; m < 4; ++m) {
;                 const int row = row0 + ai * HALF + m * 16;
;                 const size_t off = (size_t)row * ldc + col0;
;                 float q = 0.f;
; #pragma unroll
;                 for (int bj = 0; bj < 2; ++bj)
; #pragma unroll
;                     for (int n = 0; n < 2; ++n) {
;                         const f32x4 rv = *(const f32x4*)(rbase + off + bj * HALF + n * 16);
;                         const f32x4 v = rv + acc[ai][bj][m][n] * scale;
;                         if (out) *(f32x4*)(out + off + bj * HALF + n * 16) = v;
;                         if (xn) { q += (v.x * v.x + v.y * v.y) + (v.z * v.z + v.w * v.w); const f32x4 o = v * wv[bj][n];
;                             u32x2 p; p.x = pk2(o.x, o.y); p.y = pk2(o.z, o.w); *(u32x2*)(xn + off + bj * HALF + n * 16) = p; }
;                     }
;                 if (xn) { q += __shfl_xor(q, 16); q += __shfl_xor(q, 32); if (fq == 0) (void)__hip_atomic_fetch_add(ss + row, q, __ATOMIC_RELAXED, __HIP_MEMORY_SCOPE_AGENT); }
	v_add_f32_e32 v173, v173, v241
	s_nop 0
	ds_bpermute_b32 v242, v240, v173
	s_waitcnt lgkmcnt(0)
	v_add_f32_e32 v173, v173, v242
	s_mov_b64 exec, s[0:1]
	global_atomic_add_f32 v[206:207], v173, off
	s_mov_b64 exec, -1
	s_mov_b64 vcc, 64
	v_lshl_add_u64 v[206:207], v[206:207], 0, vcc
	v_mov_b32_dpp v236, v40 row_ror:8 row_mask:0xf bank_mask:0xf
	v_mov_b32_dpp v237, v41 row_ror:8 row_mask:0xf bank_mask:0xf
	v_mov_b32_dpp v238, v42 row_ror:8 row_mask:0xf bank_mask:0xf
	v_mov_b32_dpp v239, v43 row_ror:8 row_mask:0xf bank_mask:0xf
	v_cndmask_b32_e64 v40, v236, v44, s[34:35]
	v_cndmask_b32_e64 v41, v237, v45, s[34:35]
	v_cndmask_b32_e64 v42, v238, v46, s[34:35]
	v_cndmask_b32_e64 v43, v239, v47, s[34:35]
	v_cndmask_b32_e64 v44, v44, v236, s[34:35]
	v_cndmask_b32_e64 v45, v45, v237, s[34:35]
	v_cndmask_b32_e64 v46, v46, v238, s[34:35]
	v_cndmask_b32_e64 v47, v47, v239, s[34:35]
	v_mov_b32_dpp v236, v32 row_ror:8 row_mask:0xf bank_mask:0xf
	v_mov_b32_dpp v237, v33 row_ror:8 row_mask:0xf bank_mask:0xf
	v_mov_b32_dpp v238, v34 row_ror:8 row_mask:0xf bank_mask:0xf
	v_mov_b32_dpp v239, v35 row_ror:8 row_mask:0xf bank_mask:0xf
	v_cndmask_b32_e64 v32, v236, v36, s[34:35]
	v_cndmask_b32_e64 v33, v237, v37, s[34:35]
	v_cndmask_b32_e64 v34, v238, v38, s[34:35]
	v_cndmask_b32_e64 v35, v239, v39, s[34:35]
	v_cndmask_b32_e64 v36, v36, v236, s[34:35]
	v_cndmask_b32_e64 v37, v37, v237, s[34:35]
	v_cndmask_b32_e64 v38, v38, v238, s[34:35]
	v_cndmask_b32_e64 v39, v39, v239, s[34:35]
	s_waitcnt vmcnt(6)
	v_pk_add_f32 v[42:43], v[42:43], v[186:187]
	v_pk_add_f32 v[40:41], v[40:41], v[184:185]
	v_pk_add_f32 v[34:35], v[34:35], v[190:191]
	v_pk_add_f32 v[32:33], v[32:33], v[188:189]
	v_pk_add_f32 v[46:47], v[46:47], v[194:195]
	v_pk_add_f32 v[44:45], v[44:45], v[192:193]
	v_pk_add_f32 v[38:39], v[38:39], v[198:199]
	v_pk_add_f32 v[36:37], v[36:37], v[196:197]
	global_load_dwordx4 v[184:187], v[174:175], off
	global_load_dwordx4 v[188:191], v[174:175], off offset:512
	global_load_dwordx4 v[192:195], v[200:201], off
	global_load_dwordx4 v[196:199], v[200:201], off offset:512
	v_mul_f32_e32 v173, v40, v40
	v_fmac_f32_e32 v173, v41, v41
	v_fmac_f32_e32 v173, v42, v42
	v_fmac_f32_e32 v173, v43, v43
	v_fmac_f32_e32 v173, v32, v32
	v_fmac_f32_e32 v173, v33, v33
	v_fmac_f32_e32 v173, v34, v34
	v_fmac_f32_e32 v173, v35, v35
	v_mul_f32_e32 v234, v44, v44
	v_fmac_f32_e32 v234, v45, v45
	v_fmac_f32_e32 v234, v46, v46
	v_fmac_f32_e32 v234, v47, v47
	v_fmac_f32_e32 v234, v36, v36
	v_fmac_f32_e32 v234, v37, v37
	v_fmac_f32_e32 v234, v38, v38
	v_fmac_f32_e32 v234, v39, v39
	s_nop 1
	v_mov_b32_dpp v241, v173 row_ror:8 row_mask:0xf bank_mask:0xf
	v_mov_b32_dpp v242, v234 row_ror:8 row_mask:0xf bank_mask:0xf
	v_add_f32_e32 v173, v173, v241
	v_add_f32_e32 v234, v234, v242
	v_cndmask_b32_e64 v173, v234, v173, s[34:35]
	s_nop 0
	ds_bpermute_b32 v241, v235, v173
	s_waitcnt lgkmcnt(0)
	v_add_f32_e32 v173, v173, v241
	s_nop 0
	ds_bpermute_b32 v242, v240, v173
	s_waitcnt lgkmcnt(0)
	v_add_f32_e32 v173, v173, v242
	s_mov_b64 exec, s[0:1]
	global_atomic_add_f32 v[206:207], v173, off
	s_mov_b64 exec, -1
	s_mov_b64 vcc, 64
	v_lshl_add_u64 v[206:207], v[206:207], 0, vcc
	v_mov_b32_dpp v236, v24 row_ror:8 row_mask:0xf bank_mask:0xf
	v_mov_b32_dpp v237, v25 row_ror:8 row_mask:0xf bank_mask:0xf
	v_mov_b32_dpp v238, v26 row_ror:8 row_mask:0xf bank_mask:0xf
	v_mov_b32_dpp v239, v27 row_ror:8 row_mask:0xf bank_mask:0xf
	v_cndmask_b32_e64 v24, v236, v28, s[34:35]
	v_cndmask_b32_e64 v25, v237, v29, s[34:35]
	v_cndmask_b32_e64 v26, v238, v30, s[34:35]
	v_cndmask_b32_e64 v27, v239, v31, s[34:35]
	v_cndmask_b32_e64 v28, v28, v236, s[34:35]
	v_cndmask_b32_e64 v29, v29, v237, s[34:35]
	v_cndmask_b32_e64 v30, v30, v238, s[34:35]
	v_cndmask_b32_e64 v31, v31, v239, s[34:35]
	v_mov_b32_dpp v236, v16 row_ror:8 row_mask:0xf bank_mask:0xf
	v_mov_b32_dpp v237, v17 row_ror:8 row_mask:0xf bank_mask:0xf
	v_mov_b32_dpp v238, v18 row_ror:8 row_mask:0xf bank_mask:0xf
	v_mov_b32_dpp v239, v19 row_ror:8 row_mask:0xf bank_mask:0xf
	v_cndmask_b32_e64 v16, v236, v20, s[34:35]
	v_cndmask_b32_e64 v17, v237, v21, s[34:35]
	v_cndmask_b32_e64 v18, v238, v22, s[34:35]
	v_cndmask_b32_e64 v19, v239, v23, s[34:35]
	v_cndmask_b32_e64 v20, v20, v236, s[34:35]
	v_cndmask_b32_e64 v21, v21, v237, s[34:35]
	v_cndmask_b32_e64 v22, v22, v238, s[34:35]
	v_cndmask_b32_e64 v23, v23, v239, s[34:35]
	s_waitcnt vmcnt(6)
	v_pk_add_f32 v[26:27], v[26:27], v[158:159]
	v_pk_add_f32 v[24:25], v[24:25], v[156:157]
	v_pk_add_f32 v[18:19], v[18:19], v[162:163]
	v_pk_add_f32 v[16:17], v[16:17], v[160:161]
	v_pk_add_f32 v[30:31], v[30:31], v[178:179]
	v_pk_add_f32 v[28:29], v[28:29], v[176:177]
	v_pk_add_f32 v[22:23], v[22:23], v[182:183]
	v_pk_add_f32 v[20:21], v[20:21], v[180:181]
	v_mul_f32_e32 v173, v24, v24
	v_fmac_f32_e32 v173, v25, v25
	v_fmac_f32_e32 v173, v26, v26
	v_fmac_f32_e32 v173, v27, v27
	v_fmac_f32_e32 v173, v16, v16
	v_fmac_f32_e32 v173, v17, v17
	v_fmac_f32_e32 v173, v18, v18
	v_fmac_f32_e32 v173, v19, v19
	v_mul_f32_e32 v234, v28, v28
	v_fmac_f32_e32 v234, v29, v29
	v_fmac_f32_e32 v234, v30, v30
	v_fmac_f32_e32 v234, v31, v31
	v_fmac_f32_e32 v234, v20, v20
	v_fmac_f32_e32 v234, v21, v21
	v_fmac_f32_e32 v234, v22, v22
	v_fmac_f32_e32 v234, v23, v23
	s_nop 1
	v_mov_b32_dpp v241, v173 row_ror:8 row_mask:0xf bank_mask:0xf
	v_mov_b32_dpp v242, v234 row_ror:8 row_mask:0xf bank_mask:0xf
	v_add_f32_e32 v173, v173, v241
	v_add_f32_e32 v234, v234, v242
	v_cndmask_b32_e64 v173, v234, v173, s[34:35]
	s_nop 0
	ds_bpermute_b32 v241, v235, v173
	s_waitcnt lgkmcnt(0)
	v_add_f32_e32 v173, v173, v241
	s_nop 0
	ds_bpermute_b32 v242, v240, v173
	s_waitcnt lgkmcnt(0)
;     __device__ __forceinline__ void operator()(const f32x4 (&acc)[2][2][4][2], const Unit& u, int wr, int wc, int fr, int fq) const {
;     ...
;         for (int ai = 0; ai < 2; ++ai)
; #pragma unroll
;             for (int m = 0; m < 4; ++m) {
;                 const int row = row0 + ai * HALF + m * 16;
;                 const size_t off = (size_t)row * ldc + col0;
;                 float q = 0.f;
; #pragma unroll
;                 for (int bj = 0; bj < 2; ++bj)
; #pragma unroll
;                     for (int n = 0; n < 2; ++n) {
;                         const f32x4 rv = *(const f32x4*)(rbase + off + bj * HALF + n * 16);
;                         const f32x4 v = rv + acc[ai][bj][m][n] * scale;
;                         if (out) *(f32x4*)(out + off + bj * HALF + n * 16) = v;
;                         if (xn) { q += (v.x * v.x + v.y * v.y) + (v.z * v.z + v.w * v.w); const f32x4 o = v * wv[bj][n];
;                             u32x2 p; p.x = pk2(o.x, o.y); p.y = pk2(o.z, o.w); *(u32x2*)(xn + off + bj * HALF + n * 16) = p; }
;                     }
;                 if (xn) { q += __shfl_xor(q, 16); q += __shfl_xor(q, 32); if (fq == 0) (void)__hip_atomic_fetch_add(ss + row, q, __ATOMIC_RELAXED, __HIP_MEMORY_SCOPE_AGENT); }
	v_add_f32_e32 v173, v173, v242
	s_mov_b64 exec, s[0:1]
	global_atomic_add_f32 v[206:207], v173, off
	s_mov_b64 exec, -1
	s_mov_b64 vcc, 64
	v_lshl_add_u64 v[206:207], v[206:207], 0, vcc
	v_mov_b32_dpp v236, v8 row_ror:8 row_mask:0xf bank_mask:0xf
	v_mov_b32_dpp v237, v9 row_ror:8 row_mask:0xf bank_mask:0xf
	v_mov_b32_dpp v238, v10 row_ror:8 row_mask:0xf bank_mask:0xf
	v_mov_b32_dpp v239, v11 row_ror:8 row_mask:0xf bank_mask:0xf
	v_cndmask_b32_e64 v8, v236, v12, s[34:35]
	v_cndmask_b32_e64 v9, v237, v13, s[34:35]
	v_cndmask_b32_e64 v10, v238, v14, s[34:35]
	v_cndmask_b32_e64 v11, v239, v15, s[34:35]
	v_cndmask_b32_e64 v12, v12, v236, s[34:35]
	v_cndmask_b32_e64 v13, v13, v237, s[34:35]
	v_cndmask_b32_e64 v14, v14, v238, s[34:35]
	v_cndmask_b32_e64 v15, v15, v239, s[34:35]
	v_mov_b32_dpp v236, v0 row_ror:8 row_mask:0xf bank_mask:0xf
	v_mov_b32_dpp v237, v1 row_ror:8 row_mask:0xf bank_mask:0xf
	v_mov_b32_dpp v238, v2 row_ror:8 row_mask:0xf bank_mask:0xf
	v_mov_b32_dpp v239, v3 row_ror:8 row_mask:0xf bank_mask:0xf
	v_cndmask_b32_e64 v0, v236, v4, s[34:35]
	v_cndmask_b32_e64 v1, v237, v5, s[34:35]
	v_cndmask_b32_e64 v2, v238, v6, s[34:35]
	v_cndmask_b32_e64 v3, v239, v7, s[34:35]
	v_cndmask_b32_e64 v4, v4, v236, s[34:35]
	v_cndmask_b32_e64 v5, v5, v237, s[34:35]
	v_cndmask_b32_e64 v6, v6, v238, s[34:35]
	v_cndmask_b32_e64 v7, v7, v239, s[34:35]
	s_waitcnt vmcnt(2)
	v_pk_add_f32 v[10:11], v[10:11], v[186:187]
	v_pk_add_f32 v[8:9], v[8:9], v[184:185]
	v_pk_add_f32 v[2:3], v[2:3], v[190:191]
	v_pk_add_f32 v[0:1], v[0:1], v[188:189]
	v_pk_add_f32 v[14:15], v[14:15], v[194:195]
	v_pk_add_f32 v[12:13], v[12:13], v[192:193]
	v_pk_add_f32 v[6:7], v[6:7], v[198:199]
	v_pk_add_f32 v[4:5], v[4:5], v[196:197]
	v_mul_f32_e32 v173, v8, v8
	v_fmac_f32_e32 v173, v9, v9
	v_fmac_f32_e32 v173, v10, v10
	v_fmac_f32_e32 v173, v11, v11
	v_fmac_f32_e32 v173, v0, v0
	v_fmac_f32_e32 v173, v1, v1
	v_fmac_f32_e32 v173, v2, v2
	v_fmac_f32_e32 v173, v3, v3
	v_mul_f32_e32 v234, v12, v12
	v_fmac_f32_e32 v234, v13, v13
	v_fmac_f32_e32 v234, v14, v14
	v_fmac_f32_e32 v234, v15, v15
	v_fmac_f32_e32 v234, v4, v4
	v_fmac_f32_e32 v234, v5, v5
	v_fmac_f32_e32 v234, v6, v6
	v_fmac_f32_e32 v234, v7, v7
	s_nop 1
	v_mov_b32_dpp v241, v173 row_ror:8 row_mask:0xf bank_mask:0xf
	v_mov_b32_dpp v242, v234 row_ror:8 row_mask:0xf bank_mask:0xf
	v_add_f32_e32 v173, v173, v241
	v_add_f32_e32 v234, v234, v242
	v_cndmask_b32_e64 v173, v234, v173, s[34:35]
	s_nop 0
	ds_bpermute_b32 v241, v235, v173
	s_waitcnt lgkmcnt(0)
	v_add_f32_e32 v173, v173, v241
	s_nop 0
	ds_bpermute_b32 v242, v240, v173
	s_waitcnt lgkmcnt(0)
	v_add_f32_e32 v173, v173, v242
	s_mov_b64 exec, s[0:1]
	global_atomic_add_f32 v[206:207], v173, off
	s_mov_b64 exec, -1
	global_store_dwordx4 v[218:219], v[136:139], off
	v_pk_mul_f32 v[224:225], v[64:65], v[136:137]
	v_pk_mul_f32 v[226:227], v[66:67], v[138:139]
	v_add_u32_e32 v224, 0x8000, v224
	v_add_u32_e32 v225, 0x8000, v225
	v_add_u32_e32 v226, 0x8000, v226
	v_add_u32_e32 v227, 0x8000, v227
	v_perm_b32 v222, v225, v224, s58
	v_perm_b32 v223, v227, v226, s58
	global_store_dwordx2 v[202:203], v[222:223], off
	global_store_dwordx4 v[218:219], v[128:131], off offset:512
	v_pk_mul_f32 v[228:229], v[72:73], v[128:129]
	v_pk_mul_f32 v[230:231], v[74:75], v[130:131]
	v_add_u32_e32 v228, 0x8000, v228
	v_add_u32_e32 v229, 0x8000, v229
	v_add_u32_e32 v230, 0x8000, v230
	v_add_u32_e32 v231, 0x8000, v231
	v_perm_b32 v232, v229, v228, s58
	v_perm_b32 v233, v231, v230, s58
	global_store_dwordx2 v[202:203], v[232:233], off offset:256
	global_store_dwordx4 v[220:221], v[140:143], off
	v_pk_mul_f32 v[224:225], v[76:77], v[140:141]
	v_pk_mul_f32 v[226:227], v[78:79], v[142:143]
	v_add_u32_e32 v224, 0x8000, v224
	v_add_u32_e32 v225, 0x8000, v225
	v_add_u32_e32 v226, 0x8000, v226
	v_add_u32_e32 v227, 0x8000, v227
	v_perm_b32 v222, v225, v224, s58
	v_perm_b32 v223, v227, v226, s58
	global_store_dwordx2 v[204:205], v[222:223], off
	global_store_dwordx4 v[220:221], v[132:135], off offset:512
	v_pk_mul_f32 v[228:229], v[84:85], v[132:133]
	v_pk_mul_f32 v[230:231], v[86:87], v[134:135]
	v_add_u32_e32 v228, 0x8000, v228
	v_add_u32_e32 v229, 0x8000, v229
	v_add_u32_e32 v230, 0x8000, v230
	v_add_u32_e32 v231, 0x8000, v231
	v_perm_b32 v232, v229, v228, s58
	v_perm_b32 v233, v231, v230, s58
	global_store_dwordx2 v[204:205], v[232:233], off offset:256
	s_mov_b64 vcc, 0x20000
	v_lshl_add_u64 v[218:219], v[218:219], 0, vcc
	v_lshl_add_u64 v[220:221], v[220:221], 0, vcc
	s_mov_b64 vcc, 0x10000
	v_lshl_add_u64 v[202:203], v[202:203], 0, vcc
	v_lshl_add_u64 v[204:205], v[204:205], 0, vcc
	global_store_dwordx4 v[218:219], v[120:123], off
	v_pk_mul_f32 v[224:225], v[64:65], v[120:121]
	v_pk_mul_f32 v[226:227], v[66:67], v[122:123]
	v_add_u32_e32 v224, 0x8000, v224
	v_add_u32_e32 v225, 0x8000, v225
	v_add_u32_e32 v226, 0x8000, v226
	v_add_u32_e32 v227, 0x8000, v227
	v_perm_b32 v222, v225, v224, s58
	v_perm_b32 v223, v227, v226, s58
	global_store_dwordx2 v[202:203], v[222:223], off
	global_store_dwordx4 v[218:219], v[112:115], off offset:512
	v_pk_mul_f32 v[228:229], v[72:73], v[112:113]
	v_pk_mul_f32 v[230:231], v[74:75], v[114:115]
	v_add_u32_e32 v228, 0x8000, v228
	v_add_u32_e32 v229, 0x8000, v229
	v_add_u32_e32 v230, 0x8000, v230
	v_add_u32_e32 v231, 0x8000, v231
	v_perm_b32 v232, v229, v228, s58
	v_perm_b32 v233, v231, v230, s58
	global_store_dwordx2 v[202:203], v[232:233], off offset:256
	global_store_dwordx4 v[220:221], v[124:127], off
	v_pk_mul_f32 v[224:225], v[76:77], v[124:125]
	v_pk_mul_f32 v[226:227], v[78:79], v[126:127]
	v_add_u32_e32 v224, 0x8000, v224
	v_add_u32_e32 v225, 0x8000, v225
;     __device__ __forceinline__ void operator()(const f32x4 (&acc)[2][2][4][2], const Unit& u, int wr, int wc, int fr, int fq) const {
;     ...
;                         const f32x4 rv = *(const f32x4*)(rbase + off + bj * HALF + n * 16);
;                         const f32x4 v = rv + acc[ai][bj][m][n] * scale;
;                         if (out) *(f32x4*)(out + off + bj * HALF + n * 16) = v;
;                         if (xn) { q += (v.x * v.x + v.y * v.y) + (v.z * v.z + v.w * v.w); const f32x4 o = v * wv[bj][n];
;                             u32x2 p; p.x = pk2(o.x, o.y); p.y = pk2(o.z, o.w); *(u32x2*)(xn + off + bj * HALF + n * 16) = p; }
	v_add_u32_e32 v226, 0x8000, v226
	v_add_u32_e32 v227, 0x8000, v227
	v_perm_b32 v222, v225, v224, s58
	v_perm_b32 v223, v227, v226, s58
	global_store_dwordx2 v[204:205], v[222:223], off
	global_store_dwordx4 v[220:221], v[116:119], off offset:512
	v_pk_mul_f32 v[228:229], v[84:85], v[116:117]
	v_pk_mul_f32 v[230:231], v[86:87], v[118:119]
	v_add_u32_e32 v228, 0x8000, v228
	v_add_u32_e32 v229, 0x8000, v229
	v_add_u32_e32 v230, 0x8000, v230
	v_add_u32_e32 v231, 0x8000, v231
	v_perm_b32 v232, v229, v228, s58
	v_perm_b32 v233, v231, v230, s58
	global_store_dwordx2 v[204:205], v[232:233], off offset:256
	s_mov_b64 vcc, 0x20000
	v_lshl_add_u64 v[218:219], v[218:219], 0, vcc
	v_lshl_add_u64 v[220:221], v[220:221], 0, vcc
	s_mov_b64 vcc, 0x10000
	v_lshl_add_u64 v[202:203], v[202:203], 0, vcc
	v_lshl_add_u64 v[204:205], v[204:205], 0, vcc
	global_store_dwordx4 v[218:219], v[104:107], off
	v_pk_mul_f32 v[224:225], v[64:65], v[104:105]
	v_pk_mul_f32 v[226:227], v[66:67], v[106:107]
	v_add_u32_e32 v224, 0x8000, v224
	v_add_u32_e32 v225, 0x8000, v225
	v_add_u32_e32 v226, 0x8000, v226
	v_add_u32_e32 v227, 0x8000, v227
	v_perm_b32 v222, v225, v224, s58
	v_perm_b32 v223, v227, v226, s58
	global_store_dwordx2 v[202:203], v[222:223], off
	global_store_dwordx4 v[218:219], v[96:99], off offset:512
	v_pk_mul_f32 v[228:229], v[72:73], v[96:97]
	v_pk_mul_f32 v[230:231], v[74:75], v[98:99]
	v_add_u32_e32 v228, 0x8000, v228
	v_add_u32_e32 v229, 0x8000, v229
	v_add_u32_e32 v230, 0x8000, v230
	v_add_u32_e32 v231, 0x8000, v231
	v_perm_b32 v232, v229, v228, s58
	v_perm_b32 v233, v231, v230, s58
	global_store_dwordx2 v[202:203], v[232:233], off offset:256
	global_store_dwordx4 v[220:221], v[108:111], off
	v_pk_mul_f32 v[224:225], v[76:77], v[108:109]
	v_pk_mul_f32 v[226:227], v[78:79], v[110:111]
	v_add_u32_e32 v224, 0x8000, v224
	v_add_u32_e32 v225, 0x8000, v225
	v_add_u32_e32 v226, 0x8000, v226
	v_add_u32_e32 v227, 0x8000, v227
	v_perm_b32 v222, v225, v224, s58
	v_perm_b32 v223, v227, v226, s58
	global_store_dwordx2 v[204:205], v[222:223], off
	global_store_dwordx4 v[220:221], v[100:103], off offset:512
	v_pk_mul_f32 v[228:229], v[84:85], v[100:101]
	v_pk_mul_f32 v[230:231], v[86:87], v[102:103]
	v_add_u32_e32 v228, 0x8000, v228
	v_add_u32_e32 v229, 0x8000, v229
	v_add_u32_e32 v230, 0x8000, v230
	v_add_u32_e32 v231, 0x8000, v231
	v_perm_b32 v232, v229, v228, s58
	v_perm_b32 v233, v231, v230, s58
	global_store_dwordx2 v[204:205], v[232:233], off offset:256
	s_mov_b64 vcc, 0x20000
	v_lshl_add_u64 v[218:219], v[218:219], 0, vcc
	v_lshl_add_u64 v[220:221], v[220:221], 0, vcc
	s_mov_b64 vcc, 0x10000
	v_lshl_add_u64 v[202:203], v[202:203], 0, vcc
	v_lshl_add_u64 v[204:205], v[204:205], 0, vcc
	global_store_dwordx4 v[218:219], v[88:91], off
	v_pk_mul_f32 v[224:225], v[64:65], v[88:89]
	v_pk_mul_f32 v[226:227], v[66:67], v[90:91]
	v_add_u32_e32 v224, 0x8000, v224
	v_add_u32_e32 v225, 0x8000, v225
	v_add_u32_e32 v226, 0x8000, v226
	v_add_u32_e32 v227, 0x8000, v227
	v_perm_b32 v222, v225, v224, s58
	v_perm_b32 v223, v227, v226, s58
	global_store_dwordx2 v[202:203], v[222:223], off
	global_store_dwordx4 v[218:219], v[68:71], off offset:512
	v_pk_mul_f32 v[228:229], v[72:73], v[68:69]
	v_pk_mul_f32 v[230:231], v[74:75], v[70:71]
	v_add_u32_e32 v228, 0x8000, v228
	v_add_u32_e32 v229, 0x8000, v229
	v_add_u32_e32 v230, 0x8000, v230
	v_add_u32_e32 v231, 0x8000, v231
	v_perm_b32 v232, v229, v228, s58
	v_perm_b32 v233, v231, v230, s58
	global_store_dwordx2 v[202:203], v[232:233], off offset:256
	global_store_dwordx4 v[220:221], v[92:95], off
	v_pk_mul_f32 v[224:225], v[76:77], v[92:93]
	v_pk_mul_f32 v[226:227], v[78:79], v[94:95]
	v_add_u32_e32 v224, 0x8000, v224
	v_add_u32_e32 v225, 0x8000, v225
	v_add_u32_e32 v226, 0x8000, v226
	v_add_u32_e32 v227, 0x8000, v227
	v_perm_b32 v222, v225, v224, s58
	v_perm_b32 v223, v227, v226, s58
	global_store_dwordx2 v[204:205], v[222:223], off
	global_store_dwordx4 v[220:221], v[80:83], off offset:512
	v_pk_mul_f32 v[228:229], v[84:85], v[80:81]
	v_pk_mul_f32 v[230:231], v[86:87], v[82:83]
	v_add_u32_e32 v228, 0x8000, v228
	v_add_u32_e32 v229, 0x8000, v229
	v_add_u32_e32 v230, 0x8000, v230
	v_add_u32_e32 v231, 0x8000, v231
	v_perm_b32 v232, v229, v228, s58
	v_perm_b32 v233, v231, v230, s58
	global_store_dwordx2 v[204:205], v[232:233], off offset:256
	s_mov_b64 vcc, 0xa0000
	v_lshl_add_u64 v[218:219], v[218:219], 0, vcc
	v_lshl_add_u64 v[220:221], v[220:221], 0, vcc
	s_mov_b64 vcc, 0x50000
	v_lshl_add_u64 v[202:203], v[202:203], 0, vcc
	v_lshl_add_u64 v[204:205], v[204:205], 0, vcc
	global_store_dwordx4 v[218:219], v[56:59], off
	v_pk_mul_f32 v[224:225], v[64:65], v[56:57]
	v_pk_mul_f32 v[226:227], v[66:67], v[58:59]
	v_add_u32_e32 v224, 0x8000, v224
	v_add_u32_e32 v225, 0x8000, v225
	v_add_u32_e32 v226, 0x8000, v226
	v_add_u32_e32 v227, 0x8000, v227
	v_perm_b32 v222, v225, v224, s58
	v_perm_b32 v223, v227, v226, s58
	global_store_dwordx2 v[202:203], v[222:223], off
	global_store_dwordx4 v[218:219], v[48:51], off offset:512
	v_pk_mul_f32 v[228:229], v[72:73], v[48:49]
	v_pk_mul_f32 v[230:231], v[74:75], v[50:51]
	v_add_u32_e32 v228, 0x8000, v228
	v_add_u32_e32 v229, 0x8000, v229
	v_add_u32_e32 v230, 0x8000, v230
	v_add_u32_e32 v231, 0x8000, v231
	v_perm_b32 v232, v229, v228, s58
	v_perm_b32 v233, v231, v230, s58
	global_store_dwordx2 v[202:203], v[232:233], off offset:256
	global_store_dwordx4 v[220:221], v[60:63], off
	v_pk_mul_f32 v[224:225], v[76:77], v[60:61]
	v_pk_mul_f32 v[226:227], v[78:79], v[62:63]
	v_add_u32_e32 v224, 0x8000, v224
	v_add_u32_e32 v225, 0x8000, v225
	v_add_u32_e32 v226, 0x8000, v226
	v_add_u32_e32 v227, 0x8000, v227
; #define PG8_BAR __builtin_amdgcn_s_barrier()
;     __device__ __forceinline__ void operator()(const f32x4 (&acc)[2][2][4][2], const Unit& u, int wr, int wc, int fr, int fq) const {
;     ...
;                         const f32x4 rv = *(const f32x4*)(rbase + off + bj * HALF + n * 16);
;                         const f32x4 v = rv + acc[ai][bj][m][n] * scale;
;                         if (out) *(f32x4*)(out + off + bj * HALF + n * 16) = v;
;                         if (xn) { q += (v.x * v.x + v.y * v.y) + (v.z * v.z + v.w * v.w); const f32x4 o = v * wv[bj][n];
;                             u32x2 p; p.x = pk2(o.x, o.y); p.y = pk2(o.z, o.w); *(u32x2*)(xn + off + bj * HALF + n * 16) = p; }
; template <class Epi, bool ALIGN_EPI>
; __device__ __forceinline__ void gemm_phase(LAS unsigned char* lds, const Gemm g, const StaticOrder& S, const Epi& E) {
;     ...
; #pragma unroll
;         for (int a = 0; a < 2; ++a)
; #pragma unroll
;             for (int b = 0; b < 2; ++b)
; #pragma unroll
;                 for (int m = 0; m < 4; ++m)
; #pragma unroll
;                     for (int n = 0; n < 2; ++n) acc[a][b][m][n] = (f32x4){0.f, 0.f, 0.f, 0.f};
;         cur = nxt; cA = nA; cB = nB; ++ui;
;         if constexpr (ALIGN_EPI) { if (wr == 1) PG8_BAR; }
	v_perm_b32 v222, v225, v224, s58
	v_perm_b32 v223, v227, v226, s58
	global_store_dwordx2 v[204:205], v[222:223], off
	global_store_dwordx4 v[220:221], v[52:55], off offset:512
	v_pk_mul_f32 v[228:229], v[84:85], v[52:53]
	v_pk_mul_f32 v[230:231], v[86:87], v[54:55]
	v_add_u32_e32 v228, 0x8000, v228
	v_add_u32_e32 v229, 0x8000, v229
	v_add_u32_e32 v230, 0x8000, v230
	v_add_u32_e32 v231, 0x8000, v231
	v_perm_b32 v232, v229, v228, s58
	v_perm_b32 v233, v231, v230, s58
	global_store_dwordx2 v[204:205], v[232:233], off offset:256
	s_mov_b64 vcc, 0x20000
	v_lshl_add_u64 v[218:219], v[218:219], 0, vcc
	v_lshl_add_u64 v[220:221], v[220:221], 0, vcc
	s_mov_b64 vcc, 0x10000
	v_lshl_add_u64 v[202:203], v[202:203], 0, vcc
	v_lshl_add_u64 v[204:205], v[204:205], 0, vcc
	global_store_dwordx4 v[218:219], v[40:43], off
	v_pk_mul_f32 v[224:225], v[64:65], v[40:41]
	v_pk_mul_f32 v[226:227], v[66:67], v[42:43]
	v_add_u32_e32 v224, 0x8000, v224
	v_add_u32_e32 v225, 0x8000, v225
	v_add_u32_e32 v226, 0x8000, v226
	v_add_u32_e32 v227, 0x8000, v227
	v_perm_b32 v222, v225, v224, s58
	v_perm_b32 v223, v227, v226, s58
	global_store_dwordx2 v[202:203], v[222:223], off
	global_store_dwordx4 v[218:219], v[32:35], off offset:512
	v_pk_mul_f32 v[228:229], v[72:73], v[32:33]
	v_pk_mul_f32 v[230:231], v[74:75], v[34:35]
	v_add_u32_e32 v228, 0x8000, v228
	v_add_u32_e32 v229, 0x8000, v229
	v_add_u32_e32 v230, 0x8000, v230
	v_add_u32_e32 v231, 0x8000, v231
	v_perm_b32 v232, v229, v228, s58
	v_perm_b32 v233, v231, v230, s58
	global_store_dwordx2 v[202:203], v[232:233], off offset:256
	global_store_dwordx4 v[220:221], v[44:47], off
	v_pk_mul_f32 v[224:225], v[76:77], v[44:45]
	v_pk_mul_f32 v[226:227], v[78:79], v[46:47]
	v_add_u32_e32 v224, 0x8000, v224
	v_add_u32_e32 v225, 0x8000, v225
	v_add_u32_e32 v226, 0x8000, v226
	v_add_u32_e32 v227, 0x8000, v227
	v_perm_b32 v222, v225, v224, s58
	v_perm_b32 v223, v227, v226, s58
	global_store_dwordx2 v[204:205], v[222:223], off
	global_store_dwordx4 v[220:221], v[36:39], off offset:512
	v_pk_mul_f32 v[228:229], v[84:85], v[36:37]
	v_pk_mul_f32 v[230:231], v[86:87], v[38:39]
	v_add_u32_e32 v228, 0x8000, v228
	v_add_u32_e32 v229, 0x8000, v229
	v_add_u32_e32 v230, 0x8000, v230
	v_add_u32_e32 v231, 0x8000, v231
	v_perm_b32 v232, v229, v228, s58
	v_perm_b32 v233, v231, v230, s58
	global_store_dwordx2 v[204:205], v[232:233], off offset:256
	s_mov_b64 vcc, 0x20000
	v_lshl_add_u64 v[218:219], v[218:219], 0, vcc
	v_lshl_add_u64 v[220:221], v[220:221], 0, vcc
	s_mov_b64 vcc, 0x10000
	v_lshl_add_u64 v[202:203], v[202:203], 0, vcc
	v_lshl_add_u64 v[204:205], v[204:205], 0, vcc
	global_store_dwordx4 v[218:219], v[24:27], off
	v_pk_mul_f32 v[224:225], v[64:65], v[24:25]
	v_pk_mul_f32 v[226:227], v[66:67], v[26:27]
	v_add_u32_e32 v224, 0x8000, v224
	v_add_u32_e32 v225, 0x8000, v225
	v_add_u32_e32 v226, 0x8000, v226
	v_add_u32_e32 v227, 0x8000, v227
	v_perm_b32 v222, v225, v224, s58
	v_perm_b32 v223, v227, v226, s58
	global_store_dwordx2 v[202:203], v[222:223], off
	global_store_dwordx4 v[218:219], v[16:19], off offset:512
	v_pk_mul_f32 v[228:229], v[72:73], v[16:17]
	v_pk_mul_f32 v[230:231], v[74:75], v[18:19]
	v_add_u32_e32 v228, 0x8000, v228
	v_add_u32_e32 v229, 0x8000, v229
	v_add_u32_e32 v230, 0x8000, v230
	v_add_u32_e32 v231, 0x8000, v231
	v_perm_b32 v232, v229, v228, s58
	v_perm_b32 v233, v231, v230, s58
	global_store_dwordx2 v[202:203], v[232:233], off offset:256
	global_store_dwordx4 v[220:221], v[28:31], off
	v_pk_mul_f32 v[224:225], v[76:77], v[28:29]
	v_pk_mul_f32 v[226:227], v[78:79], v[30:31]
	v_add_u32_e32 v224, 0x8000, v224
	v_add_u32_e32 v225, 0x8000, v225
	v_add_u32_e32 v226, 0x8000, v226
	v_add_u32_e32 v227, 0x8000, v227
	v_perm_b32 v222, v225, v224, s58
	v_perm_b32 v223, v227, v226, s58
	global_store_dwordx2 v[204:205], v[222:223], off
	global_store_dwordx4 v[220:221], v[20:23], off offset:512
	v_pk_mul_f32 v[228:229], v[84:85], v[20:21]
	v_pk_mul_f32 v[230:231], v[86:87], v[22:23]
	v_add_u32_e32 v228, 0x8000, v228
	v_add_u32_e32 v229, 0x8000, v229
	v_add_u32_e32 v230, 0x8000, v230
	v_add_u32_e32 v231, 0x8000, v231
	v_perm_b32 v232, v229, v228, s58
	v_perm_b32 v233, v231, v230, s58
	global_store_dwordx2 v[204:205], v[232:233], off offset:256
	s_mov_b64 vcc, 0x20000
	v_lshl_add_u64 v[218:219], v[218:219], 0, vcc
	v_lshl_add_u64 v[220:221], v[220:221], 0, vcc
	s_mov_b64 vcc, 0x10000
	v_lshl_add_u64 v[202:203], v[202:203], 0, vcc
	v_lshl_add_u64 v[204:205], v[204:205], 0, vcc
	global_store_dwordx4 v[218:219], v[8:11], off
	v_pk_mul_f32 v[224:225], v[64:65], v[8:9]
	v_pk_mul_f32 v[226:227], v[66:67], v[10:11]
	v_add_u32_e32 v224, 0x8000, v224
	v_add_u32_e32 v225, 0x8000, v225
	v_add_u32_e32 v226, 0x8000, v226
	v_add_u32_e32 v227, 0x8000, v227
	v_perm_b32 v222, v225, v224, s58
	v_perm_b32 v223, v227, v226, s58
	global_store_dwordx2 v[202:203], v[222:223], off
	global_store_dwordx4 v[218:219], v[0:3], off offset:512
	v_pk_mul_f32 v[228:229], v[72:73], v[0:1]
	v_pk_mul_f32 v[230:231], v[74:75], v[2:3]
	v_add_u32_e32 v228, 0x8000, v228
	v_add_u32_e32 v229, 0x8000, v229
	v_add_u32_e32 v230, 0x8000, v230
	v_add_u32_e32 v231, 0x8000, v231
	v_perm_b32 v232, v229, v228, s58
	v_perm_b32 v233, v231, v230, s58
	global_store_dwordx2 v[202:203], v[232:233], off offset:256
	global_store_dwordx4 v[220:221], v[12:15], off
	v_pk_mul_f32 v[224:225], v[76:77], v[12:13]
	v_pk_mul_f32 v[226:227], v[78:79], v[14:15]
	v_add_u32_e32 v224, 0x8000, v224
	v_add_u32_e32 v225, 0x8000, v225
	v_add_u32_e32 v226, 0x8000, v226
	v_add_u32_e32 v227, 0x8000, v227
	v_perm_b32 v222, v225, v224, s58
	v_perm_b32 v223, v227, v226, s58
	global_store_dwordx2 v[204:205], v[222:223], off
	global_store_dwordx4 v[220:221], v[4:7], off offset:512
	v_pk_mul_f32 v[228:229], v[84:85], v[4:5]
	v_pk_mul_f32 v[230:231], v[86:87], v[6:7]
	v_add_u32_e32 v228, 0x8000, v228
	v_add_u32_e32 v229, 0x8000, v229
	v_add_u32_e32 v230, 0x8000, v230
	v_add_u32_e32 v231, 0x8000, v231
	v_perm_b32 v232, v229, v228, s58
	v_perm_b32 v233, v231, v230, s58
	global_store_dwordx2 v[204:205], v[232:233], off offset:256
	s_andn2_b64 vcc, exec, s[6:7]
	s_mov_b64 s[4:5], -1
	s_cbranch_vccnz .LBB0_1078
	s_andn2_b64 vcc, exec, s[12:13]
	s_cbranch_vccnz .LBB0_1077
	s_barrier
	s_branch .LBB0_1077

;     __device__ __forceinline__ void operator()(const f32x4 (&acc)[2][2][4][2], const Unit& u, int wr, int wc, int fr, int fq) const {
;         const int row0 = u.pm * BM + wr * 64 + fr, col0 = u.pn * BM + wc * 32 + 4 * fq;
;         const float* rbase = (u.pm * BM < SEQ_P) ? resA : (resB - (size_t)SEQ_P * ldc);
;         f32x4 wv[2][2];
;         if (xn) {
; #pragma unroll
;             for (int bj = 0; bj < 2; ++bj)
; #pragma unroll
;                 for (int n = 0; n < 2; ++n) wv[bj][n] = *(const f32x4*)(wn + col0 + bj * HALF + n * 16);
;         }
; #pragma unroll
;         for (int ai = 0; ai < 2; ++ai)
; #pragma unroll
;             for (int m = 0; m < 4; ++m) {
;                 const int row = row0 + ai * HALF + m * 16;
;                 const size_t off = (size_t)row * ldc + col0;
;                 float q = 0.f;
; #pragma unroll
;                 for (int bj = 0; bj < 2; ++bj)
; #pragma unroll
;                     for (int n = 0; n < 2; ++n) {
;                         const f32x4 rv = *(const f32x4*)(rbase + off + bj * HALF + n * 16);
;                         const f32x4 v = rv + acc[ai][bj][m][n] * scale;
;                         if (out) *(f32x4*)(out + off + bj * HALF + n * 16) = v;
;                         if (xn) { q += (v.x * v.x + v.y * v.y) + (v.z * v.z + v.w * v.w); const f32x4 o = v * wv[bj][n];
;                             u32x2 p; p.x = pk2(o.x, o.y); p.y = pk2(o.z, o.w); *(u32x2*)(xn + off + bj * HALF + n * 16) = p; }
;                     }
;                 if (xn) { q += __shfl_xor(q, 16); q += __shfl_xor(q, 32); if (fq == 0) (void)__hip_atomic_fetch_add(ss + row, q, __ATOMIC_RELAXED, __HIP_MEMORY_SCOPE_AGENT); }
.LBB0_1382:
	v_lshl_add_u32 v210, s54, 8, v160
	v_lshl_or_b32 v212, s53, 8, v162
	v_and_b32_e32 v238, 8, v167
	v_mov_b32_e32 v211, 0
	v_cmp_eq_u32_e64 s[24:25], 0, v238
	v_lshlrev_b32_e32 v232, 1, v238
	v_add_u32_e32 v214, v212, v232
	v_sub_u32_e32 v233, 16, v232
	v_add_u32_e32 v233, v212, v233
	v_mov_b32_e32 v212, v214
	v_mov_b32_e32 v214, v233
	v_mov_b32_e32 v213, 0
	v_mov_b32_e32 v215, 0
	v_sub_u32_e32 v208, v210, v238
	v_mov_b32_e32 v209, 0
	v_lshlrev_b64 v[206:207], 11, v[208:209]
	v_add_u32_e32 v208, 8, v208
	v_lshlrev_b64 v[208:209], 11, v[208:209]
	v_lshl_add_u64 v[206:207], v[206:207], 0, v[212:213]
	v_lshl_add_u64 v[208:209], v[208:209], 0, v[214:215]
	v_lshl_add_u64 v[196:197], v[206:207], 2, s[8:9]
	v_lshl_add_u64 v[198:199], v[208:209], 2, s[8:9]
	v_lshl_add_u64 v[200:201], v[212:213], 2, s[10:11]
	v_lshl_add_u64 v[202:203], v[214:215], 2, s[10:11]
	global_load_dwordx4 v[72:75], v[200:201], off
	global_load_dwordx4 v[84:87], v[200:201], off offset:512
	global_load_dwordx4 v[88:91], v[202:203], off
	global_load_dwordx4 v[96:99], v[202:203], off offset:512
	global_load_dwordx4 v[156:159], v[196:197], off
	global_load_dwordx4 v[168:171], v[196:197], off offset:512
	global_load_dwordx4 v[172:175], v[198:199], off
	global_load_dwordx4 v[176:179], v[198:199], off offset:512
	s_mov_b64 vcc, 0x20000
	v_lshl_add_u64 v[196:197], v[196:197], 0, vcc
	v_lshl_add_u64 v[198:199], v[198:199], 0, vcc
	global_load_dwordx4 v[180:183], v[196:197], off
	global_load_dwordx4 v[184:187], v[196:197], off offset:512
	global_load_dwordx4 v[188:191], v[198:199], off
	global_load_dwordx4 v[192:195], v[198:199], off offset:512
	s_mov_b64 vcc, 0x20000
	v_lshl_add_u64 v[196:197], v[196:197], 0, vcc
	v_lshl_add_u64 v[198:199], v[198:199], 0, vcc
	v_lshl_add_u64 v[200:201], v[206:207], 1, s[14:15]
	v_lshl_add_u64 v[202:203], v[208:209], 1, s[14:15]
	v_lshl_add_u64 v[204:205], v[210:211], 2, s[16:17]
	v_xor_b32_e32 v234, 16, v167
	v_xor_b32_e32 v235, 32, v167
	v_lshlrev_b32_e32 v234, 2, v234
	v_lshlrev_b32_e32 v235, 2, v235
	v_mov_b32_dpp v228, v136 row_ror:8 row_mask:0xf bank_mask:0xf
	v_mov_b32_dpp v229, v137 row_ror:8 row_mask:0xf bank_mask:0xf
	v_mov_b32_dpp v230, v138 row_ror:8 row_mask:0xf bank_mask:0xf
	v_mov_b32_dpp v231, v139 row_ror:8 row_mask:0xf bank_mask:0xf
	v_cndmask_b32_e64 v136, v228, v140, s[24:25]
	v_cndmask_b32_e64 v137, v229, v141, s[24:25]
	v_cndmask_b32_e64 v138, v230, v142, s[24:25]
	v_cndmask_b32_e64 v139, v231, v143, s[24:25]
	v_cndmask_b32_e64 v140, v140, v228, s[24:25]
	v_cndmask_b32_e64 v141, v141, v229, s[24:25]
	v_cndmask_b32_e64 v142, v142, v230, s[24:25]
	v_cndmask_b32_e64 v143, v143, v231, s[24:25]
	v_mov_b32_dpp v228, v128 row_ror:8 row_mask:0xf bank_mask:0xf
	v_mov_b32_dpp v229, v129 row_ror:8 row_mask:0xf bank_mask:0xf
	v_mov_b32_dpp v230, v130 row_ror:8 row_mask:0xf bank_mask:0xf
	v_mov_b32_dpp v231, v131 row_ror:8 row_mask:0xf bank_mask:0xf
	v_cndmask_b32_e64 v128, v228, v132, s[24:25]
	v_cndmask_b32_e64 v129, v229, v133, s[24:25]
	v_cndmask_b32_e64 v130, v230, v134, s[24:25]
	v_cndmask_b32_e64 v131, v231, v135, s[24:25]
	v_cndmask_b32_e64 v132, v132, v228, s[24:25]
	v_cndmask_b32_e64 v133, v133, v229, s[24:25]
	v_cndmask_b32_e64 v134, v134, v230, s[24:25]
	v_cndmask_b32_e64 v135, v135, v231, s[24:25]
	s_waitcnt vmcnt(4)
	v_pk_fma_f32 v[138:139], v[138:139], 0.5, v[158:159] op_sel_hi:[1,0,1]
	v_pk_fma_f32 v[136:137], v[136:137], 0.5, v[156:157] op_sel_hi:[1,0,1]
	v_pk_fma_f32 v[130:131], v[130:131], 0.5, v[170:171] op_sel_hi:[1,0,1]
	v_pk_fma_f32 v[128:129], v[128:129], 0.5, v[168:169] op_sel_hi:[1,0,1]
	v_pk_fma_f32 v[142:143], v[142:143], 0.5, v[174:175] op_sel_hi:[1,0,1]
	v_pk_fma_f32 v[140:141], v[140:141], 0.5, v[172:173] op_sel_hi:[1,0,1]
	v_pk_fma_f32 v[134:135], v[134:135], 0.5, v[178:179] op_sel_hi:[1,0,1]
	v_pk_fma_f32 v[132:133], v[132:133], 0.5, v[176:177] op_sel_hi:[1,0,1]
	global_load_dwordx4 v[156:159], v[196:197], off
	global_load_dwordx4 v[168:171], v[196:197], off offset:512
	global_load_dwordx4 v[172:175], v[198:199], off
	global_load_dwordx4 v[176:179], v[198:199], off offset:512
	s_mov_b64 vcc, 0x20000
	v_lshl_add_u64 v[196:197], v[196:197], 0, vcc
	v_lshl_add_u64 v[198:199], v[198:199], 0, vcc
	v_mul_f32_e32 v232, v136, v136
	v_fmac_f32_e32 v232, v137, v137
	v_fmac_f32_e32 v232, v138, v138
	v_fmac_f32_e32 v232, v139, v139
	v_fmac_f32_e32 v232, v128, v128
	v_fmac_f32_e32 v232, v129, v129
	v_fmac_f32_e32 v232, v130, v130
	v_fmac_f32_e32 v232, v131, v131
	v_mul_f32_e32 v233, v140, v140
	v_fmac_f32_e32 v233, v141, v141
	v_fmac_f32_e32 v233, v142, v142
	v_fmac_f32_e32 v233, v143, v143
	v_fmac_f32_e32 v233, v132, v132
	v_fmac_f32_e32 v233, v133, v133
	v_fmac_f32_e32 v233, v134, v134
	v_fmac_f32_e32 v233, v135, v135
	s_nop 1
	v_mov_b32_dpp v236, v232 row_ror:8 row_mask:0xf bank_mask:0xf
	v_mov_b32_dpp v237, v233 row_ror:8 row_mask:0xf bank_mask:0xf
	v_add_f32_e32 v232, v232, v236
	v_add_f32_e32 v233, v233, v237
	v_cndmask_b32_e64 v232, v233, v232, s[24:25]
	s_nop 0
	ds_bpermute_b32 v236, v234, v232
	s_waitcnt lgkmcnt(0)
	v_add_f32_e32 v232, v232, v236
	s_nop 0
	ds_bpermute_b32 v237, v235, v232
	s_waitcnt lgkmcnt(0)
;     __device__ __forceinline__ void operator()(const f32x4 (&acc)[2][2][4][2], const Unit& u, int wr, int wc, int fr, int fq) const {
;     ...
;         for (int ai = 0; ai < 2; ++ai)
; #pragma unroll
;             for (int m = 0; m < 4; ++m) {
;                 const int row = row0 + ai * HALF + m * 16;
;                 const size_t off = (size_t)row * ldc + col0;
;                 float q = 0.f;
; #pragma unroll
;                 for (int bj = 0; bj < 2; ++bj)
; #pragma unroll
;                     for (int n = 0; n < 2; ++n) {
;                         const f32x4 rv = *(const f32x4*)(rbase + off + bj * HALF + n * 16);
;                         const f32x4 v = rv + acc[ai][bj][m][n] * scale;
;                         if (out) *(f32x4*)(out + off + bj * HALF + n * 16) = v;
;                         if (xn) { q += (v.x * v.x + v.y * v.y) + (v.z * v.z + v.w * v.w); const f32x4 o = v * wv[bj][n];
;                             u32x2 p; p.x = pk2(o.x, o.y); p.y = pk2(o.z, o.w); *(u32x2*)(xn + off + bj * HALF + n * 16) = p; }
;                     }
;                 if (xn) { q += __shfl_xor(q, 16); q += __shfl_xor(q, 32); if (fq == 0) (void)__hip_atomic_fetch_add(ss + row, q, __ATOMIC_RELAXED, __HIP_MEMORY_SCOPE_AGENT); }
	v_add_f32_e32 v232, v232, v237
	s_mov_b64 exec, s[0:1]
	global_atomic_add_f32 v[204:205], v232, off
	s_mov_b64 exec, -1
	s_mov_b64 vcc, 64
	v_lshl_add_u64 v[204:205], v[204:205], 0, vcc
	v_mov_b32_dpp v228, v120 row_ror:8 row_mask:0xf bank_mask:0xf
	v_mov_b32_dpp v229, v121 row_ror:8 row_mask:0xf bank_mask:0xf
	v_mov_b32_dpp v230, v122 row_ror:8 row_mask:0xf bank_mask:0xf
	v_mov_b32_dpp v231, v123 row_ror:8 row_mask:0xf bank_mask:0xf
	v_cndmask_b32_e64 v120, v228, v124, s[24:25]
	v_cndmask_b32_e64 v121, v229, v125, s[24:25]
	v_cndmask_b32_e64 v122, v230, v126, s[24:25]
	v_cndmask_b32_e64 v123, v231, v127, s[24:25]
	v_cndmask_b32_e64 v124, v124, v228, s[24:25]
	v_cndmask_b32_e64 v125, v125, v229, s[24:25]
	v_cndmask_b32_e64 v126, v126, v230, s[24:25]
	v_cndmask_b32_e64 v127, v127, v231, s[24:25]
	v_mov_b32_dpp v228, v112 row_ror:8 row_mask:0xf bank_mask:0xf
	v_mov_b32_dpp v229, v113 row_ror:8 row_mask:0xf bank_mask:0xf
	v_mov_b32_dpp v230, v114 row_ror:8 row_mask:0xf bank_mask:0xf
	v_mov_b32_dpp v231, v115 row_ror:8 row_mask:0xf bank_mask:0xf
	v_cndmask_b32_e64 v112, v228, v116, s[24:25]
	v_cndmask_b32_e64 v113, v229, v117, s[24:25]
	v_cndmask_b32_e64 v114, v230, v118, s[24:25]
	v_cndmask_b32_e64 v115, v231, v119, s[24:25]
	v_cndmask_b32_e64 v116, v116, v228, s[24:25]
	v_cndmask_b32_e64 v117, v117, v229, s[24:25]
	v_cndmask_b32_e64 v118, v118, v230, s[24:25]
	v_cndmask_b32_e64 v119, v119, v231, s[24:25]
	s_waitcnt vmcnt(5)
	v_pk_fma_f32 v[122:123], v[122:123], 0.5, v[182:183] op_sel_hi:[1,0,1]
	v_pk_fma_f32 v[120:121], v[120:121], 0.5, v[180:181] op_sel_hi:[1,0,1]
	v_pk_fma_f32 v[114:115], v[114:115], 0.5, v[186:187] op_sel_hi:[1,0,1]
	v_pk_fma_f32 v[112:113], v[112:113], 0.5, v[184:185] op_sel_hi:[1,0,1]
	v_pk_fma_f32 v[126:127], v[126:127], 0.5, v[190:191] op_sel_hi:[1,0,1]
	v_pk_fma_f32 v[124:125], v[124:125], 0.5, v[188:189] op_sel_hi:[1,0,1]
	v_pk_fma_f32 v[118:119], v[118:119], 0.5, v[194:195] op_sel_hi:[1,0,1]
	v_pk_fma_f32 v[116:117], v[116:117], 0.5, v[192:193] op_sel_hi:[1,0,1]
	global_load_dwordx4 v[180:183], v[196:197], off
	global_load_dwordx4 v[184:187], v[196:197], off offset:512
	global_load_dwordx4 v[188:191], v[198:199], off
	global_load_dwordx4 v[192:195], v[198:199], off offset:512
	s_mov_b64 vcc, 0xa0000
	v_lshl_add_u64 v[196:197], v[196:197], 0, vcc
	v_lshl_add_u64 v[198:199], v[198:199], 0, vcc
	v_mul_f32_e32 v232, v120, v120
	v_fmac_f32_e32 v232, v121, v121
	v_fmac_f32_e32 v232, v122, v122
	v_fmac_f32_e32 v232, v123, v123
	v_fmac_f32_e32 v232, v112, v112
	v_fmac_f32_e32 v232, v113, v113
	v_fmac_f32_e32 v232, v114, v114
	v_fmac_f32_e32 v232, v115, v115
	v_mul_f32_e32 v233, v124, v124
	v_fmac_f32_e32 v233, v125, v125
	v_fmac_f32_e32 v233, v126, v126
	v_fmac_f32_e32 v233, v127, v127
	v_fmac_f32_e32 v233, v116, v116
	v_fmac_f32_e32 v233, v117, v117
	v_fmac_f32_e32 v233, v118, v118
	v_fmac_f32_e32 v233, v119, v119
	s_nop 1
	v_mov_b32_dpp v236, v232 row_ror:8 row_mask:0xf bank_mask:0xf
	v_mov_b32_dpp v237, v233 row_ror:8 row_mask:0xf bank_mask:0xf
	v_add_f32_e32 v232, v232, v236
	v_add_f32_e32 v233, v233, v237
	v_cndmask_b32_e64 v232, v233, v232, s[24:25]
	s_nop 0
	ds_bpermute_b32 v236, v234, v232
	s_waitcnt lgkmcnt(0)
	v_add_f32_e32 v232, v232, v236
	s_nop 0
	ds_bpermute_b32 v237, v235, v232
	s_waitcnt lgkmcnt(0)
	v_add_f32_e32 v232, v232, v237
	s_mov_b64 exec, s[0:1]
	global_atomic_add_f32 v[204:205], v232, off
	s_mov_b64 exec, -1
	s_mov_b64 vcc, 64
	v_lshl_add_u64 v[204:205], v[204:205], 0, vcc
	v_mov_b32_dpp v228, v104 row_ror:8 row_mask:0xf bank_mask:0xf
	v_mov_b32_dpp v229, v105 row_ror:8 row_mask:0xf bank_mask:0xf
	v_mov_b32_dpp v230, v106 row_ror:8 row_mask:0xf bank_mask:0xf
	v_mov_b32_dpp v231, v107 row_ror:8 row_mask:0xf bank_mask:0xf
	v_cndmask_b32_e64 v104, v228, v108, s[24:25]
	v_cndmask_b32_e64 v105, v229, v109, s[24:25]
	v_cndmask_b32_e64 v106, v230, v110, s[24:25]
	v_cndmask_b32_e64 v107, v231, v111, s[24:25]
	v_cndmask_b32_e64 v108, v108, v228, s[24:25]
	v_cndmask_b32_e64 v109, v109, v229, s[24:25]
	v_cndmask_b32_e64 v110, v110, v230, s[24:25]
	v_cndmask_b32_e64 v111, v111, v231, s[24:25]
	v_mov_b32_dpp v228, v92 row_ror:8 row_mask:0xf bank_mask:0xf
	v_mov_b32_dpp v229, v93 row_ror:8 row_mask:0xf bank_mask:0xf
	v_mov_b32_dpp v230, v94 row_ror:8 row_mask:0xf bank_mask:0xf
	v_mov_b32_dpp v231, v95 row_ror:8 row_mask:0xf bank_mask:0xf
	v_cndmask_b32_e64 v92, v228, v100, s[24:25]
	v_cndmask_b32_e64 v93, v229, v101, s[24:25]
	v_cndmask_b32_e64 v94, v230, v102, s[24:25]
	v_cndmask_b32_e64 v95, v231, v103, s[24:25]
	v_cndmask_b32_e64 v100, v100, v228, s[24:25]
	v_cndmask_b32_e64 v101, v101, v229, s[24:25]
	v_cndmask_b32_e64 v102, v102, v230, s[24:25]
	v_cndmask_b32_e64 v103, v103, v231, s[24:25]
	s_waitcnt vmcnt(6)
	v_pk_fma_f32 v[106:107], v[106:107], 0.5, v[158:159] op_sel_hi:[1,0,1]
	v_pk_fma_f32 v[104:105], v[104:105], 0.5, v[156:157] op_sel_hi:[1,0,1]
	v_pk_fma_f32 v[94:95], v[94:95], 0.5, v[170:171] op_sel_hi:[1,0,1]
	v_pk_fma_f32 v[92:93], v[92:93], 0.5, v[168:169] op_sel_hi:[1,0,1]
	v_pk_fma_f32 v[110:111], v[110:111], 0.5, v[174:175] op_sel_hi:[1,0,1]
	v_pk_fma_f32 v[108:109], v[108:109], 0.5, v[172:173] op_sel_hi:[1,0,1]
	v_pk_fma_f32 v[102:103], v[102:103], 0.5, v[178:179] op_sel_hi:[1,0,1]
	v_pk_fma_f32 v[100:101], v[100:101], 0.5, v[176:177] op_sel_hi:[1,0,1]
	global_load_dwordx4 v[156:159], v[196:197], off
	global_load_dwordx4 v[168:171], v[196:197], off offset:512
	global_load_dwordx4 v[172:175], v[198:199], off
	global_load_dwordx4 v[176:179], v[198:199], off offset:512
	s_mov_b64 vcc, 0x20000
	v_lshl_add_u64 v[196:197], v[196:197], 0, vcc
	v_lshl_add_u64 v[198:199], v[198:199], 0, vcc
	v_mul_f32_e32 v232, v104, v104
	v_fmac_f32_e32 v232, v105, v105
	v_fmac_f32_e32 v232, v106, v106
	v_fmac_f32_e32 v232, v107, v107
	v_fmac_f32_e32 v232, v92, v92
	v_fmac_f32_e32 v232, v93, v93
	v_fmac_f32_e32 v232, v94, v94
	v_fmac_f32_e32 v232, v95, v95
	v_mul_f32_e32 v233, v108, v108
	v_fmac_f32_e32 v233, v109, v109
	v_fmac_f32_e32 v233, v110, v110
	v_fmac_f32_e32 v233, v111, v111
	v_fmac_f32_e32 v233, v100, v100
	v_fmac_f32_e32 v233, v101, v101
	v_fmac_f32_e32 v233, v102, v102
	v_fmac_f32_e32 v233, v103, v103
	s_nop 1
	v_mov_b32_dpp v236, v232 row_ror:8 row_mask:0xf bank_mask:0xf
	v_mov_b32_dpp v237, v233 row_ror:8 row_mask:0xf bank_mask:0xf
	v_add_f32_e32 v232, v232, v236
	v_add_f32_e32 v233, v233, v237
	v_cndmask_b32_e64 v232, v233, v232, s[24:25]
	s_nop 0
	ds_bpermute_b32 v236, v234, v232
	s_waitcnt lgkmcnt(0)
;     __device__ __forceinline__ void operator()(const f32x4 (&acc)[2][2][4][2], const Unit& u, int wr, int wc, int fr, int fq) const {
;     ...
;         for (int ai = 0; ai < 2; ++ai)
; #pragma unroll
;             for (int m = 0; m < 4; ++m) {
;                 const int row = row0 + ai * HALF + m * 16;
;                 const size_t off = (size_t)row * ldc + col0;
;                 float q = 0.f;
; #pragma unroll
;                 for (int bj = 0; bj < 2; ++bj)
; #pragma unroll
;                     for (int n = 0; n < 2; ++n) {
;                         const f32x4 rv = *(const f32x4*)(rbase + off + bj * HALF + n * 16);
;                         const f32x4 v = rv + acc[ai][bj][m][n] * scale;
;                         if (out) *(f32x4*)(out + off + bj * HALF + n * 16) = v;
;                         if (xn) { q += (v.x * v.x + v.y * v.y) + (v.z * v.z + v.w * v.w); const f32x4 o = v * wv[bj][n];
;                             u32x2 p; p.x = pk2(o.x, o.y); p.y = pk2(o.z, o.w); *(u32x2*)(xn + off + bj * HALF + n * 16) = p; }
;                     }
;                 if (xn) { q += __shfl_xor(q, 16); q += __shfl_xor(q, 32); if (fq == 0) (void)__hip_atomic_fetch_add(ss + row, q, __ATOMIC_RELAXED, __HIP_MEMORY_SCOPE_AGENT); }
	v_add_f32_e32 v232, v232, v236
	s_nop 0
	ds_bpermute_b32 v237, v235, v232
	s_waitcnt lgkmcnt(0)
	v_add_f32_e32 v232, v232, v237
	s_mov_b64 exec, s[0:1]
	global_atomic_add_f32 v[204:205], v232, off
	s_mov_b64 exec, -1
	s_mov_b64 vcc, 64
	v_lshl_add_u64 v[204:205], v[204:205], 0, vcc
	v_mov_b32_dpp v228, v76 row_ror:8 row_mask:0xf bank_mask:0xf
	v_mov_b32_dpp v229, v77 row_ror:8 row_mask:0xf bank_mask:0xf
	v_mov_b32_dpp v230, v78 row_ror:8 row_mask:0xf bank_mask:0xf
	v_mov_b32_dpp v231, v79 row_ror:8 row_mask:0xf bank_mask:0xf
	v_cndmask_b32_e64 v76, v228, v80, s[24:25]
	v_cndmask_b32_e64 v77, v229, v81, s[24:25]
	v_cndmask_b32_e64 v78, v230, v82, s[24:25]
	v_cndmask_b32_e64 v79, v231, v83, s[24:25]
	v_cndmask_b32_e64 v80, v80, v228, s[24:25]
	v_cndmask_b32_e64 v81, v81, v229, s[24:25]
	v_cndmask_b32_e64 v82, v82, v230, s[24:25]
	v_cndmask_b32_e64 v83, v83, v231, s[24:25]
	v_mov_b32_dpp v228, v64 row_ror:8 row_mask:0xf bank_mask:0xf
	v_mov_b32_dpp v229, v65 row_ror:8 row_mask:0xf bank_mask:0xf
	v_mov_b32_dpp v230, v66 row_ror:8 row_mask:0xf bank_mask:0xf
	v_mov_b32_dpp v231, v67 row_ror:8 row_mask:0xf bank_mask:0xf
	v_cndmask_b32_e64 v64, v228, v68, s[24:25]
	v_cndmask_b32_e64 v65, v229, v69, s[24:25]
	v_cndmask_b32_e64 v66, v230, v70, s[24:25]
	v_cndmask_b32_e64 v67, v231, v71, s[24:25]
	v_cndmask_b32_e64 v68, v68, v228, s[24:25]
	v_cndmask_b32_e64 v69, v69, v229, s[24:25]
	v_cndmask_b32_e64 v70, v70, v230, s[24:25]
	v_cndmask_b32_e64 v71, v71, v231, s[24:25]
	s_waitcnt vmcnt(6)
	v_pk_fma_f32 v[78:79], v[78:79], 0.5, v[182:183] op_sel_hi:[1,0,1]
	v_pk_fma_f32 v[76:77], v[76:77], 0.5, v[180:181] op_sel_hi:[1,0,1]
	v_pk_fma_f32 v[66:67], v[66:67], 0.5, v[186:187] op_sel_hi:[1,0,1]
	v_pk_fma_f32 v[64:65], v[64:65], 0.5, v[184:185] op_sel_hi:[1,0,1]
	v_pk_fma_f32 v[82:83], v[82:83], 0.5, v[190:191] op_sel_hi:[1,0,1]
	v_pk_fma_f32 v[80:81], v[80:81], 0.5, v[188:189] op_sel_hi:[1,0,1]
	v_pk_fma_f32 v[70:71], v[70:71], 0.5, v[194:195] op_sel_hi:[1,0,1]
	v_pk_fma_f32 v[68:69], v[68:69], 0.5, v[192:193] op_sel_hi:[1,0,1]
	global_load_dwordx4 v[180:183], v[196:197], off
	global_load_dwordx4 v[184:187], v[196:197], off offset:512
	global_load_dwordx4 v[188:191], v[198:199], off
	global_load_dwordx4 v[192:195], v[198:199], off offset:512
	s_mov_b64 vcc, 0x20000
	v_lshl_add_u64 v[196:197], v[196:197], 0, vcc
	v_lshl_add_u64 v[198:199], v[198:199], 0, vcc
	v_mul_f32_e32 v232, v76, v76
	v_fmac_f32_e32 v232, v77, v77
	v_fmac_f32_e32 v232, v78, v78
	v_fmac_f32_e32 v232, v79, v79
	v_fmac_f32_e32 v232, v64, v64
	v_fmac_f32_e32 v232, v65, v65
	v_fmac_f32_e32 v232, v66, v66
	v_fmac_f32_e32 v232, v67, v67
	v_mul_f32_e32 v233, v80, v80
	v_fmac_f32_e32 v233, v81, v81
	v_fmac_f32_e32 v233, v82, v82
	v_fmac_f32_e32 v233, v83, v83
	v_fmac_f32_e32 v233, v68, v68
	v_fmac_f32_e32 v233, v69, v69
	v_fmac_f32_e32 v233, v70, v70
	v_fmac_f32_e32 v233, v71, v71
	s_nop 1
	v_mov_b32_dpp v236, v232 row_ror:8 row_mask:0xf bank_mask:0xf
	v_mov_b32_dpp v237, v233 row_ror:8 row_mask:0xf bank_mask:0xf
	v_add_f32_e32 v232, v232, v236
	v_add_f32_e32 v233, v233, v237
	v_cndmask_b32_e64 v232, v233, v232, s[24:25]
	s_nop 0
	ds_bpermute_b32 v236, v234, v232
	s_waitcnt lgkmcnt(0)
	v_add_f32_e32 v232, v232, v236
	s_nop 0
	ds_bpermute_b32 v237, v235, v232
	s_waitcnt lgkmcnt(0)
	v_add_f32_e32 v232, v232, v237
	s_mov_b64 exec, s[0:1]
	global_atomic_add_f32 v[204:205], v232, off
	s_mov_b64 exec, -1
	s_mov_b64 vcc, 320
	v_lshl_add_u64 v[204:205], v[204:205], 0, vcc
	v_mov_b32_dpp v228, v56 row_ror:8 row_mask:0xf bank_mask:0xf
	v_mov_b32_dpp v229, v57 row_ror:8 row_mask:0xf bank_mask:0xf
	v_mov_b32_dpp v230, v58 row_ror:8 row_mask:0xf bank_mask:0xf
	v_mov_b32_dpp v231, v59 row_ror:8 row_mask:0xf bank_mask:0xf
	v_cndmask_b32_e64 v56, v228, v60, s[24:25]
	v_cndmask_b32_e64 v57, v229, v61, s[24:25]
	v_cndmask_b32_e64 v58, v230, v62, s[24:25]
	v_cndmask_b32_e64 v59, v231, v63, s[24:25]
	v_cndmask_b32_e64 v60, v60, v228, s[24:25]
	v_cndmask_b32_e64 v61, v61, v229, s[24:25]
	v_cndmask_b32_e64 v62, v62, v230, s[24:25]
	v_cndmask_b32_e64 v63, v63, v231, s[24:25]
	v_mov_b32_dpp v228, v48 row_ror:8 row_mask:0xf bank_mask:0xf
	v_mov_b32_dpp v229, v49 row_ror:8 row_mask:0xf bank_mask:0xf
	v_mov_b32_dpp v230, v50 row_ror:8 row_mask:0xf bank_mask:0xf
	v_mov_b32_dpp v231, v51 row_ror:8 row_mask:0xf bank_mask:0xf
	v_cndmask_b32_e64 v48, v228, v52, s[24:25]
	v_cndmask_b32_e64 v49, v229, v53, s[24:25]
	v_cndmask_b32_e64 v50, v230, v54, s[24:25]
	v_cndmask_b32_e64 v51, v231, v55, s[24:25]
	v_cndmask_b32_e64 v52, v52, v228, s[24:25]
	v_cndmask_b32_e64 v53, v53, v229, s[24:25]
	v_cndmask_b32_e64 v54, v54, v230, s[24:25]
	v_cndmask_b32_e64 v55, v55, v231, s[24:25]
	s_waitcnt vmcnt(6)
	v_pk_fma_f32 v[58:59], v[58:59], 0.5, v[158:159] op_sel_hi:[1,0,1]
	v_pk_fma_f32 v[56:57], v[56:57], 0.5, v[156:157] op_sel_hi:[1,0,1]
	v_pk_fma_f32 v[50:51], v[50:51], 0.5, v[170:171] op_sel_hi:[1,0,1]
	v_pk_fma_f32 v[48:49], v[48:49], 0.5, v[168:169] op_sel_hi:[1,0,1]
	v_pk_fma_f32 v[62:63], v[62:63], 0.5, v[174:175] op_sel_hi:[1,0,1]
	v_pk_fma_f32 v[60:61], v[60:61], 0.5, v[172:173] op_sel_hi:[1,0,1]
	v_pk_fma_f32 v[54:55], v[54:55], 0.5, v[178:179] op_sel_hi:[1,0,1]
	v_pk_fma_f32 v[52:53], v[52:53], 0.5, v[176:177] op_sel_hi:[1,0,1]
	global_load_dwordx4 v[156:159], v[196:197], off
	global_load_dwordx4 v[168:171], v[196:197], off offset:512
	global_load_dwordx4 v[172:175], v[198:199], off
	global_load_dwordx4 v[176:179], v[198:199], off offset:512
	s_mov_b64 vcc, 0x20000
	v_lshl_add_u64 v[196:197], v[196:197], 0, vcc
	v_lshl_add_u64 v[198:199], v[198:199], 0, vcc
	v_mul_f32_e32 v232, v56, v56
	v_fmac_f32_e32 v232, v57, v57
	v_fmac_f32_e32 v232, v58, v58
	v_fmac_f32_e32 v232, v59, v59
	v_fmac_f32_e32 v232, v48, v48
	v_fmac_f32_e32 v232, v49, v49
	v_fmac_f32_e32 v232, v50, v50
	v_fmac_f32_e32 v232, v51, v51
	v_mul_f32_e32 v233, v60, v60
	v_fmac_f32_e32 v233, v61, v61
	v_fmac_f32_e32 v233, v62, v62
	v_fmac_f32_e32 v233, v63, v63
	v_fmac_f32_e32 v233, v52, v52
	v_fmac_f32_e32 v233, v53, v53
	v_fmac_f32_e32 v233, v54, v54
	v_fmac_f32_e32 v233, v55, v55
	s_nop 1
	v_mov_b32_dpp v236, v232 row_ror:8 row_mask:0xf bank_mask:0xf
	v_mov_b32_dpp v237, v233 row_ror:8 row_mask:0xf bank_mask:0xf
	v_add_f32_e32 v232, v232, v236
	v_add_f32_e32 v233, v233, v237
	v_cndmask_b32_e64 v232, v233, v232, s[24:25]
	s_nop 0
	ds_bpermute_b32 v236, v234, v232
	s_waitcnt lgkmcnt(0)
;     __device__ __forceinline__ void operator()(const f32x4 (&acc)[2][2][4][2], const Unit& u, int wr, int wc, int fr, int fq) const {
;     ...
;         for (int ai = 0; ai < 2; ++ai)
; #pragma unroll
;             for (int m = 0; m < 4; ++m) {
;                 const int row = row0 + ai * HALF + m * 16;
;                 const size_t off = (size_t)row * ldc + col0;
;                 float q = 0.f;
; #pragma unroll
;                 for (int bj = 0; bj < 2; ++bj)
; #pragma unroll
;                     for (int n = 0; n < 2; ++n) {
;                         const f32x4 rv = *(const f32x4*)(rbase + off + bj * HALF + n * 16);
;                         const f32x4 v = rv + acc[ai][bj][m][n] * scale;
;                         if (out) *(f32x4*)(out + off + bj * HALF + n * 16) = v;
;                         if (xn) { q += (v.x * v.x + v.y * v.y) + (v.z * v.z + v.w * v.w); const f32x4 o = v * wv[bj][n];
;                             u32x2 p; p.x = pk2(o.x, o.y); p.y = pk2(o.z, o.w); *(u32x2*)(xn + off + bj * HALF + n * 16) = p; }
;                     }
;                 if (xn) { q += __shfl_xor(q, 16); q += __shfl_xor(q, 32); if (fq == 0) (void)__hip_atomic_fetch_add(ss + row, q, __ATOMIC_RELAXED, __HIP_MEMORY_SCOPE_AGENT); }
	v_add_f32_e32 v232, v232, v236
	s_nop 0
	ds_bpermute_b32 v237, v235, v232
	s_waitcnt lgkmcnt(0)
	v_add_f32_e32 v232, v232, v237
	s_mov_b64 exec, s[0:1]
	global_atomic_add_f32 v[204:205], v232, off
	s_mov_b64 exec, -1
	s_mov_b64 vcc, 64
	v_lshl_add_u64 v[204:205], v[204:205], 0, vcc
	v_mov_b32_dpp v228, v40 row_ror:8 row_mask:0xf bank_mask:0xf
	v_mov_b32_dpp v229, v41 row_ror:8 row_mask:0xf bank_mask:0xf
	v_mov_b32_dpp v230, v42 row_ror:8 row_mask:0xf bank_mask:0xf
	v_mov_b32_dpp v231, v43 row_ror:8 row_mask:0xf bank_mask:0xf
	v_cndmask_b32_e64 v40, v228, v44, s[24:25]
	v_cndmask_b32_e64 v41, v229, v45, s[24:25]
	v_cndmask_b32_e64 v42, v230, v46, s[24:25]
	v_cndmask_b32_e64 v43, v231, v47, s[24:25]
	v_cndmask_b32_e64 v44, v44, v228, s[24:25]
	v_cndmask_b32_e64 v45, v45, v229, s[24:25]
	v_cndmask_b32_e64 v46, v46, v230, s[24:25]
	v_cndmask_b32_e64 v47, v47, v231, s[24:25]
	v_mov_b32_dpp v228, v32 row_ror:8 row_mask:0xf bank_mask:0xf
	v_mov_b32_dpp v229, v33 row_ror:8 row_mask:0xf bank_mask:0xf
	v_mov_b32_dpp v230, v34 row_ror:8 row_mask:0xf bank_mask:0xf
	v_mov_b32_dpp v231, v35 row_ror:8 row_mask:0xf bank_mask:0xf
	v_cndmask_b32_e64 v32, v228, v36, s[24:25]
	v_cndmask_b32_e64 v33, v229, v37, s[24:25]
	v_cndmask_b32_e64 v34, v230, v38, s[24:25]
	v_cndmask_b32_e64 v35, v231, v39, s[24:25]
	v_cndmask_b32_e64 v36, v36, v228, s[24:25]
	v_cndmask_b32_e64 v37, v37, v229, s[24:25]
	v_cndmask_b32_e64 v38, v38, v230, s[24:25]
	v_cndmask_b32_e64 v39, v39, v231, s[24:25]
	s_waitcnt vmcnt(6)
	v_pk_fma_f32 v[42:43], v[42:43], 0.5, v[182:183] op_sel_hi:[1,0,1]
	v_pk_fma_f32 v[40:41], v[40:41], 0.5, v[180:181] op_sel_hi:[1,0,1]
	v_pk_fma_f32 v[34:35], v[34:35], 0.5, v[186:187] op_sel_hi:[1,0,1]
	v_pk_fma_f32 v[32:33], v[32:33], 0.5, v[184:185] op_sel_hi:[1,0,1]
	v_pk_fma_f32 v[46:47], v[46:47], 0.5, v[190:191] op_sel_hi:[1,0,1]
	v_pk_fma_f32 v[44:45], v[44:45], 0.5, v[188:189] op_sel_hi:[1,0,1]
	v_pk_fma_f32 v[38:39], v[38:39], 0.5, v[194:195] op_sel_hi:[1,0,1]
	v_pk_fma_f32 v[36:37], v[36:37], 0.5, v[192:193] op_sel_hi:[1,0,1]
	global_load_dwordx4 v[180:183], v[196:197], off
	global_load_dwordx4 v[184:187], v[196:197], off offset:512
	global_load_dwordx4 v[188:191], v[198:199], off
	global_load_dwordx4 v[192:195], v[198:199], off offset:512
	v_mul_f32_e32 v232, v40, v40
	v_fmac_f32_e32 v232, v41, v41
	v_fmac_f32_e32 v232, v42, v42
	v_fmac_f32_e32 v232, v43, v43
	v_fmac_f32_e32 v232, v32, v32
	v_fmac_f32_e32 v232, v33, v33
	v_fmac_f32_e32 v232, v34, v34
	v_fmac_f32_e32 v232, v35, v35
	v_mul_f32_e32 v233, v44, v44
	v_fmac_f32_e32 v233, v45, v45
	v_fmac_f32_e32 v233, v46, v46
	v_fmac_f32_e32 v233, v47, v47
	v_fmac_f32_e32 v233, v36, v36
	v_fmac_f32_e32 v233, v37, v37
	v_fmac_f32_e32 v233, v38, v38
	v_fmac_f32_e32 v233, v39, v39
	s_nop 1
	v_mov_b32_dpp v236, v232 row_ror:8 row_mask:0xf bank_mask:0xf
	v_mov_b32_dpp v237, v233 row_ror:8 row_mask:0xf bank_mask:0xf
	v_add_f32_e32 v232, v232, v236
	v_add_f32_e32 v233, v233, v237
	v_cndmask_b32_e64 v232, v233, v232, s[24:25]
	s_nop 0
	ds_bpermute_b32 v236, v234, v232
	s_waitcnt lgkmcnt(0)
	v_add_f32_e32 v232, v232, v236
	s_nop 0
	ds_bpermute_b32 v237, v235, v232
	s_waitcnt lgkmcnt(0)
	v_add_f32_e32 v232, v232, v237
	s_mov_b64 exec, s[0:1]
	global_atomic_add_f32 v[204:205], v232, off
	s_mov_b64 exec, -1
	s_mov_b64 vcc, 64
	v_lshl_add_u64 v[204:205], v[204:205], 0, vcc
	v_mov_b32_dpp v228, v24 row_ror:8 row_mask:0xf bank_mask:0xf
	v_mov_b32_dpp v229, v25 row_ror:8 row_mask:0xf bank_mask:0xf
	v_mov_b32_dpp v230, v26 row_ror:8 row_mask:0xf bank_mask:0xf
	v_mov_b32_dpp v231, v27 row_ror:8 row_mask:0xf bank_mask:0xf
	v_cndmask_b32_e64 v24, v228, v28, s[24:25]
	v_cndmask_b32_e64 v25, v229, v29, s[24:25]
	v_cndmask_b32_e64 v26, v230, v30, s[24:25]
	v_cndmask_b32_e64 v27, v231, v31, s[24:25]
	v_cndmask_b32_e64 v28, v28, v228, s[24:25]
	v_cndmask_b32_e64 v29, v29, v229, s[24:25]
	v_cndmask_b32_e64 v30, v30, v230, s[24:25]
	v_cndmask_b32_e64 v31, v31, v231, s[24:25]
	v_mov_b32_dpp v228, v16 row_ror:8 row_mask:0xf bank_mask:0xf
	v_mov_b32_dpp v229, v17 row_ror:8 row_mask:0xf bank_mask:0xf
	v_mov_b32_dpp v230, v18 row_ror:8 row_mask:0xf bank_mask:0xf
	v_mov_b32_dpp v231, v19 row_ror:8 row_mask:0xf bank_mask:0xf
	v_cndmask_b32_e64 v16, v228, v20, s[24:25]
	v_cndmask_b32_e64 v17, v229, v21, s[24:25]
	v_cndmask_b32_e64 v18, v230, v22, s[24:25]
	v_cndmask_b32_e64 v19, v231, v23, s[24:25]
	v_cndmask_b32_e64 v20, v20, v228, s[24:25]
	v_cndmask_b32_e64 v21, v21, v229, s[24:25]
	v_cndmask_b32_e64 v22, v22, v230, s[24:25]
	v_cndmask_b32_e64 v23, v23, v231, s[24:25]
	s_waitcnt vmcnt(6)
	v_pk_fma_f32 v[26:27], v[26:27], 0.5, v[158:159] op_sel_hi:[1,0,1]
	v_pk_fma_f32 v[24:25], v[24:25], 0.5, v[156:157] op_sel_hi:[1,0,1]
	v_pk_fma_f32 v[18:19], v[18:19], 0.5, v[170:171] op_sel_hi:[1,0,1]
	v_pk_fma_f32 v[16:17], v[16:17], 0.5, v[168:169] op_sel_hi:[1,0,1]
	v_pk_fma_f32 v[30:31], v[30:31], 0.5, v[174:175] op_sel_hi:[1,0,1]
	v_pk_fma_f32 v[28:29], v[28:29], 0.5, v[172:173] op_sel_hi:[1,0,1]
	v_pk_fma_f32 v[22:23], v[22:23], 0.5, v[178:179] op_sel_hi:[1,0,1]
	v_pk_fma_f32 v[20:21], v[20:21], 0.5, v[176:177] op_sel_hi:[1,0,1]
	v_mul_f32_e32 v232, v24, v24
	v_fmac_f32_e32 v232, v25, v25
	v_fmac_f32_e32 v232, v26, v26
	v_fmac_f32_e32 v232, v27, v27
	v_fmac_f32_e32 v232, v16, v16
	v_fmac_f32_e32 v232, v17, v17
	v_fmac_f32_e32 v232, v18, v18
	v_fmac_f32_e32 v232, v19, v19
	v_mul_f32_e32 v233, v28, v28
	v_fmac_f32_e32 v233, v29, v29
	v_fmac_f32_e32 v233, v30, v30
	v_fmac_f32_e32 v233, v31, v31
	v_fmac_f32_e32 v233, v20, v20
	v_fmac_f32_e32 v233, v21, v21
	v_fmac_f32_e32 v233, v22, v22
	v_fmac_f32_e32 v233, v23, v23
	s_nop 1
	v_mov_b32_dpp v236, v232 row_ror:8 row_mask:0xf bank_mask:0xf
	v_mov_b32_dpp v237, v233 row_ror:8 row_mask:0xf bank_mask:0xf
	v_add_f32_e32 v232, v232, v236
	v_add_f32_e32 v233, v233, v237
	v_cndmask_b32_e64 v232, v233, v232, s[24:25]
	s_nop 0
	ds_bpermute_b32 v236, v234, v232
	s_waitcnt lgkmcnt(0)
;     __device__ __forceinline__ void operator()(const f32x4 (&acc)[2][2][4][2], const Unit& u, int wr, int wc, int fr, int fq) const {
;     ...
;         for (int ai = 0; ai < 2; ++ai)
; #pragma unroll
;             for (int m = 0; m < 4; ++m) {
;                 const int row = row0 + ai * HALF + m * 16;
;                 const size_t off = (size_t)row * ldc + col0;
;                 float q = 0.f;
; #pragma unroll
;                 for (int bj = 0; bj < 2; ++bj)
; #pragma unroll
;                     for (int n = 0; n < 2; ++n) {
;                         const f32x4 rv = *(const f32x4*)(rbase + off + bj * HALF + n * 16);
;                         const f32x4 v = rv + acc[ai][bj][m][n] * scale;
;                         if (out) *(f32x4*)(out + off + bj * HALF + n * 16) = v;
;                         if (xn) { q += (v.x * v.x + v.y * v.y) + (v.z * v.z + v.w * v.w); const f32x4 o = v * wv[bj][n];
;                             u32x2 p; p.x = pk2(o.x, o.y); p.y = pk2(o.z, o.w); *(u32x2*)(xn + off + bj * HALF + n * 16) = p; }
;                     }
;                 if (xn) { q += __shfl_xor(q, 16); q += __shfl_xor(q, 32); if (fq == 0) (void)__hip_atomic_fetch_add(ss + row, q, __ATOMIC_RELAXED, __HIP_MEMORY_SCOPE_AGENT); }
;             }
	v_add_f32_e32 v232, v232, v236
	s_nop 0
	ds_bpermute_b32 v237, v235, v232
	s_waitcnt lgkmcnt(0)
	v_add_f32_e32 v232, v232, v237
	s_mov_b64 exec, s[0:1]
	global_atomic_add_f32 v[204:205], v232, off
	s_mov_b64 exec, -1
	s_mov_b64 vcc, 64
	v_lshl_add_u64 v[204:205], v[204:205], 0, vcc
	v_mov_b32_dpp v228, v8 row_ror:8 row_mask:0xf bank_mask:0xf
	v_mov_b32_dpp v229, v9 row_ror:8 row_mask:0xf bank_mask:0xf
	v_mov_b32_dpp v230, v10 row_ror:8 row_mask:0xf bank_mask:0xf
	v_mov_b32_dpp v231, v11 row_ror:8 row_mask:0xf bank_mask:0xf
	v_cndmask_b32_e64 v8, v228, v12, s[24:25]
	v_cndmask_b32_e64 v9, v229, v13, s[24:25]
	v_cndmask_b32_e64 v10, v230, v14, s[24:25]
	v_cndmask_b32_e64 v11, v231, v15, s[24:25]
	v_cndmask_b32_e64 v12, v12, v228, s[24:25]
	v_cndmask_b32_e64 v13, v13, v229, s[24:25]
	v_cndmask_b32_e64 v14, v14, v230, s[24:25]
	v_cndmask_b32_e64 v15, v15, v231, s[24:25]
	v_mov_b32_dpp v228, v0 row_ror:8 row_mask:0xf bank_mask:0xf
	v_mov_b32_dpp v229, v1 row_ror:8 row_mask:0xf bank_mask:0xf
	v_mov_b32_dpp v230, v2 row_ror:8 row_mask:0xf bank_mask:0xf
	v_mov_b32_dpp v231, v3 row_ror:8 row_mask:0xf bank_mask:0xf
	v_cndmask_b32_e64 v0, v228, v4, s[24:25]
	v_cndmask_b32_e64 v1, v229, v5, s[24:25]
	v_cndmask_b32_e64 v2, v230, v6, s[24:25]
	v_cndmask_b32_e64 v3, v231, v7, s[24:25]
	v_cndmask_b32_e64 v4, v4, v228, s[24:25]
	v_cndmask_b32_e64 v5, v5, v229, s[24:25]
	v_cndmask_b32_e64 v6, v6, v230, s[24:25]
	v_cndmask_b32_e64 v7, v7, v231, s[24:25]
	s_waitcnt vmcnt(2)
	v_pk_fma_f32 v[10:11], v[10:11], 0.5, v[182:183] op_sel_hi:[1,0,1]
	v_pk_fma_f32 v[8:9], v[8:9], 0.5, v[180:181] op_sel_hi:[1,0,1]
	v_pk_fma_f32 v[2:3], v[2:3], 0.5, v[186:187] op_sel_hi:[1,0,1]
	v_pk_fma_f32 v[0:1], v[0:1], 0.5, v[184:185] op_sel_hi:[1,0,1]
	v_pk_fma_f32 v[14:15], v[14:15], 0.5, v[190:191] op_sel_hi:[1,0,1]
	v_pk_fma_f32 v[12:13], v[12:13], 0.5, v[188:189] op_sel_hi:[1,0,1]
	v_pk_fma_f32 v[6:7], v[6:7], 0.5, v[194:195] op_sel_hi:[1,0,1]
	v_pk_fma_f32 v[4:5], v[4:5], 0.5, v[192:193] op_sel_hi:[1,0,1]
	v_mul_f32_e32 v232, v8, v8
	v_fmac_f32_e32 v232, v9, v9
	v_fmac_f32_e32 v232, v10, v10
	v_fmac_f32_e32 v232, v11, v11
	v_fmac_f32_e32 v232, v0, v0
	v_fmac_f32_e32 v232, v1, v1
	v_fmac_f32_e32 v232, v2, v2
	v_fmac_f32_e32 v232, v3, v3
	v_mul_f32_e32 v233, v12, v12
	v_fmac_f32_e32 v233, v13, v13
	v_fmac_f32_e32 v233, v14, v14
	v_fmac_f32_e32 v233, v15, v15
	v_fmac_f32_e32 v233, v4, v4
	v_fmac_f32_e32 v233, v5, v5
	v_fmac_f32_e32 v233, v6, v6
	v_fmac_f32_e32 v233, v7, v7
	s_nop 1
	v_mov_b32_dpp v236, v232 row_ror:8 row_mask:0xf bank_mask:0xf
	v_mov_b32_dpp v237, v233 row_ror:8 row_mask:0xf bank_mask:0xf
	v_add_f32_e32 v232, v232, v236
	v_add_f32_e32 v233, v233, v237
	v_cndmask_b32_e64 v232, v233, v232, s[24:25]
	s_nop 0
	ds_bpermute_b32 v236, v234, v232
	s_waitcnt lgkmcnt(0)
	v_add_f32_e32 v232, v232, v236
	s_nop 0
	ds_bpermute_b32 v237, v235, v232
	s_waitcnt lgkmcnt(0)
	v_add_f32_e32 v232, v232, v237
	s_mov_b64 exec, s[0:1]
	global_atomic_add_f32 v[204:205], v232, off
	s_mov_b64 exec, -1
	v_pk_mul_f32 v[216:217], v[72:73], v[136:137]
	v_pk_mul_f32 v[218:219], v[74:75], v[138:139]
	v_add_u32_e32 v216, 0x8000, v216
	v_add_u32_e32 v217, 0x8000, v217
	v_add_u32_e32 v218, 0x8000, v218
	v_add_u32_e32 v219, 0x8000, v219
	v_perm_b32 v224, v217, v216, s50
	v_perm_b32 v225, v219, v218, s50
	global_store_dwordx2 v[200:201], v[224:225], off
	v_pk_mul_f32 v[220:221], v[84:85], v[128:129]
	v_pk_mul_f32 v[222:223], v[86:87], v[130:131]
	v_add_u32_e32 v220, 0x8000, v220
	v_add_u32_e32 v221, 0x8000, v221
	v_add_u32_e32 v222, 0x8000, v222
	v_add_u32_e32 v223, 0x8000, v223
	v_perm_b32 v226, v221, v220, s50
	v_perm_b32 v227, v223, v222, s50
	global_store_dwordx2 v[200:201], v[226:227], off offset:256
	v_pk_mul_f32 v[216:217], v[88:89], v[140:141]
	v_pk_mul_f32 v[218:219], v[90:91], v[142:143]
	v_add_u32_e32 v216, 0x8000, v216
	v_add_u32_e32 v217, 0x8000, v217
	v_add_u32_e32 v218, 0x8000, v218
	v_add_u32_e32 v219, 0x8000, v219
	v_perm_b32 v224, v217, v216, s50
	v_perm_b32 v225, v219, v218, s50
	global_store_dwordx2 v[202:203], v[224:225], off
	v_pk_mul_f32 v[220:221], v[96:97], v[132:133]
	v_pk_mul_f32 v[222:223], v[98:99], v[134:135]
	v_add_u32_e32 v220, 0x8000, v220
	v_add_u32_e32 v221, 0x8000, v221
	v_add_u32_e32 v222, 0x8000, v222
	v_add_u32_e32 v223, 0x8000, v223
	v_perm_b32 v226, v221, v220, s50
	v_perm_b32 v227, v223, v222, s50
	global_store_dwordx2 v[202:203], v[226:227], off offset:256
	s_mov_b64 vcc, 0x20000
	s_mov_b64 vcc, 0x10000
	v_lshl_add_u64 v[200:201], v[200:201], 0, vcc
	v_lshl_add_u64 v[202:203], v[202:203], 0, vcc
	v_pk_mul_f32 v[216:217], v[72:73], v[120:121]
	v_pk_mul_f32 v[218:219], v[74:75], v[122:123]
	v_add_u32_e32 v216, 0x8000, v216
	v_add_u32_e32 v217, 0x8000, v217
	v_add_u32_e32 v218, 0x8000, v218
	v_add_u32_e32 v219, 0x8000, v219
	v_perm_b32 v224, v217, v216, s50
	v_perm_b32 v225, v219, v218, s50
	global_store_dwordx2 v[200:201], v[224:225], off
	v_pk_mul_f32 v[220:221], v[84:85], v[112:113]
	v_pk_mul_f32 v[222:223], v[86:87], v[114:115]
	v_add_u32_e32 v220, 0x8000, v220
	v_add_u32_e32 v221, 0x8000, v221
	v_add_u32_e32 v222, 0x8000, v222
	v_add_u32_e32 v223, 0x8000, v223
	v_perm_b32 v226, v221, v220, s50
	v_perm_b32 v227, v223, v222, s50
	global_store_dwordx2 v[200:201], v[226:227], off offset:256
	v_pk_mul_f32 v[216:217], v[88:89], v[124:125]
	v_pk_mul_f32 v[218:219], v[90:91], v[126:127]
	v_add_u32_e32 v216, 0x8000, v216
	v_add_u32_e32 v217, 0x8000, v217
	v_add_u32_e32 v218, 0x8000, v218
	v_add_u32_e32 v219, 0x8000, v219
	v_perm_b32 v224, v217, v216, s50
	v_perm_b32 v225, v219, v218, s50
	global_store_dwordx2 v[202:203], v[224:225], off
;     __device__ __forceinline__ void operator()(const f32x4 (&acc)[2][2][4][2], const Unit& u, int wr, int wc, int fr, int fq) const {
;     ...
;                         if (xn) { q += (v.x * v.x + v.y * v.y) + (v.z * v.z + v.w * v.w); const f32x4 o = v * wv[bj][n];
;                             u32x2 p; p.x = pk2(o.x, o.y); p.y = pk2(o.z, o.w); *(u32x2*)(xn + off + bj * HALF + n * 16) = p; }
	v_pk_mul_f32 v[220:221], v[96:97], v[116:117]
	v_pk_mul_f32 v[222:223], v[98:99], v[118:119]
	v_add_u32_e32 v220, 0x8000, v220
	v_add_u32_e32 v221, 0x8000, v221
	v_add_u32_e32 v222, 0x8000, v222
	v_add_u32_e32 v223, 0x8000, v223
	v_perm_b32 v226, v221, v220, s50
	v_perm_b32 v227, v223, v222, s50
	global_store_dwordx2 v[202:203], v[226:227], off offset:256
	s_mov_b64 vcc, 0x20000
	s_mov_b64 vcc, 0x10000
	v_lshl_add_u64 v[200:201], v[200:201], 0, vcc
	v_lshl_add_u64 v[202:203], v[202:203], 0, vcc
	v_pk_mul_f32 v[216:217], v[72:73], v[104:105]
	v_pk_mul_f32 v[218:219], v[74:75], v[106:107]
	v_add_u32_e32 v216, 0x8000, v216
	v_add_u32_e32 v217, 0x8000, v217
	v_add_u32_e32 v218, 0x8000, v218
	v_add_u32_e32 v219, 0x8000, v219
	v_perm_b32 v224, v217, v216, s50
	v_perm_b32 v225, v219, v218, s50
	global_store_dwordx2 v[200:201], v[224:225], off
	v_pk_mul_f32 v[220:221], v[84:85], v[92:93]
	v_pk_mul_f32 v[222:223], v[86:87], v[94:95]
	v_add_u32_e32 v220, 0x8000, v220
	v_add_u32_e32 v221, 0x8000, v221
	v_add_u32_e32 v222, 0x8000, v222
	v_add_u32_e32 v223, 0x8000, v223
	v_perm_b32 v226, v221, v220, s50
	v_perm_b32 v227, v223, v222, s50
	global_store_dwordx2 v[200:201], v[226:227], off offset:256
	v_pk_mul_f32 v[216:217], v[88:89], v[108:109]
	v_pk_mul_f32 v[218:219], v[90:91], v[110:111]
	v_add_u32_e32 v216, 0x8000, v216
	v_add_u32_e32 v217, 0x8000, v217
	v_add_u32_e32 v218, 0x8000, v218
	v_add_u32_e32 v219, 0x8000, v219
	v_perm_b32 v224, v217, v216, s50
	v_perm_b32 v225, v219, v218, s50
	global_store_dwordx2 v[202:203], v[224:225], off
	v_pk_mul_f32 v[220:221], v[96:97], v[100:101]
	v_pk_mul_f32 v[222:223], v[98:99], v[102:103]
	v_add_u32_e32 v220, 0x8000, v220
	v_add_u32_e32 v221, 0x8000, v221
	v_add_u32_e32 v222, 0x8000, v222
	v_add_u32_e32 v223, 0x8000, v223
	v_perm_b32 v226, v221, v220, s50
	v_perm_b32 v227, v223, v222, s50
	global_store_dwordx2 v[202:203], v[226:227], off offset:256
	s_mov_b64 vcc, 0x20000
	s_mov_b64 vcc, 0x10000
	v_lshl_add_u64 v[200:201], v[200:201], 0, vcc
	v_lshl_add_u64 v[202:203], v[202:203], 0, vcc
	v_pk_mul_f32 v[216:217], v[72:73], v[76:77]
	v_pk_mul_f32 v[218:219], v[74:75], v[78:79]
	v_add_u32_e32 v216, 0x8000, v216
	v_add_u32_e32 v217, 0x8000, v217
	v_add_u32_e32 v218, 0x8000, v218
	v_add_u32_e32 v219, 0x8000, v219
	v_perm_b32 v224, v217, v216, s50
	v_perm_b32 v225, v219, v218, s50
	global_store_dwordx2 v[200:201], v[224:225], off
	v_pk_mul_f32 v[220:221], v[84:85], v[64:65]
	v_pk_mul_f32 v[222:223], v[86:87], v[66:67]
	v_add_u32_e32 v220, 0x8000, v220
	v_add_u32_e32 v221, 0x8000, v221
	v_add_u32_e32 v222, 0x8000, v222
	v_add_u32_e32 v223, 0x8000, v223
	v_perm_b32 v226, v221, v220, s50
	v_perm_b32 v227, v223, v222, s50
	global_store_dwordx2 v[200:201], v[226:227], off offset:256
	v_pk_mul_f32 v[216:217], v[88:89], v[80:81]
	v_pk_mul_f32 v[218:219], v[90:91], v[82:83]
	v_add_u32_e32 v216, 0x8000, v216
	v_add_u32_e32 v217, 0x8000, v217
	v_add_u32_e32 v218, 0x8000, v218
	v_add_u32_e32 v219, 0x8000, v219
	v_perm_b32 v224, v217, v216, s50
	v_perm_b32 v225, v219, v218, s50
	global_store_dwordx2 v[202:203], v[224:225], off
	v_pk_mul_f32 v[220:221], v[96:97], v[68:69]
	v_pk_mul_f32 v[222:223], v[98:99], v[70:71]
	v_add_u32_e32 v220, 0x8000, v220
	v_add_u32_e32 v221, 0x8000, v221
	v_add_u32_e32 v222, 0x8000, v222
	v_add_u32_e32 v223, 0x8000, v223
	v_perm_b32 v226, v221, v220, s50
	v_perm_b32 v227, v223, v222, s50
	global_store_dwordx2 v[202:203], v[226:227], off offset:256
	s_mov_b64 vcc, 0xa0000
	s_mov_b64 vcc, 0x50000
	v_lshl_add_u64 v[200:201], v[200:201], 0, vcc
	v_lshl_add_u64 v[202:203], v[202:203], 0, vcc
	v_pk_mul_f32 v[216:217], v[72:73], v[56:57]
	v_pk_mul_f32 v[218:219], v[74:75], v[58:59]
	v_add_u32_e32 v216, 0x8000, v216
	v_add_u32_e32 v217, 0x8000, v217
	v_add_u32_e32 v218, 0x8000, v218
	v_add_u32_e32 v219, 0x8000, v219
	v_perm_b32 v224, v217, v216, s50
	v_perm_b32 v225, v219, v218, s50
	global_store_dwordx2 v[200:201], v[224:225], off
	v_pk_mul_f32 v[220:221], v[84:85], v[48:49]
	v_pk_mul_f32 v[222:223], v[86:87], v[50:51]
	v_add_u32_e32 v220, 0x8000, v220
	v_add_u32_e32 v221, 0x8000, v221
	v_add_u32_e32 v222, 0x8000, v222
	v_add_u32_e32 v223, 0x8000, v223
	v_perm_b32 v226, v221, v220, s50
	v_perm_b32 v227, v223, v222, s50
	global_store_dwordx2 v[200:201], v[226:227], off offset:256
	v_pk_mul_f32 v[216:217], v[88:89], v[60:61]
	v_pk_mul_f32 v[218:219], v[90:91], v[62:63]
	v_add_u32_e32 v216, 0x8000, v216
	v_add_u32_e32 v217, 0x8000, v217
	v_add_u32_e32 v218, 0x8000, v218
	v_add_u32_e32 v219, 0x8000, v219
	v_perm_b32 v224, v217, v216, s50
	v_perm_b32 v225, v219, v218, s50
	global_store_dwordx2 v[202:203], v[224:225], off
	v_pk_mul_f32 v[220:221], v[96:97], v[52:53]
	v_pk_mul_f32 v[222:223], v[98:99], v[54:55]
	v_add_u32_e32 v220, 0x8000, v220
	v_add_u32_e32 v221, 0x8000, v221
	v_add_u32_e32 v222, 0x8000, v222
	v_add_u32_e32 v223, 0x8000, v223
	v_perm_b32 v226, v221, v220, s50
; #define PG8_BAR __builtin_amdgcn_s_barrier()
;     __device__ __forceinline__ void operator()(const f32x4 (&acc)[2][2][4][2], const Unit& u, int wr, int wc, int fr, int fq) const {
;     ...
;                         if (xn) { q += (v.x * v.x + v.y * v.y) + (v.z * v.z + v.w * v.w); const f32x4 o = v * wv[bj][n];
;                             u32x2 p; p.x = pk2(o.x, o.y); p.y = pk2(o.z, o.w); *(u32x2*)(xn + off + bj * HALF + n * 16) = p; }
; template <class Epi, bool ALIGN_EPI>
; __device__ __forceinline__ void gemm_phase(LAS unsigned char* lds, const Gemm g, const StaticOrder& S, const Epi& E) {
;     ...
;         if (!has_next) break;
; #pragma unroll
;         for (int a = 0; a < 2; ++a)
; #pragma unroll
;             for (int b = 0; b < 2; ++b)
; #pragma unroll
;                 for (int m = 0; m < 4; ++m)
; #pragma unroll
;                     for (int n = 0; n < 2; ++n) acc[a][b][m][n] = (f32x4){0.f, 0.f, 0.f, 0.f};
;         cur = nxt; cA = nA; cB = nB; ++ui;
;         if constexpr (ALIGN_EPI) { if (wr == 1) PG8_BAR; }
	v_perm_b32 v227, v223, v222, s50
	global_store_dwordx2 v[202:203], v[226:227], off offset:256
	s_mov_b64 vcc, 0x20000
	s_mov_b64 vcc, 0x10000
	v_lshl_add_u64 v[200:201], v[200:201], 0, vcc
	v_lshl_add_u64 v[202:203], v[202:203], 0, vcc
	v_pk_mul_f32 v[216:217], v[72:73], v[40:41]
	v_pk_mul_f32 v[218:219], v[74:75], v[42:43]
	v_add_u32_e32 v216, 0x8000, v216
	v_add_u32_e32 v217, 0x8000, v217
	v_add_u32_e32 v218, 0x8000, v218
	v_add_u32_e32 v219, 0x8000, v219
	v_perm_b32 v224, v217, v216, s50
	v_perm_b32 v225, v219, v218, s50
	global_store_dwordx2 v[200:201], v[224:225], off
	v_pk_mul_f32 v[220:221], v[84:85], v[32:33]
	v_pk_mul_f32 v[222:223], v[86:87], v[34:35]
	v_add_u32_e32 v220, 0x8000, v220
	v_add_u32_e32 v221, 0x8000, v221
	v_add_u32_e32 v222, 0x8000, v222
	v_add_u32_e32 v223, 0x8000, v223
	v_perm_b32 v226, v221, v220, s50
	v_perm_b32 v227, v223, v222, s50
	global_store_dwordx2 v[200:201], v[226:227], off offset:256
	v_pk_mul_f32 v[216:217], v[88:89], v[44:45]
	v_pk_mul_f32 v[218:219], v[90:91], v[46:47]
	v_add_u32_e32 v216, 0x8000, v216
	v_add_u32_e32 v217, 0x8000, v217
	v_add_u32_e32 v218, 0x8000, v218
	v_add_u32_e32 v219, 0x8000, v219
	v_perm_b32 v224, v217, v216, s50
	v_perm_b32 v225, v219, v218, s50
	global_store_dwordx2 v[202:203], v[224:225], off
	v_pk_mul_f32 v[220:221], v[96:97], v[36:37]
	v_pk_mul_f32 v[222:223], v[98:99], v[38:39]
	v_add_u32_e32 v220, 0x8000, v220
	v_add_u32_e32 v221, 0x8000, v221
	v_add_u32_e32 v222, 0x8000, v222
	v_add_u32_e32 v223, 0x8000, v223
	v_perm_b32 v226, v221, v220, s50
	v_perm_b32 v227, v223, v222, s50
	global_store_dwordx2 v[202:203], v[226:227], off offset:256
	s_mov_b64 vcc, 0x20000
	s_mov_b64 vcc, 0x10000
	v_lshl_add_u64 v[200:201], v[200:201], 0, vcc
	v_lshl_add_u64 v[202:203], v[202:203], 0, vcc
	v_pk_mul_f32 v[216:217], v[72:73], v[24:25]
	v_pk_mul_f32 v[218:219], v[74:75], v[26:27]
	v_add_u32_e32 v216, 0x8000, v216
	v_add_u32_e32 v217, 0x8000, v217
	v_add_u32_e32 v218, 0x8000, v218
	v_add_u32_e32 v219, 0x8000, v219
	v_perm_b32 v224, v217, v216, s50
	v_perm_b32 v225, v219, v218, s50
	global_store_dwordx2 v[200:201], v[224:225], off
	v_pk_mul_f32 v[220:221], v[84:85], v[16:17]
	v_pk_mul_f32 v[222:223], v[86:87], v[18:19]
	v_add_u32_e32 v220, 0x8000, v220
	v_add_u32_e32 v221, 0x8000, v221
	v_add_u32_e32 v222, 0x8000, v222
	v_add_u32_e32 v223, 0x8000, v223
	v_perm_b32 v226, v221, v220, s50
	v_perm_b32 v227, v223, v222, s50
	global_store_dwordx2 v[200:201], v[226:227], off offset:256
	v_pk_mul_f32 v[216:217], v[88:89], v[28:29]
	v_pk_mul_f32 v[218:219], v[90:91], v[30:31]
	v_add_u32_e32 v216, 0x8000, v216
	v_add_u32_e32 v217, 0x8000, v217
	v_add_u32_e32 v218, 0x8000, v218
	v_add_u32_e32 v219, 0x8000, v219
	v_perm_b32 v224, v217, v216, s50
	v_perm_b32 v225, v219, v218, s50
	global_store_dwordx2 v[202:203], v[224:225], off
	v_pk_mul_f32 v[220:221], v[96:97], v[20:21]
	v_pk_mul_f32 v[222:223], v[98:99], v[22:23]
	v_add_u32_e32 v220, 0x8000, v220
	v_add_u32_e32 v221, 0x8000, v221
	v_add_u32_e32 v222, 0x8000, v222
	v_add_u32_e32 v223, 0x8000, v223
	v_perm_b32 v226, v221, v220, s50
	v_perm_b32 v227, v223, v222, s50
	global_store_dwordx2 v[202:203], v[226:227], off offset:256
	s_mov_b64 vcc, 0x20000
	s_mov_b64 vcc, 0x10000
	v_lshl_add_u64 v[200:201], v[200:201], 0, vcc
	v_lshl_add_u64 v[202:203], v[202:203], 0, vcc
	v_pk_mul_f32 v[216:217], v[72:73], v[8:9]
	v_pk_mul_f32 v[218:219], v[74:75], v[10:11]
	v_add_u32_e32 v216, 0x8000, v216
	v_add_u32_e32 v217, 0x8000, v217
	v_add_u32_e32 v218, 0x8000, v218
	v_add_u32_e32 v219, 0x8000, v219
	v_perm_b32 v224, v217, v216, s50
	v_perm_b32 v225, v219, v218, s50
	global_store_dwordx2 v[200:201], v[224:225], off
	v_pk_mul_f32 v[220:221], v[84:85], v[0:1]
	v_pk_mul_f32 v[222:223], v[86:87], v[2:3]
	v_add_u32_e32 v220, 0x8000, v220
	v_add_u32_e32 v221, 0x8000, v221
	v_add_u32_e32 v222, 0x8000, v222
	v_add_u32_e32 v223, 0x8000, v223
	v_perm_b32 v226, v221, v220, s50
	v_perm_b32 v227, v223, v222, s50
	global_store_dwordx2 v[200:201], v[226:227], off offset:256
	v_pk_mul_f32 v[216:217], v[88:89], v[12:13]
	v_pk_mul_f32 v[218:219], v[90:91], v[14:15]
	v_add_u32_e32 v216, 0x8000, v216
	v_add_u32_e32 v217, 0x8000, v217
	v_add_u32_e32 v218, 0x8000, v218
	v_add_u32_e32 v219, 0x8000, v219
	v_perm_b32 v224, v217, v216, s50
	v_perm_b32 v225, v219, v218, s50
	global_store_dwordx2 v[202:203], v[224:225], off
	v_pk_mul_f32 v[220:221], v[96:97], v[4:5]
	v_pk_mul_f32 v[222:223], v[98:99], v[6:7]
	v_add_u32_e32 v220, 0x8000, v220
	v_add_u32_e32 v221, 0x8000, v221
	v_add_u32_e32 v222, 0x8000, v222
	v_add_u32_e32 v223, 0x8000, v223
	v_perm_b32 v226, v221, v220, s50
	v_perm_b32 v227, v223, v222, s50
	global_store_dwordx2 v[202:203], v[226:227], off offset:256
	s_and_b64 vcc, exec, s[6:7]
	s_mov_b64 s[6:7], -1
	s_cbranch_vccnz .LBB0_1371
	s_andn2_b64 vcc, exec, s[12:13]
	s_cbranch_vccnz .LBB0_1370
	s_barrier
	s_branch .LBB0_1370
